# GEMM epilogues (out-proj x4, retention gate): pairs of 8-byte stores merged into 16-byte stores via v_permlane16_swap; attention: -max folded into QK accumulator init, tile-start vmcnt(0) removed
# speedup vs baseline: 1.1082x; 1.0286x over previous
.LBB0_699:
	s_lshl_b32 s15, s2, 7
	s_lshl_b32 s2, s2, 8
	s_add_u32 s18, s10, s2
	s_addc_u32 s19, s11, 0
	s_and_b32 s17, s30, s28
	s_lshl_b32 s30, s14, 11
	s_lshr_b32 s16, s29, 7
	s_addk_i32 s30, 0x2000
	s_lshl_b32 s14, s14, 8
	s_and_b64 s[12:13], exec, s[12:13]
	s_cselect_b32 s12, s14, s30
	v_readfirstlane_b32 s14, v183
	s_lshl_b32 s13, s17, 7
	s_lshl_b32 s17, s14, 4
	v_or_b32_e32 v17, s17, v189
	v_bitop3_b32 v20, v17, v178, 4 bitop3:0x36
	v_bitop3_b32 v25, v17, v178, 8 bitop3:0x36
	s_add_i32 s12, s12, s13
	v_lshlrev_b32_e32 v20, 3, v20
	v_lshlrev_b32_e32 v25, 3, v25
	v_add_u32_e32 v0, s12, v191
	v_mul_lo_u32 v21, v17, s29
	v_or_b32_e32 v19, 4, v17
	v_and_b32_e32 v20, 0x78, v20
	s_lshl_b32 s12, s29, 2
	v_or_b32_e32 v23, 8, v17
	v_and_b32_e32 v26, 0x78, v25
	v_ashrrev_i32_e32 v1, 31, v0
	v_lshl_or_b32 v16, v17, 10, v194
	v_lshl_or_b32 v22, v19, 10, v20
	v_add_u32_e32 v19, s12, v21
	v_lshl_or_b32 v28, v23, 10, v26
	v_or_b32_e32 v23, 12, v17
	v_bitop3_b32 v17, v17, v178, 12 bitop3:0x36
	v_lshlrev_b64 v[152:153], 11, v[0:1]
	v_or_b32_e32 v24, v20, v19
	v_add_u32_e32 v19, s12, v19
	v_lshlrev_b32_e32 v17, 3, v17
	v_lshl_add_u64 v[0:1], s[68:69], 0, v[152:153]
	v_and_b32_e32 v32, 0x78, v17
	v_add_u32_e32 v17, s12, v19
	s_lshl_b32 s12, s14, 12
	v_lshl_add_u64 v[0:1], v[0:1], 0, s[2:3]
	v_or_b32_e32 v36, v32, v17
	s_add_i32 s12, s12, 0
	v_ashrrev_i32_e32 v17, 31, v16
	v_lshl_add_u64 v[12:13], v[0:1], 0, v[144:145]
	v_lshl_or_b32 v34, v23, 10, v32
	v_lshl_add_u64 v[16:17], v[16:17], 1, s[18:19]
	s_mov_b32 m0, s12
	v_ashrrev_i32_e32 v23, 31, v22
	global_load_dwordx4 v[0:3], v[12:13], off
	global_load_dwordx4 v[4:7], v[12:13], off offset:64
	global_load_dwordx4 v[8:11], v[12:13], off offset:128
	s_nop 0
	global_load_dwordx4 v[12:15], v[12:13], off offset:192
	v_ashrrev_i32_e32 v29, 31, v28
	global_load_lds_dwordx4 v[16:17], off
	v_lshl_add_u64 v[16:17], v[22:23], 1, s[18:19]
	s_add_i32 m0, s12, 0x400
	v_or_b32_e32 v18, v21, v194
	global_load_lds_dwordx4 v[16:17], off
	v_lshl_add_u64 v[16:17], v[28:29], 1, s[18:19]
	s_add_i32 m0, s12, 0x800
	v_ashrrev_i32_e32 v35, 31, v34
	v_or_b32_e32 v30, v26, v19
	global_load_lds_dwordx4 v[16:17], off
	v_lshl_add_u64 v[16:17], v[34:35], 1, s[18:19]
	s_add_i32 m0, s12, 0xc00
	v_ashrrev_i32_e32 v19, 31, v18
	global_load_lds_dwordx4 v[16:17], off
	s_add_i32 m0, s12, 0x8000
	v_lshl_add_u64 v[16:17], v[18:19], 1, s[0:1]
	v_ashrrev_i32_e32 v25, 31, v24
	global_load_lds_dwordx4 v[16:17], off
	v_lshl_add_u64 v[16:17], v[24:25], 1, s[0:1]
	s_add_i32 m0, s12, 0x8400
	v_ashrrev_i32_e32 v31, 31, v30
	global_load_lds_dwordx4 v[16:17], off
	v_lshl_add_u64 v[16:17], v[30:31], 1, s[0:1]
	s_add_i32 m0, s12, 0x8800
	v_ashrrev_i32_e32 v37, 31, v36
	global_load_lds_dwordx4 v[16:17], off
	v_lshl_add_u64 v[16:17], v[36:37], 1, s[0:1]
	s_add_i32 m0, s12, 0x8c00
	s_add_u32 s0, s0, 0x100
	global_load_lds_dwordx4 v[16:17], off
	v_add_u32_e32 v16, v194, v21
	s_addc_u32 s1, s1, 0
	v_ashrrev_i32_e32 v17, 31, v16
	v_lshl_add_u64 v[154:155], v[16:17], 1, s[0:1]
	v_or_b32_e32 v16, s17, v206
	v_mad_u64_u32 v[16:17], s[18:19], s29, v16, v[20:21]
	v_ashrrev_i32_e32 v17, 31, v16
	v_lshl_add_u64 v[156:157], v[16:17], 1, s[0:1]
	v_or_b32_e32 v16, s17, v207
	v_mad_u64_u32 v[16:17], s[18:19], s29, v16, v[26:27]
	v_ashrrev_i32_e32 v17, 31, v16
	v_lshl_add_u64 v[158:159], v[16:17], 1, s[0:1]
	v_or_b32_e32 v16, s17, v208
	v_mad_u64_u32 v[16:17], s[18:19], s29, v16, v[32:33]
	v_ashrrev_i32_e32 v17, 31, v16
	s_lshl_b32 s14, s14, 14
	v_lshl_add_u64 v[160:161], v[16:17], 1, s[0:1]
	s_add_u32 s0, s10, s2
	s_addc_u32 s1, s11, 0
	v_or_b32_e32 v16, s14, v209
	s_add_u32 s0, s0, 0x40000
	v_ashrrev_i32_e32 v17, 31, v16
	s_addc_u32 s1, s1, 0
	v_lshl_add_u64 v[162:163], v[16:17], 1, s[0:1]
	v_or_b32_e32 v16, s14, v210
	v_add_u32_e32 v16, v16, v20
	v_ashrrev_i32_e32 v17, 31, v16
	v_lshl_add_u64 v[164:165], v[16:17], 1, s[0:1]
	v_or_b32_e32 v16, s14, v211
	v_add_u32_e32 v16, v16, v26
	v_ashrrev_i32_e32 v17, 31, v16
	v_lshl_add_u64 v[166:167], v[16:17], 1, s[0:1]
	v_or_b32_e32 v16, s14, v212
	v_add_u32_e32 v16, v16, v32
	s_waitcnt vmcnt(0)
	v_ashrrev_i32_e32 v17, 31, v16
	v_mov_b32_e32 v72, v145
	v_mov_b32_e32 v73, v145
	v_mov_b32_e32 v74, v145
	v_mov_b32_e32 v75, v145
	v_lshl_add_u64 v[168:169], v[16:17], 1, s[0:1]
	s_lshl_b32 s0, s29, 11
	v_mov_b32_e32 v151, v150
	v_mov_b64_e32 v[16:17], v[72:73]
	v_mov_b64_e32 v[24:25], v[72:73]
	v_mov_b64_e32 v[32:33], v[72:73]
	v_mov_b64_e32 v[40:41], v[72:73]
	v_mov_b64_e32 v[48:49], v[72:73]
	v_mov_b64_e32 v[56:57], v[72:73]
	v_mov_b64_e32 v[64:65], v[72:73]
	v_mov_b64_e32 v[78:79], v[74:75]
	v_mov_b64_e32 v[20:21], v[72:73]
	v_mov_b64_e32 v[28:29], v[72:73]
	v_mov_b64_e32 v[36:37], v[72:73]
	v_mov_b64_e32 v[44:45], v[72:73]
	v_mov_b64_e32 v[52:53], v[72:73]
	v_mov_b64_e32 v[60:61], v[72:73]
	v_mov_b64_e32 v[68:69], v[72:73]
	s_mov_b32 s13, 1
	s_and_b32 s2, s0, 0x7c0000
	v_mov_b32_e32 v174, v145
	v_mov_b32_e32 v175, v145
	s_mov_b32 s14, 0
	s_mov_b64 s[10:11], 0
	v_mov_b64_e32 v[18:19], v[74:75]
	v_mov_b64_e32 v[26:27], v[74:75]
	v_mov_b64_e32 v[34:35], v[74:75]
	v_mov_b64_e32 v[42:43], v[74:75]
	v_mov_b64_e32 v[50:51], v[74:75]
	v_mov_b64_e32 v[58:59], v[74:75]
	v_mov_b64_e32 v[66:67], v[74:75]
	v_mov_b64_e32 v[76:77], v[72:73]
	v_mov_b64_e32 v[22:23], v[74:75]
	v_mov_b64_e32 v[30:31], v[74:75]
	v_mov_b64_e32 v[38:39], v[74:75]
	v_mov_b64_e32 v[46:47], v[74:75]
	v_mov_b64_e32 v[54:55], v[74:75]
	v_mov_b64_e32 v[62:63], v[74:75]
	v_mov_b64_e32 v[70:71], v[74:75]
	v_mov_b64_e32 v[170:171], v[150:151]
	v_mov_b32_e32 v244, 0
	v_mov_b32_e32 v245, 0
	v_mov_b32_e32 v246, 0
	v_mov_b32_e32 v247, 0
	v_mov_b32_e32 v248, 0
	v_mov_b32_e32 v249, 0
	v_mov_b32_e32 v250, 0
	v_mov_b32_e32 v251, 0
	s_waitcnt vmcnt(0) lgkmcnt(0)
	s_barrier
	s_branch .LBB0_702
.LBB0_700:
	v_sub_f32_e32 v56, v56, v244
	v_sub_f32_e32 v57, v57, v248
	v_sub_f32_e32 v172, v172, v244
	v_sub_f32_e32 v173, v173, v248
	ds_bpermute_b32 v58, v188, v56
	ds_bpermute_b32 v59, v188, v57
	v_max_f32_e32 v56, v56, v56
	v_max_f32_e32 v57, v57, v57
	s_waitcnt lgkmcnt(1)
	v_max_f32_e32 v58, v58, v58
	s_waitcnt lgkmcnt(0)
	v_max_f32_e32 v59, v59, v59
	v_max_f32_e32 v56, v56, v58
	v_max_f32_e32 v57, v57, v59
	ds_bpermute_b32 v58, v187, v56
	ds_bpermute_b32 v59, v187, v57
	s_waitcnt lgkmcnt(1)
	v_max_f32_e32 v58, v58, v58
	s_waitcnt lgkmcnt(0)
	v_max_f32_e32 v59, v59, v59
	v_max_f32_e32 v56, v56, v58
	v_max_f32_e32 v57, v57, v59
	v_add_f32_e32 v58, 0x41000000, v171
	v_cmp_gt_f32_e32 vcc, v57, v58
	s_nop 1
	v_cndmask_b32_e32 v57, v175, v57, vcc
	v_cmp_gt_f32_e32 vcc, v56, v172
	s_nop 1
	v_cndmask_b32_e32 v56, v174, v56, vcc
	v_pk_add_f32 v[58:59], v[174:175], v[56:57] neg_lo:[0,1] neg_hi:[0,1]
	v_mov_b64_e32 v[170:171], v[56:57]
	v_exp_f32_e32 v58, v58
	v_exp_f32_e32 v60, v59
	v_mov_b32_e32 v61, v58
	v_pk_mul_f32 v[134:135], v[134:135], v[58:59] op_sel_hi:[1,0]
	v_pk_mul_f32 v[132:133], v[132:133], v[58:59] op_sel_hi:[1,0]
	v_pk_mul_f32 v[126:127], v[126:127], v[58:59] op_sel_hi:[1,0]
	v_pk_mul_f32 v[124:125], v[124:125], v[58:59] op_sel_hi:[1,0]
	v_pk_mul_f32 v[118:119], v[118:119], v[58:59] op_sel_hi:[1,0]
	v_pk_mul_f32 v[116:117], v[116:117], v[58:59] op_sel_hi:[1,0]
	v_pk_mul_f32 v[110:111], v[110:111], v[58:59] op_sel_hi:[1,0]
	v_pk_mul_f32 v[108:109], v[108:109], v[58:59] op_sel_hi:[1,0]
	v_pk_mul_f32 v[102:103], v[102:103], v[58:59] op_sel_hi:[1,0]
	v_pk_mul_f32 v[100:101], v[100:101], v[58:59] op_sel_hi:[1,0]
	v_pk_mul_f32 v[94:95], v[94:95], v[58:59] op_sel_hi:[1,0]
	v_pk_mul_f32 v[92:93], v[92:93], v[58:59] op_sel_hi:[1,0]
	v_pk_mul_f32 v[86:87], v[86:87], v[58:59] op_sel_hi:[1,0]
	v_pk_mul_f32 v[84:85], v[84:85], v[58:59] op_sel_hi:[1,0]
	v_pk_mul_f32 v[74:75], v[74:75], v[58:59] op_sel_hi:[1,0]
	v_pk_mul_f32 v[72:73], v[72:73], v[58:59] op_sel_hi:[1,0]
	v_pk_mul_f32 v[176:177], v[176:177], v[60:61]
	v_pk_mul_f32 v[130:131], v[130:131], v[60:61] op_sel_hi:[1,0]
	v_pk_mul_f32 v[128:129], v[128:129], v[60:61] op_sel_hi:[1,0]
	v_pk_mul_f32 v[122:123], v[122:123], v[60:61] op_sel_hi:[1,0]
	v_pk_mul_f32 v[120:121], v[120:121], v[60:61] op_sel_hi:[1,0]
	v_pk_mul_f32 v[114:115], v[114:115], v[60:61] op_sel_hi:[1,0]
	v_pk_mul_f32 v[112:113], v[112:113], v[60:61] op_sel_hi:[1,0]
	v_pk_mul_f32 v[106:107], v[106:107], v[60:61] op_sel_hi:[1,0]
	v_pk_mul_f32 v[104:105], v[104:105], v[60:61] op_sel_hi:[1,0]
	v_pk_mul_f32 v[98:99], v[98:99], v[60:61] op_sel_hi:[1,0]
	v_pk_mul_f32 v[96:97], v[96:97], v[60:61] op_sel_hi:[1,0]
	v_pk_mul_f32 v[90:91], v[90:91], v[60:61] op_sel_hi:[1,0]
	v_pk_mul_f32 v[88:89], v[88:89], v[60:61] op_sel_hi:[1,0]
	v_pk_mul_f32 v[82:83], v[82:83], v[60:61] op_sel_hi:[1,0]
	v_pk_mul_f32 v[80:81], v[80:81], v[60:61] op_sel_hi:[1,0]
	v_pk_mul_f32 v[78:79], v[78:79], v[60:61] op_sel_hi:[1,0]
	v_pk_mul_f32 v[76:77], v[76:77], v[60:61] op_sel_hi:[1,0]
	v_add_f32_e32 v242, v56, v244
	v_add_f32_e32 v243, v57, v248
	v_sub_f32_e32 v40, v40, v243
	v_sub_f32_e32 v41, v41, v243
	v_sub_f32_e32 v42, v42, v243
	v_sub_f32_e32 v43, v43, v243
	v_sub_f32_e32 v44, v44, v243
	v_sub_f32_e32 v45, v45, v243
	v_sub_f32_e32 v46, v46, v243
	v_sub_f32_e32 v47, v47, v243
	v_sub_f32_e32 v48, v48, v242
	v_sub_f32_e32 v49, v49, v242
	v_sub_f32_e32 v50, v50, v242
	v_sub_f32_e32 v51, v51, v242
	v_sub_f32_e32 v52, v52, v242
	v_sub_f32_e32 v53, v53, v242
	v_sub_f32_e32 v54, v54, v242
	v_sub_f32_e32 v55, v55, v242
	v_sub_f32_e32 v244, 0, v56
	v_sub_f32_e32 v245, 0, v56
	v_sub_f32_e32 v246, 0, v56
	v_sub_f32_e32 v247, 0, v56
	v_sub_f32_e32 v248, 0, v57
	v_sub_f32_e32 v249, 0, v57
	v_sub_f32_e32 v250, 0, v57
	v_sub_f32_e32 v251, 0, v57
	v_mov_b32_e32 v172, 0x41000000
	v_mov_b32_e32 v173, 0x41000000
.LBB0_701:
	v_exp_f32_e32 v59, v52
	v_exp_f32_e32 v53, v53
	v_exp_f32_e32 v63, v48
	v_exp_f32_e32 v61, v54
	v_exp_f32_e32 v49, v49
	v_exp_f32_e32 v58, v44
	v_exp_f32_e32 v55, v55
	v_exp_f32_e32 v65, v50
	v_exp_f32_e32 v52, v45
	v_exp_f32_e32 v62, v40
	v_exp_f32_e32 v51, v51
	v_exp_f32_e32 v60, v46
	v_exp_f32_e32 v48, v41
	v_exp_f32_e32 v54, v47
	v_exp_f32_e32 v64, v42
	v_exp_f32_e32 v50, v43
	v_pk_add_f32 v[40:41], v[58:59], 0 op_sel_hi:[1,0]
	v_cvt_pk_bf16_f32 v214, v59, v53
	v_pk_add_f32 v[40:41], v[52:53], v[40:41]
	v_cvt_pk_bf16_f32 v215, v61, v55
	v_pk_add_f32 v[40:41], v[60:61], v[40:41]
	v_cvt_pk_bf16_f32 v216, v63, v49
	v_pk_add_f32 v[40:41], v[54:55], v[40:41]
	v_cvt_pk_bf16_f32 v217, v65, v51
	v_pk_add_f32 v[40:41], v[62:63], v[40:41]
	v_cvt_pk_bf16_f32 v218, v58, v52
	v_pk_add_f32 v[40:41], v[48:49], v[40:41]
	v_cvt_pk_bf16_f32 v219, v60, v54
	v_pk_add_f32 v[40:41], v[64:65], v[40:41]
	v_cvt_pk_bf16_f32 v220, v62, v48
	v_pk_add_f32 v[40:41], v[50:51], v[40:41]
	v_cvt_pk_bf16_f32 v221, v64, v50
	v_pk_add_f32 v[174:175], v[176:177], v[40:41]
	s_setprio 1
	s_waitcnt lgkmcnt(0)
	s_nop 1
	v_mfma_f32_16x16x32_bf16 v[56:59], v[32:35], v[214:217], v[124:127]
	v_mfma_f32_16x16x32_bf16 v[60:63], v[32:35], v[218:221], v[120:123]
	v_mfma_f32_16x16x32_bf16 v[64:67], v[36:39], v[214:217], v[132:135]
	v_mfma_f32_16x16x32_bf16 v[68:71], v[36:39], v[218:221], v[128:131]
	v_mfma_f32_16x16x32_bf16 v[40:43], v[24:27], v[214:217], v[108:111]
	v_mfma_f32_16x16x32_bf16 v[44:47], v[24:27], v[218:221], v[104:107]
	v_mfma_f32_16x16x32_bf16 v[48:51], v[28:31], v[214:217], v[116:119]
	v_mfma_f32_16x16x32_bf16 v[52:55], v[28:31], v[218:221], v[112:115]
	v_mfma_f32_16x16x32_bf16 v[32:35], v[20:23], v[214:217], v[100:103]
	v_mfma_f32_16x16x32_bf16 v[36:39], v[20:23], v[218:221], v[96:99]
	v_mfma_f32_16x16x32_bf16 v[24:27], v[16:19], v[214:217], v[92:95]
	v_mfma_f32_16x16x32_bf16 v[28:31], v[16:19], v[218:221], v[88:91]
	v_mfma_f32_16x16x32_bf16 v[16:19], v[140:143], v[214:217], v[84:87]
	v_mfma_f32_16x16x32_bf16 v[20:23], v[140:143], v[218:221], v[80:83]
	v_mfma_f32_16x16x32_bf16 v[72:75], v[136:139], v[214:217], v[72:75]
	v_mfma_f32_16x16x32_bf16 v[76:79], v[136:139], v[218:221], v[76:79]
	s_setprio 0
	s_add_i32 s14, s14, 0x10000
	s_waitcnt vmcnt(0)
	s_add_u32 s10, s10, 0x40000
	s_addc_u32 s11, s11, 0
	s_add_i32 s13, s13, 1
	v_lshl_add_u64 v[154:155], v[154:155], 0, s[6:7]
	v_lshl_add_u64 v[156:157], v[156:157], 0, s[6:7]
	v_lshl_add_u64 v[158:159], v[158:159], 0, s[6:7]
	s_cmp_eq_u32 s2, s10
	v_lshl_add_u64 v[160:161], v[160:161], 0, s[6:7]
	s_barrier
	s_cbranch_scc1 .LBB0_685

.LBB0_704:
	s_and_b32 s0, s14, 0x10000
	s_add_i32 s17, s0, 0
	v_add_u32_e32 v88, s17, v192
	v_add_u32_e32 v149, v88, v195
	v_add_u32_e32 v151, v88, v196
	v_add_u32_e32 v214, v88, v197
	v_add_u32_e32 v215, v88, v198
	v_add_u32_e32 v88, s17, v193
	v_add_u32_e32 v89, s17, v199
	ds_read_b128 v[80:83], v149
	ds_read_b128 v[84:87], v149 offset:4096
	ds_read_b128 v[120:123], v151
	ds_read_b128 v[128:131], v151 offset:4096
	ds_read_b128 v[132:135], v214
	ds_read_b128 v[136:139], v214 offset:4096
	ds_read_b128 v[140:143], v215
	ds_read_b128 v[216:219], v215 offset:4096
	ds_read_b64 v[116:117], v88 offset:32768
	ds_read_b64 v[118:119], v89 offset:32768
	ds_read_b64 v[112:113], v88 offset:36864
	ds_read_b64 v[114:115], v89 offset:36864
	ds_read_b64 v[108:109], v88 offset:40960
	ds_read_b64 v[110:111], v89 offset:40960
	ds_read_b64 v[104:105], v88 offset:45056
	ds_read_b64 v[106:107], v89 offset:45056
	ds_read_b64 v[100:101], v88 offset:49152
	ds_read_b64 v[102:103], v89 offset:49152
	ds_read_b64 v[96:97], v88 offset:53248
	ds_read_b64 v[98:99], v89 offset:53248
	ds_read_b64 v[92:93], v88 offset:57344
	ds_read_b64 v[94:95], v89 offset:57344
	ds_read_b64 v[90:91], v89 offset:61440
	ds_read_b64 v[88:89], v88 offset:61440
	s_waitcnt lgkmcnt(0)
	v_mfma_f32_16x16x32_bf16 v[80:83], v[80:83], v[0:3], v[244:247]
	v_mfma_f32_16x16x32_bf16 v[124:127], v[120:123], v[4:7], v[80:83]
	v_mfma_f32_16x16x32_bf16 v[80:83], v[84:87], v[0:3], v[244:247]
	v_mfma_f32_16x16x32_bf16 v[120:123], v[128:131], v[4:7], v[80:83]
	v_mfma_f32_16x16x32_bf16 v[80:83], v[132:135], v[8:11], v[248:251]
	v_mfma_f32_16x16x32_bf16 v[84:87], v[140:143], v[12:15], v[80:83]
	v_mfma_f32_16x16x32_bf16 v[80:83], v[136:139], v[8:11], v[248:251]
	v_mfma_f32_16x16x32_bf16 v[80:83], v[216:219], v[12:15], v[80:83]
	s_nop 1
	v_max3_f32 v128, v124, v125, v126
	s_nop 0
	v_max3_f32 v128, v128, v127, v120
	v_max3_f32 v128, v128, v121, v122
	v_max_f32_e32 v128, v128, v123
	v_max3_f32 v129, v84, v85, v86
	v_max3_f32 v129, v129, v87, v80
	v_max3_f32 v129, v129, v81, v82
	v_max_f32_e32 v129, v129, v83
	v_pk_add_f32 v[172:173], v[170:171], s[8:9] op_sel_hi:[1,0]
	v_add_f32_e32 v172, v172, v244
	v_add_f32_e32 v173, v173, v248
	s_nop 0
	v_cmp_gt_f32_e32 vcc, v128, v172
	v_cmp_gt_f32_e64 s[0:1], v129, v173
	s_or_b64 vcc, vcc, s[0:1]
	s_cbranch_vccz .LBB0_706
	v_sub_f32_e32 v128, v128, v244
	v_sub_f32_e32 v129, v129, v248
	v_sub_f32_e32 v172, v172, v244
	v_sub_f32_e32 v173, v173, v248
	ds_bpermute_b32 v131, v188, v129
	ds_bpermute_b32 v130, v188, v128
	v_max_f32_e32 v129, v129, v129
	v_max_f32_e32 v128, v128, v128
	s_waitcnt lgkmcnt(1)
	v_max_f32_e32 v131, v131, v131
	s_waitcnt lgkmcnt(0)
	v_max_f32_e32 v130, v130, v130
	v_max_f32_e32 v129, v129, v131
	v_max_f32_e32 v128, v128, v130
	ds_bpermute_b32 v131, v187, v129
	ds_bpermute_b32 v130, v187, v128
	s_waitcnt lgkmcnt(1)
	v_max_f32_e32 v131, v131, v131
	s_waitcnt lgkmcnt(0)
	v_max_f32_e32 v130, v130, v130
	v_max_f32_e32 v129, v129, v131
	v_max_f32_e32 v128, v128, v130
	v_cmp_gt_f32_e32 vcc, v129, v173
	s_nop 1
	v_cndmask_b32_e32 v129, v171, v129, vcc
	v_cmp_gt_f32_e32 vcc, v128, v172
	s_nop 1
	v_cndmask_b32_e32 v128, v170, v128, vcc
	v_pk_add_f32 v[130:131], v[170:171], v[128:129] neg_lo:[0,1] neg_hi:[0,1]
	v_pk_add_f32 v[172:173], v[128:129], s[8:9] op_sel_hi:[1,0]
	v_exp_f32_e32 v130, v130
	v_exp_f32_e32 v132, v131
	v_mov_b64_e32 v[170:171], v[128:129]
	v_mov_b32_e32 v133, v130
	v_pk_mul_f32 v[66:67], v[66:67], v[130:131] op_sel_hi:[1,0]
	v_pk_mul_f32 v[64:65], v[64:65], v[130:131] op_sel_hi:[1,0]
	v_pk_mul_f32 v[58:59], v[58:59], v[130:131] op_sel_hi:[1,0]
	v_pk_mul_f32 v[56:57], v[56:57], v[130:131] op_sel_hi:[1,0]
	v_pk_mul_f32 v[50:51], v[50:51], v[130:131] op_sel_hi:[1,0]
	v_pk_mul_f32 v[48:49], v[48:49], v[130:131] op_sel_hi:[1,0]
	v_pk_mul_f32 v[42:43], v[42:43], v[130:131] op_sel_hi:[1,0]
	v_pk_mul_f32 v[40:41], v[40:41], v[130:131] op_sel_hi:[1,0]
	v_pk_mul_f32 v[34:35], v[34:35], v[130:131] op_sel_hi:[1,0]
	v_pk_mul_f32 v[32:33], v[32:33], v[130:131] op_sel_hi:[1,0]
	v_pk_mul_f32 v[26:27], v[26:27], v[130:131] op_sel_hi:[1,0]
	v_pk_mul_f32 v[24:25], v[24:25], v[130:131] op_sel_hi:[1,0]
	v_pk_mul_f32 v[18:19], v[18:19], v[130:131] op_sel_hi:[1,0]
	v_pk_mul_f32 v[16:17], v[16:17], v[130:131] op_sel_hi:[1,0]
	v_pk_mul_f32 v[74:75], v[74:75], v[130:131] op_sel_hi:[1,0]
	v_pk_mul_f32 v[72:73], v[72:73], v[130:131] op_sel_hi:[1,0]
	v_pk_mul_f32 v[174:175], v[174:175], v[132:133]
	v_pk_mul_f32 v[70:71], v[70:71], v[132:133] op_sel_hi:[1,0]
	v_pk_mul_f32 v[68:69], v[68:69], v[132:133] op_sel_hi:[1,0]
	v_pk_mul_f32 v[62:63], v[62:63], v[132:133] op_sel_hi:[1,0]
	v_pk_mul_f32 v[60:61], v[60:61], v[132:133] op_sel_hi:[1,0]
	v_pk_mul_f32 v[54:55], v[54:55], v[132:133] op_sel_hi:[1,0]
	v_pk_mul_f32 v[52:53], v[52:53], v[132:133] op_sel_hi:[1,0]
	v_pk_mul_f32 v[46:47], v[46:47], v[132:133] op_sel_hi:[1,0]
	v_pk_mul_f32 v[44:45], v[44:45], v[132:133] op_sel_hi:[1,0]
	v_pk_mul_f32 v[38:39], v[38:39], v[132:133] op_sel_hi:[1,0]
	v_pk_mul_f32 v[36:37], v[36:37], v[132:133] op_sel_hi:[1,0]
	v_pk_mul_f32 v[30:31], v[30:31], v[132:133] op_sel_hi:[1,0]
	v_pk_mul_f32 v[28:29], v[28:29], v[132:133] op_sel_hi:[1,0]
	v_pk_mul_f32 v[22:23], v[22:23], v[132:133] op_sel_hi:[1,0]
	v_pk_mul_f32 v[20:21], v[20:21], v[132:133] op_sel_hi:[1,0]
	v_pk_mul_f32 v[78:79], v[78:79], v[132:133] op_sel_hi:[1,0]
	v_pk_mul_f32 v[76:77], v[76:77], v[132:133] op_sel_hi:[1,0]
	v_add_f32_e32 v242, v170, v244
	v_add_f32_e32 v243, v171, v248
	v_sub_f32_e32 v80, v80, v243
	v_sub_f32_e32 v81, v81, v243
	v_sub_f32_e32 v82, v82, v243
	v_sub_f32_e32 v83, v83, v243
	v_sub_f32_e32 v84, v84, v243
	v_sub_f32_e32 v85, v85, v243
	v_sub_f32_e32 v86, v86, v243
	v_sub_f32_e32 v87, v87, v243
	v_sub_f32_e32 v120, v120, v242
	v_sub_f32_e32 v121, v121, v242
	v_sub_f32_e32 v122, v122, v242
	v_sub_f32_e32 v123, v123, v242
	v_sub_f32_e32 v124, v124, v242
	v_sub_f32_e32 v125, v125, v242
	v_sub_f32_e32 v126, v126, v242
	v_sub_f32_e32 v127, v127, v242
	v_sub_f32_e32 v244, 0, v170
	v_sub_f32_e32 v245, 0, v170
	v_sub_f32_e32 v246, 0, v170
	v_sub_f32_e32 v247, 0, v170
	v_sub_f32_e32 v248, 0, v171
	v_sub_f32_e32 v249, 0, v171
	v_sub_f32_e32 v250, 0, v171
	v_sub_f32_e32 v251, 0, v171
	v_mov_b32_e32 v172, 0x41000000
	v_mov_b32_e32 v173, 0x41000000
.LBB0_706:
	v_exp_f32_e32 v129, v124
	v_exp_f32_e32 v128, v84
	v_exp_f32_e32 v131, v125
	v_exp_f32_e32 v130, v85
	v_exp_f32_e32 v133, v126
	v_exp_f32_e32 v132, v86
	v_exp_f32_e32 v135, v127
	v_exp_f32_e32 v134, v87
	v_exp_f32_e32 v137, v120
	v_exp_f32_e32 v136, v80
	v_pk_add_f32 v[84:85], v[128:129], 0 op_sel_hi:[1,0]
	v_exp_f32_e32 v139, v121
	v_pk_add_f32 v[84:85], v[130:131], v[84:85]
	v_exp_f32_e32 v138, v81
	v_exp_f32_e32 v141, v122
	v_pk_add_f32 v[84:85], v[132:133], v[84:85]
	v_exp_f32_e32 v140, v82
	v_exp_f32_e32 v143, v123
	v_pk_add_f32 v[84:85], v[134:135], v[84:85]
	v_exp_f32_e32 v142, v83
	v_pk_add_f32 v[80:81], v[136:137], v[84:85]
	v_cvt_pk_bf16_f32 v124, v129, v131
	v_pk_add_f32 v[80:81], v[138:139], v[80:81]
	v_cvt_pk_bf16_f32 v125, v133, v135
	v_pk_add_f32 v[80:81], v[140:141], v[80:81]
	v_cvt_pk_bf16_f32 v126, v137, v139
	v_pk_add_f32 v[80:81], v[142:143], v[80:81]
	v_cvt_pk_bf16_f32 v127, v141, v143
	v_cvt_pk_bf16_f32 v120, v128, v130
	v_cvt_pk_bf16_f32 v121, v132, v134
	v_cvt_pk_bf16_f32 v122, v136, v138
	v_cvt_pk_bf16_f32 v123, v140, v142
	v_pk_add_f32 v[128:129], v[174:175], v[80:81]
	s_setprio 1
	s_waitcnt lgkmcnt(0)
	s_nop 1
	v_mfma_f32_16x16x32_bf16 v[80:83], v[116:119], v[124:127], v[64:67]
	v_mfma_f32_16x16x32_bf16 v[84:87], v[116:119], v[120:123], v[68:71]
	v_mfma_f32_16x16x32_bf16 v[68:71], v[112:115], v[120:123], v[60:63]
	v_mfma_f32_16x16x32_bf16 v[64:67], v[112:115], v[124:127], v[56:59]
	v_mfma_f32_16x16x32_bf16 v[56:59], v[108:111], v[124:127], v[48:51]
	v_mfma_f32_16x16x32_bf16 v[60:63], v[108:111], v[120:123], v[52:55]
	v_mfma_f32_16x16x32_bf16 v[52:55], v[104:107], v[120:123], v[44:47]
	v_mfma_f32_16x16x32_bf16 v[48:51], v[104:107], v[124:127], v[40:43]
	v_mfma_f32_16x16x32_bf16 v[40:43], v[100:103], v[124:127], v[32:35]
	v_mfma_f32_16x16x32_bf16 v[44:47], v[100:103], v[120:123], v[36:39]
	v_mfma_f32_16x16x32_bf16 v[36:39], v[96:99], v[120:123], v[28:31]
	v_mfma_f32_16x16x32_bf16 v[32:35], v[96:99], v[124:127], v[24:27]
	v_mfma_f32_16x16x32_bf16 v[24:27], v[92:95], v[124:127], v[16:19]
	v_mfma_f32_16x16x32_bf16 v[28:31], v[92:95], v[120:123], v[20:23]
	v_mfma_f32_16x16x32_bf16 v[16:19], v[88:91], v[124:127], v[72:75]
	v_mfma_f32_16x16x32_bf16 v[20:23], v[88:91], v[120:123], v[76:79]
	s_setprio 0
	s_nop 0
	ds_read_b128 v[72:75], v149 offset:8192
	ds_read_b128 v[76:79], v149 offset:12288
	ds_read_b128 v[120:123], v151 offset:8192
	ds_read_b128 v[130:133], v151 offset:12288
	ds_read_b128 v[134:137], v214 offset:8192
	ds_read_b128 v[138:141], v214 offset:12288
	ds_read_b128 v[174:177], v215 offset:8192
	ds_read_b128 v[216:219], v215 offset:12288
	v_add_u32_e32 v88, s17, v200
	v_add_u32_e32 v89, s17, v201
	ds_read_b64 v[116:117], v88 offset:32768
	ds_read_b64 v[118:119], v89 offset:32768
	ds_read_b64 v[112:113], v88 offset:36864
	ds_read_b64 v[114:115], v89 offset:36864
	ds_read_b64 v[108:109], v88 offset:40960
	ds_read_b64 v[110:111], v89 offset:40960
	ds_read_b64 v[104:105], v88 offset:45056
	ds_read_b64 v[106:107], v89 offset:45056
	ds_read_b64 v[100:101], v88 offset:49152
	ds_read_b64 v[102:103], v89 offset:49152
	ds_read_b64 v[96:97], v88 offset:53248
	ds_read_b64 v[98:99], v89 offset:53248
	ds_read_b64 v[92:93], v88 offset:57344
	ds_read_b64 v[94:95], v89 offset:57344
	ds_read_b64 v[90:91], v89 offset:61440
	ds_read_b64 v[88:89], v88 offset:61440
	s_waitcnt lgkmcnt(14)
	v_mfma_f32_16x16x32_bf16 v[72:75], v[72:75], v[0:3], v[244:247]
	s_waitcnt lgkmcnt(13)
	v_mfma_f32_16x16x32_bf16 v[124:127], v[120:123], v[4:7], v[72:75]
	v_mfma_f32_16x16x32_bf16 v[72:75], v[76:79], v[0:3], v[244:247]
	s_waitcnt lgkmcnt(12)
	v_mfma_f32_16x16x32_bf16 v[120:123], v[130:133], v[4:7], v[72:75]
	s_waitcnt lgkmcnt(11)
	v_mfma_f32_16x16x32_bf16 v[72:75], v[134:137], v[8:11], v[248:251]
	s_waitcnt lgkmcnt(9)
	v_mfma_f32_16x16x32_bf16 v[76:79], v[174:177], v[12:15], v[72:75]
	v_mfma_f32_16x16x32_bf16 v[72:75], v[138:141], v[8:11], v[248:251]
	s_waitcnt lgkmcnt(8)
	v_mfma_f32_16x16x32_bf16 v[72:75], v[216:219], v[12:15], v[72:75]
	v_max3_f32 v130, v124, v125, v126
	v_max3_f32 v130, v130, v127, v120
	v_max3_f32 v130, v130, v121, v122
	v_max_f32_e32 v130, v130, v123
	s_nop 0
	v_max3_f32 v131, v76, v77, v78
	s_nop 1
	v_max3_f32 v131, v131, v79, v72
	v_max3_f32 v131, v131, v73, v74
	v_max_f32_e32 v131, v131, v75
	v_cmp_gt_f32_e32 vcc, v130, v172
	v_cmp_gt_f32_e64 s[0:1], v131, v173
	s_or_b64 vcc, vcc, s[0:1]
	s_cbranch_vccz .LBB0_708
	v_sub_f32_e32 v130, v130, v244
	v_sub_f32_e32 v131, v131, v248
	v_sub_f32_e32 v172, v172, v244
	v_sub_f32_e32 v173, v173, v248
	ds_bpermute_b32 v132, v188, v130
	ds_bpermute_b32 v133, v188, v131
	v_max_f32_e32 v130, v130, v130
	v_max_f32_e32 v131, v131, v131
	s_waitcnt lgkmcnt(1)
	v_max_f32_e32 v132, v132, v132
	s_waitcnt lgkmcnt(0)
	v_max_f32_e32 v133, v133, v133
	v_max_f32_e32 v130, v130, v132
	v_max_f32_e32 v131, v131, v133
	ds_bpermute_b32 v132, v187, v130
	ds_bpermute_b32 v133, v187, v131
	s_waitcnt lgkmcnt(1)
	v_max_f32_e32 v132, v132, v132
	s_waitcnt lgkmcnt(0)
	v_max_f32_e32 v133, v133, v133
	v_max_f32_e32 v130, v130, v132
	v_max_f32_e32 v131, v131, v133
	v_add_f32_e32 v132, 0x41000000, v171
	v_cmp_gt_f32_e32 vcc, v131, v132
	s_nop 1
	v_cndmask_b32_e32 v175, v171, v131, vcc
	v_cmp_gt_f32_e32 vcc, v130, v172
	s_nop 1
	v_cndmask_b32_e32 v174, v170, v130, vcc
	v_pk_add_f32 v[130:131], v[170:171], v[174:175] neg_lo:[0,1] neg_hi:[0,1]
	v_pk_add_f32 v[172:173], v[174:175], s[8:9] op_sel_hi:[1,0]
	v_exp_f32_e32 v130, v130
	v_exp_f32_e32 v132, v131
	v_mov_b32_e32 v171, v175
	v_mov_b32_e32 v170, v174
	v_mov_b32_e32 v133, v130
	v_pk_mul_f32 v[82:83], v[82:83], v[130:131] op_sel_hi:[1,0]
	v_pk_mul_f32 v[80:81], v[80:81], v[130:131] op_sel_hi:[1,0]
	v_pk_mul_f32 v[66:67], v[66:67], v[130:131] op_sel_hi:[1,0]
	v_pk_mul_f32 v[64:65], v[64:65], v[130:131] op_sel_hi:[1,0]
	v_pk_mul_f32 v[58:59], v[58:59], v[130:131] op_sel_hi:[1,0]
	v_pk_mul_f32 v[56:57], v[56:57], v[130:131] op_sel_hi:[1,0]
	v_pk_mul_f32 v[50:51], v[50:51], v[130:131] op_sel_hi:[1,0]
	v_pk_mul_f32 v[48:49], v[48:49], v[130:131] op_sel_hi:[1,0]
	v_pk_mul_f32 v[42:43], v[42:43], v[130:131] op_sel_hi:[1,0]
	v_pk_mul_f32 v[40:41], v[40:41], v[130:131] op_sel_hi:[1,0]
	v_pk_mul_f32 v[34:35], v[34:35], v[130:131] op_sel_hi:[1,0]
	v_pk_mul_f32 v[32:33], v[32:33], v[130:131] op_sel_hi:[1,0]
	v_pk_mul_f32 v[26:27], v[26:27], v[130:131] op_sel_hi:[1,0]
	v_pk_mul_f32 v[24:25], v[24:25], v[130:131] op_sel_hi:[1,0]
	v_pk_mul_f32 v[18:19], v[18:19], v[130:131] op_sel_hi:[1,0]
	v_pk_mul_f32 v[16:17], v[16:17], v[130:131] op_sel_hi:[1,0]
	v_pk_mul_f32 v[128:129], v[128:129], v[132:133]
	v_pk_mul_f32 v[86:87], v[86:87], v[132:133] op_sel_hi:[1,0]
	v_pk_mul_f32 v[84:85], v[84:85], v[132:133] op_sel_hi:[1,0]
	v_pk_mul_f32 v[70:71], v[70:71], v[132:133] op_sel_hi:[1,0]
	v_pk_mul_f32 v[68:69], v[68:69], v[132:133] op_sel_hi:[1,0]
	v_pk_mul_f32 v[62:63], v[62:63], v[132:133] op_sel_hi:[1,0]
	v_pk_mul_f32 v[60:61], v[60:61], v[132:133] op_sel_hi:[1,0]
	v_pk_mul_f32 v[54:55], v[54:55], v[132:133] op_sel_hi:[1,0]
	v_pk_mul_f32 v[52:53], v[52:53], v[132:133] op_sel_hi:[1,0]
	v_pk_mul_f32 v[46:47], v[46:47], v[132:133] op_sel_hi:[1,0]
	v_pk_mul_f32 v[44:45], v[44:45], v[132:133] op_sel_hi:[1,0]
	v_pk_mul_f32 v[38:39], v[38:39], v[132:133] op_sel_hi:[1,0]
	v_pk_mul_f32 v[36:37], v[36:37], v[132:133] op_sel_hi:[1,0]
	v_pk_mul_f32 v[30:31], v[30:31], v[132:133] op_sel_hi:[1,0]
	v_pk_mul_f32 v[28:29], v[28:29], v[132:133] op_sel_hi:[1,0]
	v_pk_mul_f32 v[22:23], v[22:23], v[132:133] op_sel_hi:[1,0]
	v_pk_mul_f32 v[20:21], v[20:21], v[132:133] op_sel_hi:[1,0]
	v_add_f32_e32 v242, v170, v244
	v_add_f32_e32 v243, v171, v248
	v_sub_f32_e32 v72, v72, v243
	v_sub_f32_e32 v73, v73, v243
	v_sub_f32_e32 v74, v74, v243
	v_sub_f32_e32 v75, v75, v243
	v_sub_f32_e32 v76, v76, v243
	v_sub_f32_e32 v77, v77, v243
	v_sub_f32_e32 v78, v78, v243
	v_sub_f32_e32 v79, v79, v243
	v_sub_f32_e32 v120, v120, v242
	v_sub_f32_e32 v121, v121, v242
	v_sub_f32_e32 v122, v122, v242
	v_sub_f32_e32 v123, v123, v242
	v_sub_f32_e32 v124, v124, v242
	v_sub_f32_e32 v125, v125, v242
	v_sub_f32_e32 v126, v126, v242
	v_sub_f32_e32 v127, v127, v242
	v_sub_f32_e32 v244, 0, v170
	v_sub_f32_e32 v245, 0, v170
	v_sub_f32_e32 v246, 0, v170
	v_sub_f32_e32 v247, 0, v170
	v_sub_f32_e32 v248, 0, v171
	v_sub_f32_e32 v249, 0, v171
	v_sub_f32_e32 v250, 0, v171
	v_sub_f32_e32 v251, 0, v171
	v_mov_b32_e32 v172, 0x41000000
	v_mov_b32_e32 v173, 0x41000000
	s_branch .LBB0_709

.LBB0_709:
	v_exp_f32_e32 v131, v124
	v_exp_f32_e32 v130, v76
	v_exp_f32_e32 v133, v125
	v_exp_f32_e32 v137, v120
	v_exp_f32_e32 v132, v77
	v_exp_f32_e32 v135, v126
	v_exp_f32_e32 v121, v121
	v_exp_f32_e32 v134, v78
	v_exp_f32_e32 v127, v127
	v_exp_f32_e32 v139, v122
	v_exp_f32_e32 v126, v79
	v_exp_f32_e32 v136, v72
	v_exp_f32_e32 v141, v123
	v_pk_add_f32 v[76:77], v[130:131], 0 op_sel_hi:[1,0]
	v_exp_f32_e32 v120, v73
	v_pk_add_f32 v[76:77], v[132:133], v[76:77]
	v_exp_f32_e32 v138, v74
	v_exp_f32_e32 v140, v75
	v_pk_add_f32 v[72:73], v[134:135], v[76:77]
	v_cvt_pk_bf16_f32 v122, v131, v133
	v_pk_add_f32 v[72:73], v[126:127], v[72:73]
	v_cvt_pk_bf16_f32 v123, v135, v127
	v_pk_add_f32 v[72:73], v[136:137], v[72:73]
	v_cvt_pk_bf16_f32 v124, v137, v121
	v_pk_add_f32 v[72:73], v[120:121], v[72:73]
	v_cvt_pk_bf16_f32 v130, v130, v132
	v_pk_add_f32 v[72:73], v[138:139], v[72:73]
	v_cvt_pk_bf16_f32 v132, v136, v120
	v_pk_add_f32 v[72:73], v[140:141], v[72:73]
	v_cvt_pk_bf16_f32 v125, v139, v141
	v_pk_add_f32 v[120:121], v[128:129], v[72:73]
	v_cvt_pk_bf16_f32 v131, v134, v126
	v_cvt_pk_bf16_f32 v133, v138, v140
	s_setprio 1
	s_waitcnt lgkmcnt(0)
	s_nop 1
	v_mfma_f32_16x16x32_bf16 v[72:75], v[116:119], v[122:125], v[80:83]
	v_mfma_f32_16x16x32_bf16 v[56:59], v[108:111], v[122:125], v[56:59]
	v_mfma_f32_16x16x32_bf16 v[60:63], v[108:111], v[130:133], v[60:63]
	v_mfma_f32_16x16x32_bf16 v[40:43], v[100:103], v[122:125], v[40:43]
	v_mfma_f32_16x16x32_bf16 v[44:47], v[100:103], v[130:133], v[44:47]
	v_mfma_f32_16x16x32_bf16 v[76:79], v[116:119], v[130:133], v[84:87]
	v_mfma_f32_16x16x32_bf16 v[64:67], v[112:115], v[122:125], v[64:67]
	v_mfma_f32_16x16x32_bf16 v[68:71], v[112:115], v[130:133], v[68:71]
	v_mfma_f32_16x16x32_bf16 v[48:51], v[104:107], v[122:125], v[48:51]
	v_mfma_f32_16x16x32_bf16 v[52:55], v[104:107], v[130:133], v[52:55]
	v_mfma_f32_16x16x32_bf16 v[32:35], v[96:99], v[122:125], v[32:35]
	v_mfma_f32_16x16x32_bf16 v[36:39], v[96:99], v[130:133], v[36:39]
	v_mfma_f32_16x16x32_bf16 v[24:27], v[92:95], v[122:125], v[24:27]
	v_mfma_f32_16x16x32_bf16 v[28:31], v[92:95], v[130:133], v[28:31]
	v_mfma_f32_16x16x32_bf16 v[16:19], v[88:91], v[122:125], v[16:19]
	v_mfma_f32_16x16x32_bf16 v[20:23], v[88:91], v[130:133], v[20:23]
	s_setprio 0
	ds_read_b128 v[104:107], v149 offset:16384
	ds_read_b128 v[108:111], v149 offset:20480
	ds_read_b128 v[112:115], v151 offset:16384
	ds_read_b128 v[122:125], v151 offset:20480
	ds_read_b128 v[126:129], v214 offset:16384
	ds_read_b128 v[130:133], v214 offset:20480
	ds_read_b128 v[216:219], v215 offset:16384
	ds_read_b128 v[220:223], v215 offset:20480
	v_add_u32_e32 v116, s17, v202
	v_add_u32_e32 v117, s17, v203
	ds_read_b64 v[100:101], v116 offset:32768
	ds_read_b64 v[102:103], v117 offset:32768
	ds_read_b64 v[96:97], v116 offset:36864
	ds_read_b64 v[98:99], v117 offset:36864
	ds_read_b64 v[92:93], v116 offset:40960
	ds_read_b64 v[94:95], v117 offset:40960
	ds_read_b64 v[88:89], v116 offset:45056
	ds_read_b64 v[90:91], v117 offset:45056
	ds_read_b64 v[84:85], v116 offset:49152
	ds_read_b64 v[86:87], v117 offset:49152
	ds_read_b64 v[80:81], v116 offset:53248
	ds_read_b64 v[82:83], v117 offset:53248
	ds_read_b64 v[140:141], v116 offset:57344
	ds_read_b64 v[142:143], v117 offset:57344
	ds_read_b64 v[136:137], v116 offset:61440
	ds_read_b64 v[138:139], v117 offset:61440
	s_waitcnt lgkmcnt(14)
	v_mfma_f32_16x16x32_bf16 v[104:107], v[104:107], v[0:3], v[244:247]
	s_waitcnt lgkmcnt(13)
	v_mfma_f32_16x16x32_bf16 v[116:119], v[112:115], v[4:7], v[104:107]
	v_mfma_f32_16x16x32_bf16 v[104:107], v[108:111], v[0:3], v[244:247]
	s_waitcnt lgkmcnt(12)
	v_mfma_f32_16x16x32_bf16 v[112:115], v[122:125], v[4:7], v[104:107]
	s_waitcnt lgkmcnt(11)
	v_mfma_f32_16x16x32_bf16 v[104:107], v[126:129], v[8:11], v[248:251]
	s_waitcnt lgkmcnt(9)
	v_mfma_f32_16x16x32_bf16 v[108:111], v[216:219], v[12:15], v[104:107]
	v_mfma_f32_16x16x32_bf16 v[104:107], v[130:133], v[8:11], v[248:251]
	s_waitcnt lgkmcnt(8)
	v_mfma_f32_16x16x32_bf16 v[104:107], v[220:223], v[12:15], v[104:107]
	v_max3_f32 v122, v116, v117, v118
	v_max3_f32 v122, v122, v119, v112
	v_max3_f32 v122, v122, v113, v114
	v_max_f32_e32 v122, v122, v115
	s_nop 0
	v_max3_f32 v123, v108, v109, v110
	s_nop 1
	v_max3_f32 v123, v123, v111, v104
	v_max3_f32 v123, v123, v105, v106
	v_max_f32_e32 v123, v123, v107
	v_cmp_gt_f32_e32 vcc, v122, v172
	v_cmp_gt_f32_e64 s[0:1], v123, v173
	s_or_b64 vcc, vcc, s[0:1]
	s_cbranch_vccz .LBB0_711
	v_sub_f32_e32 v122, v122, v244
	v_sub_f32_e32 v123, v123, v248
	v_sub_f32_e32 v172, v172, v244
	v_sub_f32_e32 v173, v173, v248
	ds_bpermute_b32 v124, v188, v122
	ds_bpermute_b32 v125, v188, v123
	v_max_f32_e32 v122, v122, v122
	v_max_f32_e32 v123, v123, v123
	s_waitcnt lgkmcnt(1)
	v_max_f32_e32 v124, v124, v124
	s_waitcnt lgkmcnt(0)
	v_max_f32_e32 v125, v125, v125
	v_max_f32_e32 v122, v122, v124
	v_max_f32_e32 v123, v123, v125
	ds_bpermute_b32 v124, v187, v122
	ds_bpermute_b32 v125, v187, v123
	s_waitcnt lgkmcnt(1)
	v_max_f32_e32 v124, v124, v124
	s_waitcnt lgkmcnt(0)
	v_max_f32_e32 v125, v125, v125
	v_max_f32_e32 v122, v122, v124
	v_max_f32_e32 v123, v123, v125
	v_add_f32_e32 v124, 0x41000000, v171
	v_cmp_gt_f32_e32 vcc, v123, v124
	s_nop 1
	v_cndmask_b32_e32 v171, v175, v123, vcc
	v_cmp_gt_f32_e32 vcc, v122, v172
	s_nop 1
	v_cndmask_b32_e32 v170, v174, v122, vcc
	v_pk_add_f32 v[122:123], v[174:175], v[170:171] neg_lo:[0,1] neg_hi:[0,1]
	v_pk_add_f32 v[172:173], v[170:171], s[8:9] op_sel_hi:[1,0]
	v_exp_f32_e32 v122, v122
	v_exp_f32_e32 v124, v123
	v_mov_b64_e32 v[174:175], v[170:171]
	v_mov_b32_e32 v125, v122
	v_pk_mul_f32 v[74:75], v[74:75], v[122:123] op_sel_hi:[1,0]
	v_pk_mul_f32 v[72:73], v[72:73], v[122:123] op_sel_hi:[1,0]
	v_pk_mul_f32 v[66:67], v[66:67], v[122:123] op_sel_hi:[1,0]
	v_pk_mul_f32 v[64:65], v[64:65], v[122:123] op_sel_hi:[1,0]
	v_pk_mul_f32 v[58:59], v[58:59], v[122:123] op_sel_hi:[1,0]
	v_pk_mul_f32 v[56:57], v[56:57], v[122:123] op_sel_hi:[1,0]
	v_pk_mul_f32 v[50:51], v[50:51], v[122:123] op_sel_hi:[1,0]
	v_pk_mul_f32 v[48:49], v[48:49], v[122:123] op_sel_hi:[1,0]
	v_pk_mul_f32 v[42:43], v[42:43], v[122:123] op_sel_hi:[1,0]
	v_pk_mul_f32 v[40:41], v[40:41], v[122:123] op_sel_hi:[1,0]
	v_pk_mul_f32 v[34:35], v[34:35], v[122:123] op_sel_hi:[1,0]
	v_pk_mul_f32 v[32:33], v[32:33], v[122:123] op_sel_hi:[1,0]
	v_pk_mul_f32 v[26:27], v[26:27], v[122:123] op_sel_hi:[1,0]
	v_pk_mul_f32 v[24:25], v[24:25], v[122:123] op_sel_hi:[1,0]
	v_pk_mul_f32 v[18:19], v[18:19], v[122:123] op_sel_hi:[1,0]
	v_pk_mul_f32 v[16:17], v[16:17], v[122:123] op_sel_hi:[1,0]
	v_pk_mul_f32 v[120:121], v[120:121], v[124:125]
	v_pk_mul_f32 v[78:79], v[78:79], v[124:125] op_sel_hi:[1,0]
	v_pk_mul_f32 v[76:77], v[76:77], v[124:125] op_sel_hi:[1,0]
	v_pk_mul_f32 v[70:71], v[70:71], v[124:125] op_sel_hi:[1,0]
	v_pk_mul_f32 v[68:69], v[68:69], v[124:125] op_sel_hi:[1,0]
	v_pk_mul_f32 v[62:63], v[62:63], v[124:125] op_sel_hi:[1,0]
	v_pk_mul_f32 v[60:61], v[60:61], v[124:125] op_sel_hi:[1,0]
	v_pk_mul_f32 v[54:55], v[54:55], v[124:125] op_sel_hi:[1,0]
	v_pk_mul_f32 v[52:53], v[52:53], v[124:125] op_sel_hi:[1,0]
	v_pk_mul_f32 v[46:47], v[46:47], v[124:125] op_sel_hi:[1,0]
	v_pk_mul_f32 v[44:45], v[44:45], v[124:125] op_sel_hi:[1,0]
	v_pk_mul_f32 v[38:39], v[38:39], v[124:125] op_sel_hi:[1,0]
	v_pk_mul_f32 v[36:37], v[36:37], v[124:125] op_sel_hi:[1,0]
	v_pk_mul_f32 v[30:31], v[30:31], v[124:125] op_sel_hi:[1,0]
	v_pk_mul_f32 v[28:29], v[28:29], v[124:125] op_sel_hi:[1,0]
	v_pk_mul_f32 v[22:23], v[22:23], v[124:125] op_sel_hi:[1,0]
	v_pk_mul_f32 v[20:21], v[20:21], v[124:125] op_sel_hi:[1,0]
	v_add_f32_e32 v242, v170, v244
	v_add_f32_e32 v243, v171, v248
	v_sub_f32_e32 v104, v104, v243
	v_sub_f32_e32 v105, v105, v243
	v_sub_f32_e32 v106, v106, v243
	v_sub_f32_e32 v107, v107, v243
	v_sub_f32_e32 v108, v108, v243
	v_sub_f32_e32 v109, v109, v243
	v_sub_f32_e32 v110, v110, v243
	v_sub_f32_e32 v111, v111, v243
	v_sub_f32_e32 v112, v112, v242
	v_sub_f32_e32 v113, v113, v242
	v_sub_f32_e32 v114, v114, v242
	v_sub_f32_e32 v115, v115, v242
	v_sub_f32_e32 v116, v116, v242
	v_sub_f32_e32 v117, v117, v242
	v_sub_f32_e32 v118, v118, v242
	v_sub_f32_e32 v119, v119, v242
	v_sub_f32_e32 v244, 0, v170
	v_sub_f32_e32 v245, 0, v170
	v_sub_f32_e32 v246, 0, v170
	v_sub_f32_e32 v247, 0, v170
	v_sub_f32_e32 v248, 0, v171
	v_sub_f32_e32 v249, 0, v171
	v_sub_f32_e32 v250, 0, v171
	v_sub_f32_e32 v251, 0, v171
	v_mov_b32_e32 v172, 0x41000000
	v_mov_b32_e32 v173, 0x41000000
.LBB0_711:
	v_exp_f32_e32 v123, v116
	v_exp_f32_e32 v117, v117
	v_exp_f32_e32 v127, v112
	v_exp_f32_e32 v125, v118
	v_exp_f32_e32 v113, v113
	v_exp_f32_e32 v122, v108
	v_exp_f32_e32 v119, v119
	v_exp_f32_e32 v129, v114
	v_exp_f32_e32 v116, v109
	v_exp_f32_e32 v126, v104
	v_exp_f32_e32 v115, v115
	v_exp_f32_e32 v124, v110
	v_exp_f32_e32 v112, v105
	v_exp_f32_e32 v118, v111
	v_exp_f32_e32 v128, v106
	v_exp_f32_e32 v114, v107
	v_pk_add_f32 v[104:105], v[122:123], 0 op_sel_hi:[1,0]
	v_cvt_pk_bf16_f32 v216, v123, v117
	v_pk_add_f32 v[104:105], v[116:117], v[104:105]
	v_cvt_pk_bf16_f32 v217, v125, v119
	v_pk_add_f32 v[104:105], v[124:125], v[104:105]
	v_cvt_pk_bf16_f32 v218, v127, v113
	v_pk_add_f32 v[104:105], v[118:119], v[104:105]
	v_cvt_pk_bf16_f32 v219, v129, v115
	v_pk_add_f32 v[104:105], v[126:127], v[104:105]
	v_cvt_pk_bf16_f32 v220, v122, v116
	v_pk_add_f32 v[104:105], v[112:113], v[104:105]
	v_cvt_pk_bf16_f32 v221, v124, v118
	v_pk_add_f32 v[104:105], v[128:129], v[104:105]
	v_cvt_pk_bf16_f32 v222, v126, v112
	v_pk_add_f32 v[104:105], v[114:115], v[104:105]
	v_cvt_pk_bf16_f32 v223, v128, v114
	v_pk_add_f32 v[176:177], v[120:121], v[104:105]
	s_setprio 1
	s_waitcnt lgkmcnt(0)
	s_nop 1
	v_mfma_f32_16x16x32_bf16 v[124:127], v[96:99], v[216:219], v[64:67]
	v_mfma_f32_16x16x32_bf16 v[108:111], v[88:91], v[216:219], v[48:51]
	v_mfma_f32_16x16x32_bf16 v[132:135], v[100:103], v[216:219], v[72:75]
	v_mfma_f32_16x16x32_bf16 v[128:131], v[100:103], v[220:223], v[76:79]
	v_mfma_f32_16x16x32_bf16 v[120:123], v[96:99], v[220:223], v[68:71]
	v_mfma_f32_16x16x32_bf16 v[116:119], v[92:95], v[216:219], v[56:59]
	v_mfma_f32_16x16x32_bf16 v[112:115], v[92:95], v[220:223], v[60:63]
	v_mfma_f32_16x16x32_bf16 v[92:95], v[80:83], v[216:219], v[32:35]
	v_mfma_f32_16x16x32_bf16 v[104:107], v[88:91], v[220:223], v[52:55]
	v_mfma_f32_16x16x32_bf16 v[100:103], v[84:87], v[216:219], v[40:43]
	v_mfma_f32_16x16x32_bf16 v[96:99], v[84:87], v[220:223], v[44:47]
	v_mfma_f32_16x16x32_bf16 v[88:91], v[80:83], v[220:223], v[36:39]
	v_mfma_f32_16x16x32_bf16 v[84:87], v[140:143], v[216:219], v[24:27]
	v_mfma_f32_16x16x32_bf16 v[80:83], v[140:143], v[220:223], v[28:31]
	v_mfma_f32_16x16x32_bf16 v[72:75], v[136:139], v[216:219], v[16:19]
	v_mfma_f32_16x16x32_bf16 v[76:79], v[136:139], v[220:223], v[20:23]
	s_setprio 0
	ds_read_b128 v[40:43], v149 offset:24576
	ds_read_b128 v[44:47], v149 offset:28672
	ds_read_b128 v[48:51], v151 offset:24576
	ds_read_b128 v[56:59], v151 offset:28672
	ds_read_b128 v[60:63], v214 offset:24576
	ds_read_b128 v[64:67], v214 offset:28672
	ds_read_b128 v[68:71], v215 offset:24576
	ds_read_b128 v[214:217], v215 offset:28672
	v_add_u32_e32 v52, s17, v204
	v_add_u32_e32 v53, s17, v205
	ds_read_b64 v[36:37], v52 offset:32768
	ds_read_b64 v[38:39], v53 offset:32768
	ds_read_b64 v[32:33], v52 offset:36864
	ds_read_b64 v[34:35], v53 offset:36864
	ds_read_b64 v[28:29], v52 offset:40960
	ds_read_b64 v[30:31], v53 offset:40960
	ds_read_b64 v[24:25], v52 offset:45056
	ds_read_b64 v[26:27], v53 offset:45056
	ds_read_b64 v[20:21], v52 offset:49152
	ds_read_b64 v[22:23], v53 offset:49152
	ds_read_b64 v[16:17], v52 offset:53248
	ds_read_b64 v[18:19], v53 offset:53248
	ds_read_b64 v[140:141], v52 offset:57344
	ds_read_b64 v[142:143], v53 offset:57344
	ds_read_b64 v[136:137], v52 offset:61440
	ds_read_b64 v[138:139], v53 offset:61440
	s_waitcnt lgkmcnt(14)
	v_mfma_f32_16x16x32_bf16 v[40:43], v[40:43], v[0:3], v[244:247]
	s_waitcnt lgkmcnt(13)
	v_mfma_f32_16x16x32_bf16 v[52:55], v[48:51], v[4:7], v[40:43]
	v_mfma_f32_16x16x32_bf16 v[40:43], v[44:47], v[0:3], v[244:247]
	s_waitcnt lgkmcnt(12)
	v_mfma_f32_16x16x32_bf16 v[48:51], v[56:59], v[4:7], v[40:43]
	s_waitcnt lgkmcnt(11)
	v_mfma_f32_16x16x32_bf16 v[40:43], v[60:63], v[8:11], v[248:251]
	s_waitcnt lgkmcnt(9)
	v_mfma_f32_16x16x32_bf16 v[44:47], v[68:71], v[12:15], v[40:43]
	v_mfma_f32_16x16x32_bf16 v[40:43], v[64:67], v[8:11], v[248:251]
	s_waitcnt lgkmcnt(8)
	v_mfma_f32_16x16x32_bf16 v[40:43], v[214:217], v[12:15], v[40:43]
	v_max3_f32 v56, v52, v53, v54
	v_max3_f32 v56, v56, v55, v48
	v_max3_f32 v56, v56, v49, v50
	v_max_f32_e32 v56, v56, v51
	s_nop 0
	v_max3_f32 v57, v44, v45, v46
	s_nop 1
	v_max3_f32 v57, v57, v47, v40
	v_max3_f32 v57, v57, v41, v42
	v_max_f32_e32 v57, v57, v43
	v_cmp_gt_f32_e32 vcc, v56, v172
	v_cmp_gt_f32_e64 s[0:1], v57, v173
	s_or_b64 vcc, vcc, s[0:1]
	s_cbranch_vccnz .LBB0_700
	v_mov_b32_e32 v57, v171
	v_mov_b32_e32 v56, v170
	v_mov_b64_e32 v[170:171], v[174:175]
	s_branch .LBB0_701

.LBB0_728:
	s_nop 0
	v_add_u32_e32 v140, s51, v152
	v_ashrrev_i32_e32 v141, 31, v140
	v_or_b32_e32 v144, s18, v151
	v_lshlrev_b64 v[142:143], 11, v[140:141]
	v_ashrrev_i32_e32 v145, 31, v144
	v_cvt_pk_bf16_f32 v124, v124, v125
	v_cvt_pk_bf16_f32 v125, v126, v127
	v_lshl_add_u64 v[126:127], s[68:69], 0, v[142:143]
	v_lshlrev_b64 v[142:143], 1, v[144:145]
	v_lshl_add_u64 v[126:127], v[126:127], 0, v[142:143]
	v_cvt_pk_bf16_f32 v112, v112, v113
	v_cvt_pk_bf16_f32 v113, v114, v115
	v_mov_b32_e32 v246, v112
	v_mov_b32_e32 v247, v113
	v_or_b32_e32 v112, 16, v140
	v_ashrrev_i32_e32 v113, 31, v112
	v_lshlrev_b64 v[112:113], 11, v[112:113]
	v_cvt_pk_bf16_f32 v108, v108, v109
	v_cvt_pk_bf16_f32 v109, v110, v111
	v_lshl_add_u64 v[110:111], s[68:69], 0, v[112:113]
	v_lshl_add_u64 v[110:111], v[110:111], 0, v[142:143]
	v_cvt_pk_bf16_f32 v96, v96, v97
	v_cvt_pk_bf16_f32 v97, v98, v99
	v_mov_b32_e32 v250, v96
	v_mov_b32_e32 v251, v97
	v_or_b32_e32 v96, 32, v140
	v_ashrrev_i32_e32 v97, 31, v96
	v_lshlrev_b64 v[96:97], 11, v[96:97]
	v_cvt_pk_bf16_f32 v92, v92, v93
	v_cvt_pk_bf16_f32 v93, v94, v95
	v_lshl_add_u64 v[94:95], s[68:69], 0, v[96:97]
	v_lshl_add_u64 v[94:95], v[94:95], 0, v[142:143]
	v_cvt_pk_bf16_f32 v80, v80, v81
	v_cvt_pk_bf16_f32 v81, v82, v83
	v_mov_b32_e32 v158, v80
	v_mov_b32_e32 v159, v81
	v_or_b32_e32 v80, 48, v140
	v_ashrrev_i32_e32 v81, 31, v80
	v_lshlrev_b64 v[80:81], 11, v[80:81]
	v_cvt_pk_bf16_f32 v76, v76, v77
	v_cvt_pk_bf16_f32 v77, v78, v79
	v_lshl_add_u64 v[78:79], s[68:69], 0, v[80:81]
	v_lshl_add_u64 v[78:79], v[78:79], 0, v[142:143]
	v_cvt_pk_bf16_f32 v64, v64, v65
	v_cvt_pk_bf16_f32 v65, v66, v67
	v_mov_b32_e32 v162, v64
	v_mov_b32_e32 v163, v65
	v_or_b32_e32 v64, 64, v140
	v_ashrrev_i32_e32 v65, 31, v64
	v_lshlrev_b64 v[64:65], 11, v[64:65]
	v_cvt_pk_bf16_f32 v60, v60, v61
	v_cvt_pk_bf16_f32 v61, v62, v63
	v_lshl_add_u64 v[62:63], s[68:69], 0, v[64:65]
	v_lshl_add_u64 v[62:63], v[62:63], 0, v[142:143]
	v_cvt_pk_bf16_f32 v48, v48, v49
	v_cvt_pk_bf16_f32 v49, v50, v51
	v_mov_b32_e32 v166, v48
	v_mov_b32_e32 v167, v49
	v_or_b32_e32 v48, 0x50, v140
	v_ashrrev_i32_e32 v49, 31, v48
	v_lshlrev_b64 v[48:49], 11, v[48:49]
	v_cvt_pk_bf16_f32 v44, v44, v45
	v_cvt_pk_bf16_f32 v45, v46, v47
	v_lshl_add_u64 v[46:47], s[68:69], 0, v[48:49]
	v_lshl_add_u64 v[46:47], v[46:47], 0, v[142:143]
	v_cvt_pk_bf16_f32 v32, v32, v33
	v_cvt_pk_bf16_f32 v33, v34, v35
	v_mov_b32_e32 v170, v32
	v_mov_b32_e32 v171, v33
	v_or_b32_e32 v32, 0x60, v140
	v_ashrrev_i32_e32 v33, 31, v32
	v_lshlrev_b64 v[32:33], 11, v[32:33]
	v_cvt_pk_bf16_f32 v28, v28, v29
	v_cvt_pk_bf16_f32 v29, v30, v31
	v_lshl_add_u64 v[30:31], s[68:69], 0, v[32:33]
	v_lshl_add_u64 v[30:31], v[30:31], 0, v[142:143]
	v_cvt_pk_bf16_f32 v16, v16, v17
	v_cvt_pk_bf16_f32 v17, v18, v19
	v_mov_b32_e32 v174, v16
	v_mov_b32_e32 v175, v17
	v_or_b32_e32 v16, 0x70, v140
	v_ashrrev_i32_e32 v17, 31, v16
	v_lshlrev_b64 v[16:17], 11, v[16:17]
	v_cvt_pk_bf16_f32 v12, v12, v13
	v_cvt_pk_bf16_f32 v13, v14, v15
	v_lshl_add_u64 v[14:15], s[68:69], 0, v[16:17]
	v_lshl_add_u64 v[14:15], v[14:15], 0, v[142:143]
	v_cvt_pk_bf16_f32 v4, v4, v5
	v_cvt_pk_bf16_f32 v5, v6, v7
	v_cvt_pk_bf16_f32 v120, v120, v121
	v_cvt_pk_bf16_f32 v121, v122, v123
	v_cvt_pk_bf16_f32 v116, v116, v117
	v_cvt_pk_bf16_f32 v117, v118, v119
	v_cvt_pk_bf16_f32 v104, v104, v105
	v_cvt_pk_bf16_f32 v105, v106, v107
	v_cvt_pk_bf16_f32 v100, v100, v101
	v_cvt_pk_bf16_f32 v101, v102, v103
	v_cvt_pk_bf16_f32 v88, v88, v89
	v_cvt_pk_bf16_f32 v89, v90, v91
	v_cvt_pk_bf16_f32 v84, v84, v85
	v_cvt_pk_bf16_f32 v85, v86, v87
	v_cvt_pk_bf16_f32 v72, v72, v73
	v_cvt_pk_bf16_f32 v73, v74, v75
	v_cvt_pk_bf16_f32 v68, v68, v69
	v_cvt_pk_bf16_f32 v69, v70, v71
	v_cvt_pk_bf16_f32 v56, v56, v57
	v_cvt_pk_bf16_f32 v57, v58, v59
	v_cvt_pk_bf16_f32 v52, v52, v53
	v_cvt_pk_bf16_f32 v53, v54, v55
	v_cvt_pk_bf16_f32 v40, v40, v41
	v_cvt_pk_bf16_f32 v41, v42, v43
	v_cvt_pk_bf16_f32 v36, v36, v37
	v_cvt_pk_bf16_f32 v37, v38, v39
	v_cvt_pk_bf16_f32 v24, v24, v25
	v_cvt_pk_bf16_f32 v25, v26, v27
	v_cvt_pk_bf16_f32 v20, v20, v21
	v_cvt_pk_bf16_f32 v21, v22, v23
	global_store_dwordx2 v[14:15], v[4:5], off offset:32
	v_cvt_pk_bf16_f32 v4, v8, v9
	v_cvt_pk_bf16_f32 v5, v10, v11
	v_cvt_pk_bf16_f32 v0, v0, v1
	v_cvt_pk_bf16_f32 v1, v2, v3
	s_mov_b64 s[26:27], -1
	s_and_b64 vcc, exec, s[16:17]
	global_store_dwordx2 v[126:127], v[124:125], off
	global_store_dwordx2 v[126:127], v[120:121], off offset:32
	v_and_b32_e32 v242, 16, v178
	v_lshrrev_b32_e32 v243, 1, v242
	v_add_u32_e32 v242, v242, v243
	v_mov_b32_e32 v243, 0
	v_mov_b32_e32 v244, v116
	v_mov_b32_e32 v245, v117
	v_lshl_add_u64 v[252:253], v[126:127], 0, v[242:243]
	s_nop 0
	v_permlane16_swap_b32_e32 v244, v246
	v_permlane16_swap_b32_e32 v245, v247
	global_store_dwordx4 v[252:253], v[244:247], off offset:64
	s_nop 1
	v_mov_b32_e32 v244, v108
	v_mov_b32_e32 v245, v109
	v_mov_b32_e32 v246, v104
	v_mov_b32_e32 v247, v105
	v_lshl_add_u64 v[254:255], v[110:111], 0, v[242:243]
	s_nop 0
	v_permlane16_swap_b32_e32 v244, v246
	v_permlane16_swap_b32_e32 v245, v247
	global_store_dwordx4 v[254:255], v[244:247], off
	v_mov_b32_e32 v248, v100
	v_mov_b32_e32 v249, v101
	v_lshl_add_u64 v[252:253], v[110:111], 0, v[242:243]
	s_nop 0
	v_permlane16_swap_b32_e32 v248, v250
	v_permlane16_swap_b32_e32 v249, v251
	global_store_dwordx4 v[252:253], v[248:251], off offset:64
	s_nop 1
	v_mov_b32_e32 v248, v92
	v_mov_b32_e32 v249, v93
	v_mov_b32_e32 v250, v88
	v_mov_b32_e32 v251, v89
	v_lshl_add_u64 v[254:255], v[94:95], 0, v[242:243]
	s_nop 0
	v_permlane16_swap_b32_e32 v248, v250
	v_permlane16_swap_b32_e32 v249, v251
	global_store_dwordx4 v[254:255], v[248:251], off
	v_mov_b32_e32 v156, v84
	v_mov_b32_e32 v157, v85
	v_lshl_add_u64 v[252:253], v[94:95], 0, v[242:243]
	s_nop 0
	v_permlane16_swap_b32_e32 v156, v158
	v_permlane16_swap_b32_e32 v157, v159
	global_store_dwordx4 v[252:253], v[156:159], off offset:64
	s_nop 1
	v_mov_b32_e32 v244, v76
	v_mov_b32_e32 v245, v77
	v_mov_b32_e32 v246, v72
	v_mov_b32_e32 v247, v73
	v_lshl_add_u64 v[254:255], v[78:79], 0, v[242:243]
	s_nop 0
	v_permlane16_swap_b32_e32 v244, v246
	v_permlane16_swap_b32_e32 v245, v247
	global_store_dwordx4 v[254:255], v[244:247], off
	v_mov_b32_e32 v160, v68
	v_mov_b32_e32 v161, v69
	v_lshl_add_u64 v[252:253], v[78:79], 0, v[242:243]
	s_nop 0
	v_permlane16_swap_b32_e32 v160, v162
	v_permlane16_swap_b32_e32 v161, v163
	global_store_dwordx4 v[252:253], v[160:163], off offset:64
	s_nop 1
	v_mov_b32_e32 v156, v60
	v_mov_b32_e32 v157, v61
	v_mov_b32_e32 v158, v56
	v_mov_b32_e32 v159, v57
	v_lshl_add_u64 v[254:255], v[62:63], 0, v[242:243]
	s_nop 0
	v_permlane16_swap_b32_e32 v156, v158
	v_permlane16_swap_b32_e32 v157, v159
	global_store_dwordx4 v[254:255], v[156:159], off
	v_mov_b32_e32 v164, v52
	v_mov_b32_e32 v165, v53
	v_lshl_add_u64 v[252:253], v[62:63], 0, v[242:243]
	s_nop 0
	v_permlane16_swap_b32_e32 v164, v166
	v_permlane16_swap_b32_e32 v165, v167
	global_store_dwordx4 v[252:253], v[164:167], off offset:64
	v_mov_b32_e32 v248, v44
	v_mov_b32_e32 v249, v45
	v_mov_b32_e32 v250, v40
	v_mov_b32_e32 v251, v41
	v_lshl_add_u64 v[254:255], v[46:47], 0, v[242:243]
	s_nop 0
	v_permlane16_swap_b32_e32 v248, v250
	v_permlane16_swap_b32_e32 v249, v251
	global_store_dwordx4 v[254:255], v[248:251], off
	v_mov_b32_e32 v168, v36
	v_mov_b32_e32 v169, v37
	v_lshl_add_u64 v[252:253], v[46:47], 0, v[242:243]
	s_nop 0
	v_permlane16_swap_b32_e32 v168, v170
	v_permlane16_swap_b32_e32 v169, v171
	global_store_dwordx4 v[252:253], v[168:171], off offset:64
	v_mov_b32_e32 v160, v28
	v_mov_b32_e32 v161, v29
	v_mov_b32_e32 v162, v24
	v_mov_b32_e32 v163, v25
	v_lshl_add_u64 v[254:255], v[30:31], 0, v[242:243]
	s_nop 0
	v_permlane16_swap_b32_e32 v160, v162
	v_permlane16_swap_b32_e32 v161, v163
	global_store_dwordx4 v[254:255], v[160:163], off
	v_mov_b32_e32 v172, v20
	v_mov_b32_e32 v173, v21
	v_lshl_add_u64 v[252:253], v[30:31], 0, v[242:243]
	s_nop 0
	v_permlane16_swap_b32_e32 v172, v174
	v_permlane16_swap_b32_e32 v173, v175
	global_store_dwordx4 v[252:253], v[172:175], off offset:64
	global_store_dwordx2 v[14:15], v[12:13], off
	v_mov_b32_e32 v244, v4
	v_mov_b32_e32 v245, v5
	v_mov_b32_e32 v246, v0
	v_mov_b32_e32 v247, v1
	v_lshl_add_u64 v[254:255], v[14:15], 0, v[242:243]
	s_nop 0
	v_permlane16_swap_b32_e32 v244, v246
	v_permlane16_swap_b32_e32 v245, v247
	global_store_dwordx4 v[254:255], v[244:247], off offset:64
	s_cbranch_vccnz .LBB0_739

.LBB0_1128:
	v_mul_f32_e32 v139, 0xbfb8aa3b, v124
	v_exp_f32_e32 v142, v139
	v_mul_f32_e32 v139, 0xbfb8aa3b, v125
	v_exp_f32_e32 v143, v139
	v_add_u32_e32 v140, s63, v152
	v_ashrrev_i32_e32 v141, 31, v140
	v_lshlrev_b64 v[144:145], 12, v[140:141]
	v_pk_add_f32 v[142:143], v[142:143], 1.0 op_sel_hi:[1,0]
	v_or_b32_e32 v146, s28, v151
	s_mov_b64 s[38:39], -1
	v_mul_f32_e32 v147, 0xbfb8aa3b, v126
	v_exp_f32_e32 v154, v147
	v_mul_f32_e32 v147, 0xbfb8aa3b, v127
	v_rcp_f32_e32 v139, v143
	s_nop 0
	v_mul_f32_e32 v125, v125, v139
	v_exp_f32_e32 v155, v147
	s_nop 0
	v_pk_add_f32 v[154:155], v[154:155], 1.0 op_sel_hi:[1,0]
	v_rcp_f32_e32 v139, v142
	s_nop 0
	v_mul_f32_e32 v124, v124, v139
	v_cvt_pk_bf16_f32 v142, v124, v125
	v_rcp_f32_e32 v124, v155
	s_nop 0
	v_mul_f32_e32 v127, v127, v124
	v_ashrrev_i32_e32 v147, 31, v146
	v_rcp_f32_e32 v124, v154
	s_nop 0
	v_mul_f32_e32 v126, v126, v124
	v_mul_f32_e32 v124, 0xbfb8aa3b, v120
	v_mul_f32_e32 v125, 0xbfb8aa3b, v121
	v_exp_f32_e32 v124, v124
	v_exp_f32_e32 v125, v125
	v_cvt_pk_bf16_f32 v143, v126, v127
	v_lshl_add_u64 v[126:127], s[68:69], 0, v[144:145]
	v_pk_add_f32 v[144:145], v[124:125], 1.0 op_sel_hi:[1,0]
	s_nop 0
	v_lshlrev_b64 v[124:125], 1, v[146:147]
	v_lshl_add_u64 v[126:127], v[126:127], 0, v[124:125]
	v_mov_b32_e32 v244, v142
	v_mov_b32_e32 v245, v143
	v_mul_f32_e32 v142, 0xbfb8aa3b, v122
	v_mul_f32_e32 v143, 0xbfb8aa3b, v123
	v_exp_f32_e32 v142, v142
	v_exp_f32_e32 v143, v143
	v_rcp_f32_e32 v139, v145
	s_nop 0
	v_mul_f32_e32 v121, v121, v139
	v_pk_add_f32 v[142:143], v[142:143], 1.0 op_sel_hi:[1,0]
	v_rcp_f32_e32 v139, v144
	s_nop 0
	v_mul_f32_e32 v120, v120, v139
	v_cvt_pk_bf16_f32 v120, v120, v121
	v_rcp_f32_e32 v121, v143
	s_nop 0
	v_mul_f32_e32 v121, v123, v121
	v_mul_f32_e32 v143, 0xbfb8aa3b, v116
	v_exp_f32_e32 v144, v143
	v_mul_f32_e32 v143, 0xbfb8aa3b, v117
	v_exp_f32_e32 v145, v143
	v_rcp_f32_e32 v123, v142
	s_nop 0
	v_mul_f32_e32 v122, v122, v123
	v_pk_add_f32 v[144:145], v[144:145], 1.0 op_sel_hi:[1,0]
	v_cvt_pk_bf16_f32 v121, v122, v121
	v_and_b32_e32 v242, 16, v178
	v_lshrrev_b32_e32 v243, 1, v242
	v_add_u32_e32 v242, v242, v243
	v_mov_b32_e32 v243, 0
	v_mov_b32_e32 v246, v120
	v_mov_b32_e32 v247, v121
	v_lshl_add_u64 v[252:253], v[126:127], 0, v[242:243]
	s_nop 0
	v_permlane16_swap_b32_e32 v244, v246
	v_permlane16_swap_b32_e32 v245, v247
	global_store_dwordx4 v[252:253], v[244:247], off
	v_rcp_f32_e32 v120, v145
	s_nop 0
	v_mul_f32_e32 v117, v117, v120
	v_mul_f32_e32 v120, 0xbfb8aa3b, v118
	v_mul_f32_e32 v121, 0xbfb8aa3b, v119
	v_exp_f32_e32 v120, v120
	v_exp_f32_e32 v121, v121
	s_nop 0
	v_pk_add_f32 v[120:121], v[120:121], 1.0 op_sel_hi:[1,0]
	v_rcp_f32_e32 v122, v144
	s_nop 0
	v_mul_f32_e32 v116, v116, v122
	v_cvt_pk_bf16_f32 v116, v116, v117
	v_rcp_f32_e32 v117, v121
	s_nop 0
	v_mul_f32_e32 v117, v119, v117
	v_mul_f32_e32 v123, 0xbfb8aa3b, v113
	v_mul_f32_e32 v122, 0xbfb8aa3b, v112
	v_exp_f32_e32 v122, v122
	v_exp_f32_e32 v123, v123
	v_rcp_f32_e32 v119, v120
	s_nop 0
	v_mul_f32_e32 v118, v118, v119
	v_pk_add_f32 v[122:123], v[122:123], 1.0 op_sel_hi:[1,0]
	v_cvt_pk_bf16_f32 v117, v118, v117
	v_mov_b32_e32 v248, v116
	v_mov_b32_e32 v249, v117
	v_rcp_f32_e32 v116, v123
	s_nop 0
	v_mul_f32_e32 v113, v113, v116
	v_mul_f32_e32 v116, 0xbfb8aa3b, v114
	v_mul_f32_e32 v117, 0xbfb8aa3b, v115
	v_exp_f32_e32 v116, v116
	v_exp_f32_e32 v117, v117
	s_nop 0
	v_pk_add_f32 v[116:117], v[116:117], 1.0 op_sel_hi:[1,0]
	v_rcp_f32_e32 v118, v122
	s_nop 0
	v_mul_f32_e32 v112, v112, v118
	v_cvt_pk_bf16_f32 v112, v112, v113
	v_rcp_f32_e32 v113, v117
	s_nop 0
	v_mul_f32_e32 v113, v115, v113
	v_mul_f32_e32 v117, 0xbfb8aa3b, v108
	v_exp_f32_e32 v118, v117
	v_mul_f32_e32 v117, 0xbfb8aa3b, v109
	v_exp_f32_e32 v119, v117
	v_rcp_f32_e32 v115, v116
	s_nop 0
	v_mul_f32_e32 v114, v114, v115
	v_cvt_pk_bf16_f32 v113, v114, v113
	v_mov_b32_e32 v250, v112
	v_mov_b32_e32 v251, v113
	v_lshl_add_u64 v[254:255], v[126:127], 0, v[242:243]
	s_nop 0
	v_permlane16_swap_b32_e32 v248, v250
	v_permlane16_swap_b32_e32 v249, v251
	global_store_dwordx4 v[254:255], v[248:251], off offset:64
	v_pk_add_f32 v[112:113], v[118:119], 1.0 op_sel_hi:[1,0]
	v_or_b32_e32 v114, 16, v140
	v_ashrrev_i32_e32 v115, 31, v114
	v_lshlrev_b64 v[114:115], 12, v[114:115]
	v_rcp_f32_e32 v116, v113
	s_nop 0
	v_mul_f32_e32 v109, v109, v116
	v_mul_f32_e32 v116, 0xbfb8aa3b, v110
	v_mul_f32_e32 v117, 0xbfb8aa3b, v111
	v_exp_f32_e32 v116, v116
	v_exp_f32_e32 v117, v117
	s_nop 0
	v_pk_add_f32 v[116:117], v[116:117], 1.0 op_sel_hi:[1,0]
	v_rcp_f32_e32 v113, v112
	s_nop 0
	v_mul_f32_e32 v108, v108, v113
	v_cvt_pk_bf16_f32 v112, v108, v109
	v_rcp_f32_e32 v108, v117
	s_nop 0
	v_mul_f32_e32 v111, v111, v108
	v_mul_f32_e32 v108, 0xbfb8aa3b, v104
	v_mul_f32_e32 v109, 0xbfb8aa3b, v105
	v_exp_f32_e32 v108, v108
	v_exp_f32_e32 v109, v109
	v_rcp_f32_e32 v113, v116
	s_nop 0
	v_mul_f32_e32 v110, v110, v113
	v_cvt_pk_bf16_f32 v113, v110, v111
	v_pk_add_f32 v[110:111], v[108:109], 1.0 op_sel_hi:[1,0]
	v_lshl_add_u64 v[108:109], s[68:69], 0, v[114:115]
	v_lshl_add_u64 v[108:109], v[108:109], 0, v[124:125]
	v_mov_b32_e32 v156, v112
	v_mov_b32_e32 v157, v113
	v_rcp_f32_e32 v112, v111
	s_nop 0
	v_mul_f32_e32 v105, v105, v112
	v_mul_f32_e32 v112, 0xbfb8aa3b, v106
	v_mul_f32_e32 v113, 0xbfb8aa3b, v107
	v_exp_f32_e32 v112, v112
	v_exp_f32_e32 v113, v113
	s_nop 0
	v_pk_add_f32 v[112:113], v[112:113], 1.0 op_sel_hi:[1,0]
	v_rcp_f32_e32 v111, v110
	s_nop 0
	v_mul_f32_e32 v104, v104, v111
	v_cvt_pk_bf16_f32 v104, v104, v105
	v_rcp_f32_e32 v105, v113
	s_nop 0
	v_mul_f32_e32 v105, v107, v105
	v_mul_f32_e32 v111, 0xbfb8aa3b, v101
	v_mul_f32_e32 v110, 0xbfb8aa3b, v100
	v_exp_f32_e32 v110, v110
	v_exp_f32_e32 v111, v111
	v_rcp_f32_e32 v107, v112
	s_nop 0
	v_mul_f32_e32 v106, v106, v107
	v_pk_add_f32 v[110:111], v[110:111], 1.0 op_sel_hi:[1,0]
	v_cvt_pk_bf16_f32 v105, v106, v105
	v_mov_b32_e32 v158, v104
	v_mov_b32_e32 v159, v105
	v_lshl_add_u64 v[252:253], v[108:109], 0, v[242:243]
	s_nop 0
	v_permlane16_swap_b32_e32 v156, v158
	v_permlane16_swap_b32_e32 v157, v159
	global_store_dwordx4 v[252:253], v[156:159], off
	v_rcp_f32_e32 v104, v111
	s_nop 0
	v_mul_f32_e32 v101, v101, v104
	v_mul_f32_e32 v104, 0xbfb8aa3b, v102
	v_mul_f32_e32 v105, 0xbfb8aa3b, v103
	v_exp_f32_e32 v104, v104
	v_exp_f32_e32 v105, v105
	s_nop 0
	v_pk_add_f32 v[104:105], v[104:105], 1.0 op_sel_hi:[1,0]
	v_rcp_f32_e32 v106, v110
	s_nop 0
	v_mul_f32_e32 v100, v100, v106
	v_cvt_pk_bf16_f32 v100, v100, v101
	v_rcp_f32_e32 v101, v105
	s_nop 0
	v_mul_f32_e32 v101, v103, v101
	v_mul_f32_e32 v107, 0xbfb8aa3b, v97
	v_mul_f32_e32 v106, 0xbfb8aa3b, v96
	v_exp_f32_e32 v106, v106
	v_exp_f32_e32 v107, v107
	v_rcp_f32_e32 v103, v104
	s_nop 0
	v_mul_f32_e32 v102, v102, v103
	v_pk_add_f32 v[106:107], v[106:107], 1.0 op_sel_hi:[1,0]
	v_cvt_pk_bf16_f32 v101, v102, v101
	v_mov_b32_e32 v160, v100
	v_mov_b32_e32 v161, v101
	v_rcp_f32_e32 v100, v107
	s_nop 0
	v_mul_f32_e32 v97, v97, v100
	v_mul_f32_e32 v100, 0xbfb8aa3b, v98
	v_mul_f32_e32 v101, 0xbfb8aa3b, v99
	v_exp_f32_e32 v100, v100
	v_exp_f32_e32 v101, v101
	s_nop 0
	v_pk_add_f32 v[100:101], v[100:101], 1.0 op_sel_hi:[1,0]
	v_rcp_f32_e32 v102, v106
	s_nop 0
	v_mul_f32_e32 v96, v96, v102
	v_cvt_pk_bf16_f32 v96, v96, v97
	v_rcp_f32_e32 v97, v101
	s_nop 0
	v_mul_f32_e32 v97, v99, v97
	v_mul_f32_e32 v101, 0xbfb8aa3b, v92
	v_exp_f32_e32 v102, v101
	v_mul_f32_e32 v101, 0xbfb8aa3b, v93
	v_exp_f32_e32 v103, v101
	v_rcp_f32_e32 v99, v100
	s_nop 0
	v_mul_f32_e32 v98, v98, v99
	v_cvt_pk_bf16_f32 v97, v98, v97
	v_mov_b32_e32 v162, v96
	v_mov_b32_e32 v163, v97
	v_lshl_add_u64 v[254:255], v[108:109], 0, v[242:243]
	s_nop 0
	v_permlane16_swap_b32_e32 v160, v162
	v_permlane16_swap_b32_e32 v161, v163
	global_store_dwordx4 v[254:255], v[160:163], off offset:64
	v_pk_add_f32 v[96:97], v[102:103], 1.0 op_sel_hi:[1,0]
	v_or_b32_e32 v98, 32, v140
	v_ashrrev_i32_e32 v99, 31, v98
	v_lshlrev_b64 v[98:99], 12, v[98:99]
	v_rcp_f32_e32 v100, v97
	s_nop 0
	v_mul_f32_e32 v93, v93, v100
	v_mul_f32_e32 v100, 0xbfb8aa3b, v94
	v_mul_f32_e32 v101, 0xbfb8aa3b, v95
	v_exp_f32_e32 v100, v100
	v_exp_f32_e32 v101, v101
	s_nop 0
	v_pk_add_f32 v[100:101], v[100:101], 1.0 op_sel_hi:[1,0]
	v_rcp_f32_e32 v97, v96
	s_nop 0
	v_mul_f32_e32 v92, v92, v97
	v_cvt_pk_bf16_f32 v96, v92, v93
	v_rcp_f32_e32 v92, v101
	s_nop 0
	v_mul_f32_e32 v95, v95, v92
	v_mul_f32_e32 v92, 0xbfb8aa3b, v88
	v_mul_f32_e32 v93, 0xbfb8aa3b, v89
	v_exp_f32_e32 v92, v92
	v_exp_f32_e32 v93, v93
	v_rcp_f32_e32 v97, v100
	s_nop 0
	v_mul_f32_e32 v94, v94, v97
	v_cvt_pk_bf16_f32 v97, v94, v95
	v_pk_add_f32 v[94:95], v[92:93], 1.0 op_sel_hi:[1,0]
	v_lshl_add_u64 v[92:93], s[68:69], 0, v[98:99]
	v_lshl_add_u64 v[92:93], v[92:93], 0, v[124:125]
	v_mov_b32_e32 v164, v96
	v_mov_b32_e32 v165, v97
	v_rcp_f32_e32 v96, v95
	s_nop 0
	v_mul_f32_e32 v89, v89, v96
	v_mul_f32_e32 v96, 0xbfb8aa3b, v90
	v_mul_f32_e32 v97, 0xbfb8aa3b, v91
	v_exp_f32_e32 v96, v96
	v_exp_f32_e32 v97, v97
	s_nop 0
	v_pk_add_f32 v[96:97], v[96:97], 1.0 op_sel_hi:[1,0]
	v_rcp_f32_e32 v95, v94
	s_nop 0
	v_mul_f32_e32 v88, v88, v95
	v_cvt_pk_bf16_f32 v88, v88, v89
	v_rcp_f32_e32 v89, v97
	s_nop 0
	v_mul_f32_e32 v89, v91, v89
	v_mul_f32_e32 v95, 0xbfb8aa3b, v85
	v_mul_f32_e32 v94, 0xbfb8aa3b, v84
	v_exp_f32_e32 v94, v94
	v_exp_f32_e32 v95, v95
	v_rcp_f32_e32 v91, v96
	s_nop 0
	v_mul_f32_e32 v90, v90, v91
	v_pk_add_f32 v[94:95], v[94:95], 1.0 op_sel_hi:[1,0]
	v_cvt_pk_bf16_f32 v89, v90, v89
	v_mov_b32_e32 v166, v88
	v_mov_b32_e32 v167, v89
	v_lshl_add_u64 v[252:253], v[92:93], 0, v[242:243]
	s_nop 0
	v_permlane16_swap_b32_e32 v164, v166
	v_permlane16_swap_b32_e32 v165, v167
	global_store_dwordx4 v[252:253], v[164:167], off
	v_rcp_f32_e32 v88, v95
	s_nop 0
	v_mul_f32_e32 v85, v85, v88
	v_mul_f32_e32 v88, 0xbfb8aa3b, v86
	v_mul_f32_e32 v89, 0xbfb8aa3b, v87
	v_exp_f32_e32 v88, v88
	v_exp_f32_e32 v89, v89
	s_nop 0
	v_pk_add_f32 v[88:89], v[88:89], 1.0 op_sel_hi:[1,0]
	v_rcp_f32_e32 v90, v94
	s_nop 0
	v_mul_f32_e32 v84, v84, v90
	v_cvt_pk_bf16_f32 v84, v84, v85
	v_rcp_f32_e32 v85, v89
	s_nop 0
	v_mul_f32_e32 v85, v87, v85
	v_mul_f32_e32 v91, 0xbfb8aa3b, v81
	v_mul_f32_e32 v90, 0xbfb8aa3b, v80
	v_exp_f32_e32 v90, v90
	v_exp_f32_e32 v91, v91
	v_rcp_f32_e32 v87, v88
	s_nop 0
	v_mul_f32_e32 v86, v86, v87
	v_pk_add_f32 v[90:91], v[90:91], 1.0 op_sel_hi:[1,0]
	v_cvt_pk_bf16_f32 v85, v86, v85
	v_mov_b32_e32 v168, v84
	v_mov_b32_e32 v169, v85
	v_rcp_f32_e32 v84, v91
	s_nop 0
	v_mul_f32_e32 v81, v81, v84
	v_mul_f32_e32 v84, 0xbfb8aa3b, v82
	v_mul_f32_e32 v85, 0xbfb8aa3b, v83
	v_exp_f32_e32 v84, v84
	v_exp_f32_e32 v85, v85
	s_nop 0
	v_pk_add_f32 v[84:85], v[84:85], 1.0 op_sel_hi:[1,0]
	v_rcp_f32_e32 v86, v90
	s_nop 0
	v_mul_f32_e32 v80, v80, v86
	v_cvt_pk_bf16_f32 v80, v80, v81
	v_rcp_f32_e32 v81, v85
	s_nop 0
	v_mul_f32_e32 v81, v83, v81
	v_mul_f32_e32 v85, 0xbfb8aa3b, v76
	v_exp_f32_e32 v86, v85
	v_mul_f32_e32 v85, 0xbfb8aa3b, v77
	v_exp_f32_e32 v87, v85
	v_rcp_f32_e32 v83, v84
	s_nop 0
	v_mul_f32_e32 v82, v82, v83
	v_cvt_pk_bf16_f32 v81, v82, v81
	v_mov_b32_e32 v170, v80
	v_mov_b32_e32 v171, v81
	v_lshl_add_u64 v[254:255], v[92:93], 0, v[242:243]
	s_nop 0
	v_permlane16_swap_b32_e32 v168, v170
	v_permlane16_swap_b32_e32 v169, v171
	global_store_dwordx4 v[254:255], v[168:171], off offset:64
	v_pk_add_f32 v[80:81], v[86:87], 1.0 op_sel_hi:[1,0]
	v_or_b32_e32 v82, 48, v140
	v_ashrrev_i32_e32 v83, 31, v82
	v_lshlrev_b64 v[82:83], 12, v[82:83]
	v_rcp_f32_e32 v84, v81
	s_nop 0
	v_mul_f32_e32 v77, v77, v84
	v_mul_f32_e32 v84, 0xbfb8aa3b, v78
	v_mul_f32_e32 v85, 0xbfb8aa3b, v79
	v_exp_f32_e32 v84, v84
	v_exp_f32_e32 v85, v85
	s_nop 0
	v_pk_add_f32 v[84:85], v[84:85], 1.0 op_sel_hi:[1,0]
	v_rcp_f32_e32 v81, v80
	s_nop 0
	v_mul_f32_e32 v76, v76, v81
	v_cvt_pk_bf16_f32 v80, v76, v77
	v_rcp_f32_e32 v76, v85
	s_nop 0
	v_mul_f32_e32 v79, v79, v76
	v_mul_f32_e32 v76, 0xbfb8aa3b, v72
	v_mul_f32_e32 v77, 0xbfb8aa3b, v73
	v_exp_f32_e32 v76, v76
	v_exp_f32_e32 v77, v77
	v_rcp_f32_e32 v81, v84
	s_nop 0
	v_mul_f32_e32 v78, v78, v81
	v_cvt_pk_bf16_f32 v81, v78, v79
	v_pk_add_f32 v[78:79], v[76:77], 1.0 op_sel_hi:[1,0]
	v_lshl_add_u64 v[76:77], s[68:69], 0, v[82:83]
	v_lshl_add_u64 v[76:77], v[76:77], 0, v[124:125]
	v_mov_b32_e32 v172, v80
	v_mov_b32_e32 v173, v81
	v_rcp_f32_e32 v80, v79
	s_nop 0
	v_mul_f32_e32 v73, v73, v80
	v_mul_f32_e32 v80, 0xbfb8aa3b, v74
	v_mul_f32_e32 v81, 0xbfb8aa3b, v75
	v_exp_f32_e32 v80, v80
	v_exp_f32_e32 v81, v81
	s_nop 0
	v_pk_add_f32 v[80:81], v[80:81], 1.0 op_sel_hi:[1,0]
	v_rcp_f32_e32 v79, v78
	s_nop 0
	v_mul_f32_e32 v72, v72, v79
	v_cvt_pk_bf16_f32 v72, v72, v73
	v_rcp_f32_e32 v73, v81
	s_nop 0
	v_mul_f32_e32 v73, v75, v73
	v_mul_f32_e32 v79, 0xbfb8aa3b, v69
	v_mul_f32_e32 v78, 0xbfb8aa3b, v68
	v_exp_f32_e32 v78, v78
	v_exp_f32_e32 v79, v79
	v_rcp_f32_e32 v75, v80
	s_nop 0
	v_mul_f32_e32 v74, v74, v75
	v_pk_add_f32 v[78:79], v[78:79], 1.0 op_sel_hi:[1,0]
	v_cvt_pk_bf16_f32 v73, v74, v73
	v_mov_b32_e32 v174, v72
	v_mov_b32_e32 v175, v73
	v_lshl_add_u64 v[252:253], v[76:77], 0, v[242:243]
	s_nop 0
	v_permlane16_swap_b32_e32 v172, v174
	v_permlane16_swap_b32_e32 v173, v175
	global_store_dwordx4 v[252:253], v[172:175], off
	v_rcp_f32_e32 v72, v79
	s_nop 0
	v_mul_f32_e32 v69, v69, v72
	v_mul_f32_e32 v72, 0xbfb8aa3b, v70
	v_mul_f32_e32 v73, 0xbfb8aa3b, v71
	v_exp_f32_e32 v72, v72
	v_exp_f32_e32 v73, v73
	s_nop 0
	v_pk_add_f32 v[72:73], v[72:73], 1.0 op_sel_hi:[1,0]
	v_rcp_f32_e32 v74, v78
	s_nop 0
	v_mul_f32_e32 v68, v68, v74
	v_cvt_pk_bf16_f32 v68, v68, v69
	v_rcp_f32_e32 v69, v73
	s_nop 0
	v_mul_f32_e32 v69, v71, v69
	v_mul_f32_e32 v75, 0xbfb8aa3b, v65
	v_mul_f32_e32 v74, 0xbfb8aa3b, v64
	v_exp_f32_e32 v74, v74
	v_exp_f32_e32 v75, v75
	v_rcp_f32_e32 v71, v72
	s_nop 0
	v_mul_f32_e32 v70, v70, v71
	v_pk_add_f32 v[74:75], v[74:75], 1.0 op_sel_hi:[1,0]
	v_cvt_pk_bf16_f32 v69, v70, v69
	v_mov_b32_e32 v244, v68
	v_mov_b32_e32 v245, v69
	v_rcp_f32_e32 v68, v75
	s_nop 0
	v_mul_f32_e32 v65, v65, v68
	v_mul_f32_e32 v68, 0xbfb8aa3b, v66
	v_mul_f32_e32 v69, 0xbfb8aa3b, v67
	v_exp_f32_e32 v68, v68
	v_exp_f32_e32 v69, v69
	s_nop 0
	v_pk_add_f32 v[68:69], v[68:69], 1.0 op_sel_hi:[1,0]
	v_rcp_f32_e32 v70, v74
	s_nop 0
	v_mul_f32_e32 v64, v64, v70
	v_cvt_pk_bf16_f32 v64, v64, v65
	v_rcp_f32_e32 v65, v69
	s_nop 0
	v_mul_f32_e32 v65, v67, v65
	v_mul_f32_e32 v69, 0xbfb8aa3b, v60
	v_exp_f32_e32 v70, v69
	v_mul_f32_e32 v69, 0xbfb8aa3b, v61
	v_exp_f32_e32 v71, v69
	v_rcp_f32_e32 v67, v68
	s_nop 0
	v_mul_f32_e32 v66, v66, v67
	v_cvt_pk_bf16_f32 v65, v66, v65
	v_mov_b32_e32 v246, v64
	v_mov_b32_e32 v247, v65
	v_lshl_add_u64 v[254:255], v[76:77], 0, v[242:243]
	s_nop 0
	v_permlane16_swap_b32_e32 v244, v246
	v_permlane16_swap_b32_e32 v245, v247
	global_store_dwordx4 v[254:255], v[244:247], off offset:64
	v_pk_add_f32 v[64:65], v[70:71], 1.0 op_sel_hi:[1,0]
	v_or_b32_e32 v66, 64, v140
	v_ashrrev_i32_e32 v67, 31, v66
	v_lshlrev_b64 v[66:67], 12, v[66:67]
	v_rcp_f32_e32 v68, v65
	s_nop 0
	v_mul_f32_e32 v61, v61, v68
	v_mul_f32_e32 v68, 0xbfb8aa3b, v62
	v_mul_f32_e32 v69, 0xbfb8aa3b, v63
	v_exp_f32_e32 v68, v68
	v_exp_f32_e32 v69, v69
	s_nop 0
	v_pk_add_f32 v[68:69], v[68:69], 1.0 op_sel_hi:[1,0]
	v_rcp_f32_e32 v65, v64
	s_nop 0
	v_mul_f32_e32 v60, v60, v65
	v_cvt_pk_bf16_f32 v64, v60, v61
	v_rcp_f32_e32 v60, v69
	s_nop 0
	v_mul_f32_e32 v63, v63, v60
	v_mul_f32_e32 v60, 0xbfb8aa3b, v56
	v_mul_f32_e32 v61, 0xbfb8aa3b, v57
	v_exp_f32_e32 v60, v60
	v_exp_f32_e32 v61, v61
	v_rcp_f32_e32 v65, v68
	s_nop 0
	v_mul_f32_e32 v62, v62, v65
	v_cvt_pk_bf16_f32 v65, v62, v63
	v_pk_add_f32 v[62:63], v[60:61], 1.0 op_sel_hi:[1,0]
	v_lshl_add_u64 v[60:61], s[68:69], 0, v[66:67]
	v_lshl_add_u64 v[60:61], v[60:61], 0, v[124:125]
	v_mov_b32_e32 v248, v64
	v_mov_b32_e32 v249, v65
	v_rcp_f32_e32 v64, v63
	s_nop 0
	v_mul_f32_e32 v57, v57, v64
	v_mul_f32_e32 v64, 0xbfb8aa3b, v58
	v_mul_f32_e32 v65, 0xbfb8aa3b, v59
	v_exp_f32_e32 v64, v64
	v_exp_f32_e32 v65, v65
	s_nop 0
	v_pk_add_f32 v[64:65], v[64:65], 1.0 op_sel_hi:[1,0]
	v_rcp_f32_e32 v63, v62
	s_nop 0
	v_mul_f32_e32 v56, v56, v63
	v_cvt_pk_bf16_f32 v56, v56, v57
	v_rcp_f32_e32 v57, v65
	s_nop 0
	v_mul_f32_e32 v57, v59, v57
	v_mul_f32_e32 v63, 0xbfb8aa3b, v53
	v_mul_f32_e32 v62, 0xbfb8aa3b, v52
	v_exp_f32_e32 v62, v62
	v_exp_f32_e32 v63, v63
	v_rcp_f32_e32 v59, v64
	s_nop 0
	v_mul_f32_e32 v58, v58, v59
	v_pk_add_f32 v[62:63], v[62:63], 1.0 op_sel_hi:[1,0]
	v_cvt_pk_bf16_f32 v57, v58, v57
	v_mov_b32_e32 v250, v56
	v_mov_b32_e32 v251, v57
	v_lshl_add_u64 v[252:253], v[60:61], 0, v[242:243]
	s_nop 0
	v_permlane16_swap_b32_e32 v248, v250
	v_permlane16_swap_b32_e32 v249, v251
	global_store_dwordx4 v[252:253], v[248:251], off
	v_rcp_f32_e32 v56, v63
	s_nop 0
	v_mul_f32_e32 v53, v53, v56
	v_mul_f32_e32 v56, 0xbfb8aa3b, v54
	v_mul_f32_e32 v57, 0xbfb8aa3b, v55
	v_exp_f32_e32 v56, v56
	v_exp_f32_e32 v57, v57
	s_nop 0
	v_pk_add_f32 v[56:57], v[56:57], 1.0 op_sel_hi:[1,0]
	v_rcp_f32_e32 v58, v62
	s_nop 0
	v_mul_f32_e32 v52, v52, v58
	v_cvt_pk_bf16_f32 v52, v52, v53
	v_rcp_f32_e32 v53, v57
	s_nop 0
	v_mul_f32_e32 v53, v55, v53
	v_mul_f32_e32 v59, 0xbfb8aa3b, v49
	v_mul_f32_e32 v58, 0xbfb8aa3b, v48
	v_exp_f32_e32 v58, v58
	v_exp_f32_e32 v59, v59
	v_rcp_f32_e32 v55, v56
	s_nop 0
	v_mul_f32_e32 v54, v54, v55
	v_pk_add_f32 v[58:59], v[58:59], 1.0 op_sel_hi:[1,0]
	v_cvt_pk_bf16_f32 v53, v54, v53
	v_mov_b32_e32 v156, v52
	v_mov_b32_e32 v157, v53
	v_rcp_f32_e32 v52, v59
	s_nop 0
	v_mul_f32_e32 v49, v49, v52
	v_mul_f32_e32 v52, 0xbfb8aa3b, v50
	v_mul_f32_e32 v53, 0xbfb8aa3b, v51
	v_exp_f32_e32 v52, v52
	v_exp_f32_e32 v53, v53
	s_nop 0
	v_pk_add_f32 v[52:53], v[52:53], 1.0 op_sel_hi:[1,0]
	v_rcp_f32_e32 v54, v58
	s_nop 0
	v_mul_f32_e32 v48, v48, v54
	v_cvt_pk_bf16_f32 v48, v48, v49
	v_rcp_f32_e32 v49, v53
	s_nop 0
	v_mul_f32_e32 v49, v51, v49
	v_mul_f32_e32 v53, 0xbfb8aa3b, v44
	v_exp_f32_e32 v54, v53
	v_mul_f32_e32 v53, 0xbfb8aa3b, v45
	v_exp_f32_e32 v55, v53
	v_rcp_f32_e32 v51, v52
	s_nop 0
	v_mul_f32_e32 v50, v50, v51
	v_cvt_pk_bf16_f32 v49, v50, v49
	v_mov_b32_e32 v158, v48
	v_mov_b32_e32 v159, v49
	v_lshl_add_u64 v[254:255], v[60:61], 0, v[242:243]
	s_nop 0
	v_permlane16_swap_b32_e32 v156, v158
	v_permlane16_swap_b32_e32 v157, v159
	global_store_dwordx4 v[254:255], v[156:159], off offset:64
	v_pk_add_f32 v[48:49], v[54:55], 1.0 op_sel_hi:[1,0]
	v_or_b32_e32 v50, 0x50, v140
	v_ashrrev_i32_e32 v51, 31, v50
	v_lshlrev_b64 v[50:51], 12, v[50:51]
	v_rcp_f32_e32 v52, v49
	s_nop 0
	v_mul_f32_e32 v45, v45, v52
	v_mul_f32_e32 v52, 0xbfb8aa3b, v46
	v_mul_f32_e32 v53, 0xbfb8aa3b, v47
	v_exp_f32_e32 v52, v52
	v_exp_f32_e32 v53, v53
	s_nop 0
	v_pk_add_f32 v[52:53], v[52:53], 1.0 op_sel_hi:[1,0]
	v_rcp_f32_e32 v49, v48
	s_nop 0
	v_mul_f32_e32 v44, v44, v49
	v_cvt_pk_bf16_f32 v48, v44, v45
	v_rcp_f32_e32 v44, v53
	s_nop 0
	v_mul_f32_e32 v47, v47, v44
	v_mul_f32_e32 v44, 0xbfb8aa3b, v40
	v_mul_f32_e32 v45, 0xbfb8aa3b, v41
	v_exp_f32_e32 v44, v44
	v_exp_f32_e32 v45, v45
	v_rcp_f32_e32 v49, v52
	s_nop 0
	v_mul_f32_e32 v46, v46, v49
	v_cvt_pk_bf16_f32 v49, v46, v47
	v_pk_add_f32 v[46:47], v[44:45], 1.0 op_sel_hi:[1,0]
	v_lshl_add_u64 v[44:45], s[68:69], 0, v[50:51]
	v_lshl_add_u64 v[44:45], v[44:45], 0, v[124:125]
	v_mov_b32_e32 v160, v48
	v_mov_b32_e32 v161, v49
	v_rcp_f32_e32 v48, v47
	s_nop 0
	v_mul_f32_e32 v41, v41, v48
	v_mul_f32_e32 v48, 0xbfb8aa3b, v42
	v_mul_f32_e32 v49, 0xbfb8aa3b, v43
	v_exp_f32_e32 v48, v48
	v_exp_f32_e32 v49, v49
	s_nop 0
	v_pk_add_f32 v[48:49], v[48:49], 1.0 op_sel_hi:[1,0]
	v_rcp_f32_e32 v47, v46
	s_nop 0
	v_mul_f32_e32 v40, v40, v47
	v_cvt_pk_bf16_f32 v40, v40, v41
	v_rcp_f32_e32 v41, v49
	s_nop 0
	v_mul_f32_e32 v41, v43, v41
	v_mul_f32_e32 v47, 0xbfb8aa3b, v37
	v_mul_f32_e32 v46, 0xbfb8aa3b, v36
	v_exp_f32_e32 v46, v46
	v_exp_f32_e32 v47, v47
	v_rcp_f32_e32 v43, v48
	s_nop 0
	v_mul_f32_e32 v42, v42, v43
	v_pk_add_f32 v[46:47], v[46:47], 1.0 op_sel_hi:[1,0]
	v_cvt_pk_bf16_f32 v41, v42, v41
	v_mov_b32_e32 v162, v40
	v_mov_b32_e32 v163, v41
	v_lshl_add_u64 v[252:253], v[44:45], 0, v[242:243]
	s_nop 0
	v_permlane16_swap_b32_e32 v160, v162
	v_permlane16_swap_b32_e32 v161, v163
	global_store_dwordx4 v[252:253], v[160:163], off
	v_rcp_f32_e32 v40, v47
	s_nop 0
	v_mul_f32_e32 v37, v37, v40
	v_mul_f32_e32 v40, 0xbfb8aa3b, v38
	v_mul_f32_e32 v41, 0xbfb8aa3b, v39
	v_exp_f32_e32 v40, v40
	v_exp_f32_e32 v41, v41
	s_nop 0
	v_pk_add_f32 v[40:41], v[40:41], 1.0 op_sel_hi:[1,0]
	v_rcp_f32_e32 v42, v46
	s_nop 0
	v_mul_f32_e32 v36, v36, v42
	v_cvt_pk_bf16_f32 v36, v36, v37
	v_rcp_f32_e32 v37, v41
	s_nop 0
	v_mul_f32_e32 v37, v39, v37
	v_mul_f32_e32 v43, 0xbfb8aa3b, v33
	v_mul_f32_e32 v42, 0xbfb8aa3b, v32
	v_exp_f32_e32 v42, v42
	v_exp_f32_e32 v43, v43
	v_rcp_f32_e32 v39, v40
	s_nop 0
	v_mul_f32_e32 v38, v38, v39
	v_pk_add_f32 v[42:43], v[42:43], 1.0 op_sel_hi:[1,0]
	v_cvt_pk_bf16_f32 v37, v38, v37
	v_mov_b32_e32 v164, v36
	v_mov_b32_e32 v165, v37
	v_rcp_f32_e32 v36, v43
	s_nop 0
	v_mul_f32_e32 v33, v33, v36
	v_mul_f32_e32 v36, 0xbfb8aa3b, v34
	v_mul_f32_e32 v37, 0xbfb8aa3b, v35
	v_exp_f32_e32 v36, v36
	v_exp_f32_e32 v37, v37
	s_nop 0
	v_pk_add_f32 v[36:37], v[36:37], 1.0 op_sel_hi:[1,0]
	v_rcp_f32_e32 v38, v42
	s_nop 0
	v_mul_f32_e32 v32, v32, v38
	v_cvt_pk_bf16_f32 v32, v32, v33
	v_rcp_f32_e32 v33, v37
	s_nop 0
	v_mul_f32_e32 v33, v35, v33
	v_mul_f32_e32 v37, 0xbfb8aa3b, v28
	v_exp_f32_e32 v38, v37
	v_mul_f32_e32 v37, 0xbfb8aa3b, v29
	v_exp_f32_e32 v39, v37
	v_rcp_f32_e32 v35, v36
	s_nop 0
	v_mul_f32_e32 v34, v34, v35
	v_cvt_pk_bf16_f32 v33, v34, v33
	v_mov_b32_e32 v166, v32
	v_mov_b32_e32 v167, v33
	v_lshl_add_u64 v[254:255], v[44:45], 0, v[242:243]
	s_nop 0
	v_permlane16_swap_b32_e32 v164, v166
	v_permlane16_swap_b32_e32 v165, v167
	global_store_dwordx4 v[254:255], v[164:167], off offset:64
	v_pk_add_f32 v[32:33], v[38:39], 1.0 op_sel_hi:[1,0]
	v_or_b32_e32 v34, 0x60, v140
	v_ashrrev_i32_e32 v35, 31, v34
	v_lshlrev_b64 v[34:35], 12, v[34:35]
	v_rcp_f32_e32 v36, v33
	s_nop 0
	v_mul_f32_e32 v29, v29, v36
	v_mul_f32_e32 v36, 0xbfb8aa3b, v30
	v_mul_f32_e32 v37, 0xbfb8aa3b, v31
	v_exp_f32_e32 v36, v36
	v_exp_f32_e32 v37, v37
	s_nop 0
	v_pk_add_f32 v[36:37], v[36:37], 1.0 op_sel_hi:[1,0]
	v_rcp_f32_e32 v33, v32
	s_nop 0
	v_mul_f32_e32 v28, v28, v33
	v_cvt_pk_bf16_f32 v32, v28, v29
	v_rcp_f32_e32 v28, v37
	s_nop 0
	v_mul_f32_e32 v31, v31, v28
	v_mul_f32_e32 v28, 0xbfb8aa3b, v24
	v_mul_f32_e32 v29, 0xbfb8aa3b, v25
	v_exp_f32_e32 v28, v28
	v_exp_f32_e32 v29, v29
	v_rcp_f32_e32 v33, v36
	s_nop 0
	v_mul_f32_e32 v30, v30, v33
	v_cvt_pk_bf16_f32 v33, v30, v31
	v_pk_add_f32 v[30:31], v[28:29], 1.0 op_sel_hi:[1,0]
	v_lshl_add_u64 v[28:29], s[68:69], 0, v[34:35]
	v_lshl_add_u64 v[28:29], v[28:29], 0, v[124:125]
	v_mov_b32_e32 v168, v32
	v_mov_b32_e32 v169, v33
	v_rcp_f32_e32 v32, v31
	s_nop 0
	v_mul_f32_e32 v25, v25, v32
	v_mul_f32_e32 v32, 0xbfb8aa3b, v26
	v_mul_f32_e32 v33, 0xbfb8aa3b, v27
	v_exp_f32_e32 v32, v32
	v_exp_f32_e32 v33, v33
	s_nop 0
	v_pk_add_f32 v[32:33], v[32:33], 1.0 op_sel_hi:[1,0]
	v_rcp_f32_e32 v31, v30
	s_nop 0
	v_mul_f32_e32 v24, v24, v31
	v_cvt_pk_bf16_f32 v24, v24, v25
	v_rcp_f32_e32 v25, v33
	s_nop 0
	v_mul_f32_e32 v25, v27, v25
	v_mul_f32_e32 v31, 0xbfb8aa3b, v21
	v_mul_f32_e32 v30, 0xbfb8aa3b, v20
	v_exp_f32_e32 v30, v30
	v_exp_f32_e32 v31, v31
	v_rcp_f32_e32 v27, v32
	s_nop 0
	v_mul_f32_e32 v26, v26, v27
	v_pk_add_f32 v[30:31], v[30:31], 1.0 op_sel_hi:[1,0]
	v_cvt_pk_bf16_f32 v25, v26, v25
	v_mov_b32_e32 v170, v24
	v_mov_b32_e32 v171, v25
	v_lshl_add_u64 v[252:253], v[28:29], 0, v[242:243]
	s_nop 0
	v_permlane16_swap_b32_e32 v168, v170
	v_permlane16_swap_b32_e32 v169, v171
	global_store_dwordx4 v[252:253], v[168:171], off
	v_rcp_f32_e32 v24, v31
	s_nop 0
	v_mul_f32_e32 v21, v21, v24
	v_mul_f32_e32 v24, 0xbfb8aa3b, v22
	v_mul_f32_e32 v25, 0xbfb8aa3b, v23
	v_exp_f32_e32 v24, v24
	v_exp_f32_e32 v25, v25
	s_nop 0
	v_pk_add_f32 v[24:25], v[24:25], 1.0 op_sel_hi:[1,0]
	v_rcp_f32_e32 v26, v30
	s_nop 0
	v_mul_f32_e32 v20, v20, v26
	v_cvt_pk_bf16_f32 v20, v20, v21
	v_rcp_f32_e32 v21, v25
	s_nop 0
	v_mul_f32_e32 v21, v23, v21
	v_mul_f32_e32 v27, 0xbfb8aa3b, v17
	v_mul_f32_e32 v26, 0xbfb8aa3b, v16
	v_exp_f32_e32 v26, v26
	v_exp_f32_e32 v27, v27
	v_rcp_f32_e32 v23, v24
	s_nop 0
	v_mul_f32_e32 v22, v22, v23
	v_pk_add_f32 v[26:27], v[26:27], 1.0 op_sel_hi:[1,0]
	v_cvt_pk_bf16_f32 v21, v22, v21
	v_mov_b32_e32 v172, v20
	v_mov_b32_e32 v173, v21
	v_rcp_f32_e32 v20, v27
	s_nop 0
	v_mul_f32_e32 v17, v17, v20
	v_mul_f32_e32 v20, 0xbfb8aa3b, v18
	v_mul_f32_e32 v21, 0xbfb8aa3b, v19
	v_exp_f32_e32 v20, v20
	v_exp_f32_e32 v21, v21
	s_nop 0
	v_pk_add_f32 v[20:21], v[20:21], 1.0 op_sel_hi:[1,0]
	v_rcp_f32_e32 v22, v26
	s_nop 0
	v_mul_f32_e32 v16, v16, v22
	v_cvt_pk_bf16_f32 v16, v16, v17
	v_rcp_f32_e32 v17, v21
	s_nop 0
	v_mul_f32_e32 v17, v19, v17
	v_mul_f32_e32 v21, 0xbfb8aa3b, v12
	v_exp_f32_e32 v22, v21
	v_mul_f32_e32 v21, 0xbfb8aa3b, v13
	v_exp_f32_e32 v23, v21
	v_rcp_f32_e32 v19, v20
	s_nop 0
	v_mul_f32_e32 v18, v18, v19
	v_cvt_pk_bf16_f32 v17, v18, v17
	v_mov_b32_e32 v174, v16
	v_mov_b32_e32 v175, v17
	v_lshl_add_u64 v[254:255], v[28:29], 0, v[242:243]
	s_nop 0
	v_permlane16_swap_b32_e32 v172, v174
	v_permlane16_swap_b32_e32 v173, v175
	global_store_dwordx4 v[254:255], v[172:175], off offset:64
	v_pk_add_f32 v[16:17], v[22:23], 1.0 op_sel_hi:[1,0]
	v_or_b32_e32 v18, 0x70, v140
	v_ashrrev_i32_e32 v19, 31, v18
	v_lshlrev_b64 v[18:19], 12, v[18:19]
	v_rcp_f32_e32 v20, v17
	s_nop 0
	v_mul_f32_e32 v13, v13, v20
	v_mul_f32_e32 v20, 0xbfb8aa3b, v14
	v_mul_f32_e32 v21, 0xbfb8aa3b, v15
	v_exp_f32_e32 v20, v20
	v_exp_f32_e32 v21, v21
	s_nop 0
	v_pk_add_f32 v[20:21], v[20:21], 1.0 op_sel_hi:[1,0]
	v_rcp_f32_e32 v17, v16
	s_nop 0
	v_mul_f32_e32 v12, v12, v17
	v_cvt_pk_bf16_f32 v16, v12, v13
	v_rcp_f32_e32 v12, v21
	s_nop 0
	v_mul_f32_e32 v15, v15, v12
	v_mul_f32_e32 v12, 0xbfb8aa3b, v8
	v_mul_f32_e32 v13, 0xbfb8aa3b, v9
	v_exp_f32_e32 v12, v12
	v_exp_f32_e32 v13, v13
	v_rcp_f32_e32 v17, v20
	s_nop 0
	v_mul_f32_e32 v14, v14, v17
	v_cvt_pk_bf16_f32 v17, v14, v15
	v_pk_add_f32 v[14:15], v[12:13], 1.0 op_sel_hi:[1,0]
	v_lshl_add_u64 v[12:13], s[68:69], 0, v[18:19]
	v_lshl_add_u64 v[12:13], v[12:13], 0, v[124:125]
	v_mov_b32_e32 v244, v16
	v_mov_b32_e32 v245, v17
	v_rcp_f32_e32 v16, v15
	s_nop 0
	v_mul_f32_e32 v9, v9, v16
	v_mul_f32_e32 v16, 0xbfb8aa3b, v10
	v_mul_f32_e32 v17, 0xbfb8aa3b, v11
	v_exp_f32_e32 v16, v16
	v_exp_f32_e32 v17, v17
	s_nop 0
	v_pk_add_f32 v[16:17], v[16:17], 1.0 op_sel_hi:[1,0]
	v_rcp_f32_e32 v15, v14
	s_nop 0
	v_mul_f32_e32 v8, v8, v15
	v_cvt_pk_bf16_f32 v8, v8, v9
	v_rcp_f32_e32 v9, v17
	s_nop 0
	v_mul_f32_e32 v9, v11, v9
	v_mul_f32_e32 v15, 0xbfb8aa3b, v5
	v_mul_f32_e32 v14, 0xbfb8aa3b, v4
	v_exp_f32_e32 v14, v14
	v_exp_f32_e32 v15, v15
	v_rcp_f32_e32 v11, v16
	s_nop 0
	v_mul_f32_e32 v10, v10, v11
	v_pk_add_f32 v[14:15], v[14:15], 1.0 op_sel_hi:[1,0]
	v_cvt_pk_bf16_f32 v9, v10, v9
	v_mov_b32_e32 v246, v8
	v_mov_b32_e32 v247, v9
	v_lshl_add_u64 v[252:253], v[12:13], 0, v[242:243]
	s_nop 0
	v_permlane16_swap_b32_e32 v244, v246
	v_permlane16_swap_b32_e32 v245, v247
	global_store_dwordx4 v[252:253], v[244:247], off
	v_rcp_f32_e32 v8, v15
	s_nop 0
	v_mul_f32_e32 v5, v5, v8
	v_mul_f32_e32 v8, 0xbfb8aa3b, v6
	v_mul_f32_e32 v9, 0xbfb8aa3b, v7
	v_exp_f32_e32 v8, v8
	v_exp_f32_e32 v9, v9
	s_nop 0
	v_pk_add_f32 v[8:9], v[8:9], 1.0 op_sel_hi:[1,0]
	v_rcp_f32_e32 v10, v14
	s_nop 0
	v_mul_f32_e32 v4, v4, v10
	v_cvt_pk_bf16_f32 v4, v4, v5
	v_rcp_f32_e32 v5, v9
	s_nop 0
	v_mul_f32_e32 v5, v7, v5
	v_mul_f32_e32 v11, 0xbfb8aa3b, v1
	v_mul_f32_e32 v10, 0xbfb8aa3b, v0
	v_exp_f32_e32 v10, v10
	v_exp_f32_e32 v11, v11
	v_rcp_f32_e32 v7, v8
	s_nop 0
	v_mul_f32_e32 v6, v6, v7
	v_pk_add_f32 v[10:11], v[10:11], 1.0 op_sel_hi:[1,0]
	v_cvt_pk_bf16_f32 v5, v6, v5
	v_mov_b32_e32 v248, v4
	v_mov_b32_e32 v249, v5
	v_rcp_f32_e32 v4, v11
	s_nop 0
	v_mul_f32_e32 v1, v1, v4
	v_mul_f32_e32 v4, 0xbfb8aa3b, v2
	v_mul_f32_e32 v5, 0xbfb8aa3b, v3
	v_exp_f32_e32 v4, v4
	v_exp_f32_e32 v5, v5
	s_nop 0
	v_pk_add_f32 v[4:5], v[4:5], 1.0 op_sel_hi:[1,0]
	v_rcp_f32_e32 v6, v10
	s_nop 0
	v_mul_f32_e32 v0, v0, v6
	v_cvt_pk_bf16_f32 v0, v0, v1
	v_rcp_f32_e32 v1, v5
	s_nop 0
	v_mul_f32_e32 v1, v3, v1
	v_rcp_f32_e32 v3, v4
	s_nop 0
	v_mul_f32_e32 v2, v2, v3
	v_cvt_pk_bf16_f32 v1, v2, v1
	s_and_b64 vcc, exec, s[26:27]
	v_mov_b32_e32 v250, v0
	v_mov_b32_e32 v251, v1
	v_lshl_add_u64 v[254:255], v[12:13], 0, v[242:243]
	s_nop 0
	v_permlane16_swap_b32_e32 v248, v250
	v_permlane16_swap_b32_e32 v249, v251
	global_store_dwordx4 v[254:255], v[248:251], off offset:64
	s_cbranch_vccnz .LBB0_1143

.LBB0_1179:
	s_nop 0
	v_add_u32_e32 v140, s63, v152
	v_ashrrev_i32_e32 v141, 31, v140
	v_or_b32_e32 v144, s30, v151
	v_lshlrev_b64 v[142:143], 11, v[140:141]
	v_ashrrev_i32_e32 v145, 31, v144
	v_cvt_pk_bf16_f32 v124, v124, v125
	v_cvt_pk_bf16_f32 v125, v126, v127
	v_lshl_add_u64 v[126:127], s[4:5], 0, v[142:143]
	v_lshlrev_b64 v[142:143], 1, v[144:145]
	v_lshl_add_u64 v[126:127], v[126:127], 0, v[142:143]
	v_cvt_pk_bf16_f32 v112, v112, v113
	v_cvt_pk_bf16_f32 v113, v114, v115
	v_mov_b32_e32 v246, v112
	v_mov_b32_e32 v247, v113
	v_or_b32_e32 v112, 16, v140
	v_ashrrev_i32_e32 v113, 31, v112
	v_lshlrev_b64 v[112:113], 11, v[112:113]
	v_cvt_pk_bf16_f32 v108, v108, v109
	v_cvt_pk_bf16_f32 v109, v110, v111
	v_lshl_add_u64 v[110:111], s[4:5], 0, v[112:113]
	v_lshl_add_u64 v[110:111], v[110:111], 0, v[142:143]
	v_cvt_pk_bf16_f32 v96, v96, v97
	v_cvt_pk_bf16_f32 v97, v98, v99
	v_mov_b32_e32 v250, v96
	v_mov_b32_e32 v251, v97
	v_or_b32_e32 v96, 32, v140
	v_ashrrev_i32_e32 v97, 31, v96
	v_lshlrev_b64 v[96:97], 11, v[96:97]
	v_cvt_pk_bf16_f32 v92, v92, v93
	v_cvt_pk_bf16_f32 v93, v94, v95
	v_lshl_add_u64 v[94:95], s[4:5], 0, v[96:97]
	v_lshl_add_u64 v[94:95], v[94:95], 0, v[142:143]
	v_cvt_pk_bf16_f32 v80, v80, v81
	v_cvt_pk_bf16_f32 v81, v82, v83
	v_mov_b32_e32 v158, v80
	v_mov_b32_e32 v159, v81
	v_or_b32_e32 v80, 48, v140
	v_ashrrev_i32_e32 v81, 31, v80
	v_lshlrev_b64 v[80:81], 11, v[80:81]
	v_cvt_pk_bf16_f32 v76, v76, v77
	v_cvt_pk_bf16_f32 v77, v78, v79
	v_lshl_add_u64 v[78:79], s[4:5], 0, v[80:81]
	v_lshl_add_u64 v[78:79], v[78:79], 0, v[142:143]
	v_cvt_pk_bf16_f32 v64, v64, v65
	v_cvt_pk_bf16_f32 v65, v66, v67
	v_mov_b32_e32 v162, v64
	v_mov_b32_e32 v163, v65
	v_or_b32_e32 v64, 64, v140
	v_ashrrev_i32_e32 v65, 31, v64
	v_lshlrev_b64 v[64:65], 11, v[64:65]
	v_cvt_pk_bf16_f32 v60, v60, v61
	v_cvt_pk_bf16_f32 v61, v62, v63
	v_lshl_add_u64 v[62:63], s[4:5], 0, v[64:65]
	v_lshl_add_u64 v[62:63], v[62:63], 0, v[142:143]
	v_cvt_pk_bf16_f32 v48, v48, v49
	v_cvt_pk_bf16_f32 v49, v50, v51
	v_mov_b32_e32 v166, v48
	v_mov_b32_e32 v167, v49
	v_or_b32_e32 v48, 0x50, v140
	v_ashrrev_i32_e32 v49, 31, v48
	v_lshlrev_b64 v[48:49], 11, v[48:49]
	v_cvt_pk_bf16_f32 v44, v44, v45
	v_cvt_pk_bf16_f32 v45, v46, v47
	v_lshl_add_u64 v[46:47], s[4:5], 0, v[48:49]
	v_lshl_add_u64 v[46:47], v[46:47], 0, v[142:143]
	v_cvt_pk_bf16_f32 v32, v32, v33
	v_cvt_pk_bf16_f32 v33, v34, v35
	v_mov_b32_e32 v170, v32
	v_mov_b32_e32 v171, v33
	v_or_b32_e32 v32, 0x60, v140
	v_ashrrev_i32_e32 v33, 31, v32
	v_lshlrev_b64 v[32:33], 11, v[32:33]
	v_cvt_pk_bf16_f32 v28, v28, v29
	v_cvt_pk_bf16_f32 v29, v30, v31
	v_lshl_add_u64 v[30:31], s[4:5], 0, v[32:33]
	v_lshl_add_u64 v[30:31], v[30:31], 0, v[142:143]
	v_cvt_pk_bf16_f32 v16, v16, v17
	v_cvt_pk_bf16_f32 v17, v18, v19
	v_mov_b32_e32 v174, v16
	v_mov_b32_e32 v175, v17
	v_or_b32_e32 v16, 0x70, v140
	v_ashrrev_i32_e32 v17, 31, v16
	v_lshlrev_b64 v[16:17], 11, v[16:17]
	v_cvt_pk_bf16_f32 v12, v12, v13
	v_cvt_pk_bf16_f32 v13, v14, v15
	v_lshl_add_u64 v[14:15], s[4:5], 0, v[16:17]
	v_lshl_add_u64 v[14:15], v[14:15], 0, v[142:143]
	v_cvt_pk_bf16_f32 v4, v4, v5
	v_cvt_pk_bf16_f32 v5, v6, v7
	v_cvt_pk_bf16_f32 v120, v120, v121
	v_cvt_pk_bf16_f32 v121, v122, v123
	v_cvt_pk_bf16_f32 v116, v116, v117
	v_cvt_pk_bf16_f32 v117, v118, v119
	v_cvt_pk_bf16_f32 v104, v104, v105
	v_cvt_pk_bf16_f32 v105, v106, v107
	v_cvt_pk_bf16_f32 v100, v100, v101
	v_cvt_pk_bf16_f32 v101, v102, v103
	v_cvt_pk_bf16_f32 v88, v88, v89
	v_cvt_pk_bf16_f32 v89, v90, v91
	v_cvt_pk_bf16_f32 v84, v84, v85
	v_cvt_pk_bf16_f32 v85, v86, v87
	v_cvt_pk_bf16_f32 v72, v72, v73
	v_cvt_pk_bf16_f32 v73, v74, v75
	v_cvt_pk_bf16_f32 v68, v68, v69
	v_cvt_pk_bf16_f32 v69, v70, v71
	v_cvt_pk_bf16_f32 v56, v56, v57
	v_cvt_pk_bf16_f32 v57, v58, v59
	v_cvt_pk_bf16_f32 v52, v52, v53
	v_cvt_pk_bf16_f32 v53, v54, v55
	v_cvt_pk_bf16_f32 v40, v40, v41
	v_cvt_pk_bf16_f32 v41, v42, v43
	v_cvt_pk_bf16_f32 v36, v36, v37
	v_cvt_pk_bf16_f32 v37, v38, v39
	v_cvt_pk_bf16_f32 v24, v24, v25
	v_cvt_pk_bf16_f32 v25, v26, v27
	v_cvt_pk_bf16_f32 v20, v20, v21
	v_cvt_pk_bf16_f32 v21, v22, v23
	global_store_dwordx2 v[14:15], v[4:5], off offset:32
	v_cvt_pk_bf16_f32 v4, v8, v9
	v_cvt_pk_bf16_f32 v5, v10, v11
	v_cvt_pk_bf16_f32 v0, v0, v1
	v_cvt_pk_bf16_f32 v1, v2, v3
	s_mov_b64 s[40:41], -1
	s_and_b64 vcc, exec, s[28:29]
	global_store_dwordx2 v[126:127], v[124:125], off
	global_store_dwordx2 v[126:127], v[120:121], off offset:32
	v_and_b32_e32 v242, 16, v178
	v_lshrrev_b32_e32 v243, 1, v242
	v_add_u32_e32 v242, v242, v243
	v_mov_b32_e32 v243, 0
	v_mov_b32_e32 v244, v116
	v_mov_b32_e32 v245, v117
	v_lshl_add_u64 v[252:253], v[126:127], 0, v[242:243]
	s_nop 0
	v_permlane16_swap_b32_e32 v244, v246
	v_permlane16_swap_b32_e32 v245, v247
	global_store_dwordx4 v[252:253], v[244:247], off offset:64
	s_nop 1
	v_mov_b32_e32 v244, v108
	v_mov_b32_e32 v245, v109
	v_mov_b32_e32 v246, v104
	v_mov_b32_e32 v247, v105
	v_lshl_add_u64 v[254:255], v[110:111], 0, v[242:243]
	s_nop 0
	v_permlane16_swap_b32_e32 v244, v246
	v_permlane16_swap_b32_e32 v245, v247
	global_store_dwordx4 v[254:255], v[244:247], off
	v_mov_b32_e32 v248, v100
	v_mov_b32_e32 v249, v101
	v_lshl_add_u64 v[252:253], v[110:111], 0, v[242:243]
	s_nop 0
	v_permlane16_swap_b32_e32 v248, v250
	v_permlane16_swap_b32_e32 v249, v251
	global_store_dwordx4 v[252:253], v[248:251], off offset:64
	s_nop 1
	v_mov_b32_e32 v248, v92
	v_mov_b32_e32 v249, v93
	v_mov_b32_e32 v250, v88
	v_mov_b32_e32 v251, v89
	v_lshl_add_u64 v[254:255], v[94:95], 0, v[242:243]
	s_nop 0
	v_permlane16_swap_b32_e32 v248, v250
	v_permlane16_swap_b32_e32 v249, v251
	global_store_dwordx4 v[254:255], v[248:251], off
	v_mov_b32_e32 v156, v84
	v_mov_b32_e32 v157, v85
	v_lshl_add_u64 v[252:253], v[94:95], 0, v[242:243]
	s_nop 0
	v_permlane16_swap_b32_e32 v156, v158
	v_permlane16_swap_b32_e32 v157, v159
	global_store_dwordx4 v[252:253], v[156:159], off offset:64
	s_nop 1
	v_mov_b32_e32 v244, v76
	v_mov_b32_e32 v245, v77
	v_mov_b32_e32 v246, v72
	v_mov_b32_e32 v247, v73
	v_lshl_add_u64 v[254:255], v[78:79], 0, v[242:243]
	s_nop 0
	v_permlane16_swap_b32_e32 v244, v246
	v_permlane16_swap_b32_e32 v245, v247
	global_store_dwordx4 v[254:255], v[244:247], off
	v_mov_b32_e32 v160, v68
	v_mov_b32_e32 v161, v69
	v_lshl_add_u64 v[252:253], v[78:79], 0, v[242:243]
	s_nop 0
	v_permlane16_swap_b32_e32 v160, v162
	v_permlane16_swap_b32_e32 v161, v163
	global_store_dwordx4 v[252:253], v[160:163], off offset:64
	s_nop 1
	v_mov_b32_e32 v156, v60
	v_mov_b32_e32 v157, v61
	v_mov_b32_e32 v158, v56
	v_mov_b32_e32 v159, v57
	v_lshl_add_u64 v[254:255], v[62:63], 0, v[242:243]
	s_nop 0
	v_permlane16_swap_b32_e32 v156, v158
	v_permlane16_swap_b32_e32 v157, v159
	global_store_dwordx4 v[254:255], v[156:159], off
	v_mov_b32_e32 v164, v52
	v_mov_b32_e32 v165, v53
	v_lshl_add_u64 v[252:253], v[62:63], 0, v[242:243]
	s_nop 0
	v_permlane16_swap_b32_e32 v164, v166
	v_permlane16_swap_b32_e32 v165, v167
	global_store_dwordx4 v[252:253], v[164:167], off offset:64
	v_mov_b32_e32 v248, v44
	v_mov_b32_e32 v249, v45
	v_mov_b32_e32 v250, v40
	v_mov_b32_e32 v251, v41
	v_lshl_add_u64 v[254:255], v[46:47], 0, v[242:243]
	s_nop 0
	v_permlane16_swap_b32_e32 v248, v250
	v_permlane16_swap_b32_e32 v249, v251
	global_store_dwordx4 v[254:255], v[248:251], off
	v_mov_b32_e32 v168, v36
	v_mov_b32_e32 v169, v37
	v_lshl_add_u64 v[252:253], v[46:47], 0, v[242:243]
	s_nop 0
	v_permlane16_swap_b32_e32 v168, v170
	v_permlane16_swap_b32_e32 v169, v171
	global_store_dwordx4 v[252:253], v[168:171], off offset:64
	v_mov_b32_e32 v160, v28
	v_mov_b32_e32 v161, v29
	v_mov_b32_e32 v162, v24
	v_mov_b32_e32 v163, v25
	v_lshl_add_u64 v[254:255], v[30:31], 0, v[242:243]
	s_nop 0
	v_permlane16_swap_b32_e32 v160, v162
	v_permlane16_swap_b32_e32 v161, v163
	global_store_dwordx4 v[254:255], v[160:163], off
	v_mov_b32_e32 v172, v20
	v_mov_b32_e32 v173, v21
	v_lshl_add_u64 v[252:253], v[30:31], 0, v[242:243]
	s_nop 0
	v_permlane16_swap_b32_e32 v172, v174
	v_permlane16_swap_b32_e32 v173, v175
	global_store_dwordx4 v[252:253], v[172:175], off offset:64
	global_store_dwordx2 v[14:15], v[12:13], off
	v_mov_b32_e32 v244, v4
	v_mov_b32_e32 v245, v5
	v_mov_b32_e32 v246, v0
	v_mov_b32_e32 v247, v1
	v_lshl_add_u64 v[254:255], v[14:15], 0, v[242:243]
	s_nop 0
	v_permlane16_swap_b32_e32 v244, v246
	v_permlane16_swap_b32_e32 v245, v247
	global_store_dwordx4 v[254:255], v[244:247], off offset:64
	s_cbranch_vccnz .LBB0_1190

.LBB0_1547:
	s_nop 0
	v_add_u32_e32 v140, s61, v152
	v_ashrrev_i32_e32 v141, 31, v140
	v_or_b32_e32 v144, s28, v151
	v_lshlrev_b64 v[142:143], 11, v[140:141]
	v_ashrrev_i32_e32 v145, 31, v144
	v_cvt_pk_bf16_f32 v124, v124, v125
	v_cvt_pk_bf16_f32 v125, v126, v127
	v_lshl_add_u64 v[126:127], s[68:69], 0, v[142:143]
	v_lshlrev_b64 v[142:143], 1, v[144:145]
	v_lshl_add_u64 v[126:127], v[126:127], 0, v[142:143]
	v_cvt_pk_bf16_f32 v112, v112, v113
	v_cvt_pk_bf16_f32 v113, v114, v115
	v_mov_b32_e32 v246, v112
	v_mov_b32_e32 v247, v113
	v_or_b32_e32 v112, 16, v140
	v_ashrrev_i32_e32 v113, 31, v112
	v_lshlrev_b64 v[112:113], 11, v[112:113]
	v_cvt_pk_bf16_f32 v108, v108, v109
	v_cvt_pk_bf16_f32 v109, v110, v111
	v_lshl_add_u64 v[110:111], s[68:69], 0, v[112:113]
	v_lshl_add_u64 v[110:111], v[110:111], 0, v[142:143]
	v_cvt_pk_bf16_f32 v96, v96, v97
	v_cvt_pk_bf16_f32 v97, v98, v99
	v_mov_b32_e32 v250, v96
	v_mov_b32_e32 v251, v97
	v_or_b32_e32 v96, 32, v140
	v_ashrrev_i32_e32 v97, 31, v96
	v_lshlrev_b64 v[96:97], 11, v[96:97]
	v_cvt_pk_bf16_f32 v92, v92, v93
	v_cvt_pk_bf16_f32 v93, v94, v95
	v_lshl_add_u64 v[94:95], s[68:69], 0, v[96:97]
	v_lshl_add_u64 v[94:95], v[94:95], 0, v[142:143]
	v_cvt_pk_bf16_f32 v80, v80, v81
	v_cvt_pk_bf16_f32 v81, v82, v83
	v_mov_b32_e32 v158, v80
	v_mov_b32_e32 v159, v81
	v_or_b32_e32 v80, 48, v140
	v_ashrrev_i32_e32 v81, 31, v80
	v_lshlrev_b64 v[80:81], 11, v[80:81]
	v_cvt_pk_bf16_f32 v76, v76, v77
	v_cvt_pk_bf16_f32 v77, v78, v79
	v_lshl_add_u64 v[78:79], s[68:69], 0, v[80:81]
	v_lshl_add_u64 v[78:79], v[78:79], 0, v[142:143]
	v_cvt_pk_bf16_f32 v64, v64, v65
	v_cvt_pk_bf16_f32 v65, v66, v67
	v_mov_b32_e32 v162, v64
	v_mov_b32_e32 v163, v65
	v_or_b32_e32 v64, 64, v140
	v_ashrrev_i32_e32 v65, 31, v64
	v_lshlrev_b64 v[64:65], 11, v[64:65]
	v_cvt_pk_bf16_f32 v60, v60, v61
	v_cvt_pk_bf16_f32 v61, v62, v63
	v_lshl_add_u64 v[62:63], s[68:69], 0, v[64:65]
	v_lshl_add_u64 v[62:63], v[62:63], 0, v[142:143]
	v_cvt_pk_bf16_f32 v48, v48, v49
	v_cvt_pk_bf16_f32 v49, v50, v51
	v_mov_b32_e32 v166, v48
	v_mov_b32_e32 v167, v49
	v_or_b32_e32 v48, 0x50, v140
	v_ashrrev_i32_e32 v49, 31, v48
	v_lshlrev_b64 v[48:49], 11, v[48:49]
	v_cvt_pk_bf16_f32 v44, v44, v45
	v_cvt_pk_bf16_f32 v45, v46, v47
	v_lshl_add_u64 v[46:47], s[68:69], 0, v[48:49]
	v_lshl_add_u64 v[46:47], v[46:47], 0, v[142:143]
	v_cvt_pk_bf16_f32 v32, v32, v33
	v_cvt_pk_bf16_f32 v33, v34, v35
	v_mov_b32_e32 v170, v32
	v_mov_b32_e32 v171, v33
	v_or_b32_e32 v32, 0x60, v140
	v_ashrrev_i32_e32 v33, 31, v32
	v_lshlrev_b64 v[32:33], 11, v[32:33]
	v_cvt_pk_bf16_f32 v28, v28, v29
	v_cvt_pk_bf16_f32 v29, v30, v31
	v_lshl_add_u64 v[30:31], s[68:69], 0, v[32:33]
	v_lshl_add_u64 v[30:31], v[30:31], 0, v[142:143]
	v_cvt_pk_bf16_f32 v16, v16, v17
	v_cvt_pk_bf16_f32 v17, v18, v19
	v_mov_b32_e32 v174, v16
	v_mov_b32_e32 v175, v17
	v_or_b32_e32 v16, 0x70, v140
	v_ashrrev_i32_e32 v17, 31, v16
	v_lshlrev_b64 v[16:17], 11, v[16:17]
	v_cvt_pk_bf16_f32 v12, v12, v13
	v_cvt_pk_bf16_f32 v13, v14, v15
	v_lshl_add_u64 v[14:15], s[68:69], 0, v[16:17]
	v_lshl_add_u64 v[14:15], v[14:15], 0, v[142:143]
	v_cvt_pk_bf16_f32 v4, v4, v5
	v_cvt_pk_bf16_f32 v5, v6, v7
	v_cvt_pk_bf16_f32 v120, v120, v121
	v_cvt_pk_bf16_f32 v121, v122, v123
	v_cvt_pk_bf16_f32 v116, v116, v117
	v_cvt_pk_bf16_f32 v117, v118, v119
	v_cvt_pk_bf16_f32 v104, v104, v105
	v_cvt_pk_bf16_f32 v105, v106, v107
	v_cvt_pk_bf16_f32 v100, v100, v101
	v_cvt_pk_bf16_f32 v101, v102, v103
	v_cvt_pk_bf16_f32 v88, v88, v89
	v_cvt_pk_bf16_f32 v89, v90, v91
	v_cvt_pk_bf16_f32 v84, v84, v85
	v_cvt_pk_bf16_f32 v85, v86, v87
	v_cvt_pk_bf16_f32 v72, v72, v73
	v_cvt_pk_bf16_f32 v73, v74, v75
	v_cvt_pk_bf16_f32 v68, v68, v69
	v_cvt_pk_bf16_f32 v69, v70, v71
	v_cvt_pk_bf16_f32 v56, v56, v57
	v_cvt_pk_bf16_f32 v57, v58, v59
	v_cvt_pk_bf16_f32 v52, v52, v53
	v_cvt_pk_bf16_f32 v53, v54, v55
	v_cvt_pk_bf16_f32 v40, v40, v41
	v_cvt_pk_bf16_f32 v41, v42, v43
	v_cvt_pk_bf16_f32 v36, v36, v37
	v_cvt_pk_bf16_f32 v37, v38, v39
	v_cvt_pk_bf16_f32 v24, v24, v25
	v_cvt_pk_bf16_f32 v25, v26, v27
	v_cvt_pk_bf16_f32 v20, v20, v21
	v_cvt_pk_bf16_f32 v21, v22, v23
	global_store_dwordx2 v[14:15], v[4:5], off offset:32
	v_cvt_pk_bf16_f32 v4, v8, v9
	v_cvt_pk_bf16_f32 v5, v10, v11
	v_cvt_pk_bf16_f32 v0, v0, v1
	v_cvt_pk_bf16_f32 v1, v2, v3
	s_mov_b64 s[38:39], -1
	s_and_b64 vcc, exec, s[26:27]
	global_store_dwordx2 v[126:127], v[124:125], off
	global_store_dwordx2 v[126:127], v[120:121], off offset:32
	v_and_b32_e32 v242, 16, v178
	v_lshrrev_b32_e32 v243, 1, v242
	v_add_u32_e32 v242, v242, v243
	v_mov_b32_e32 v243, 0
	v_mov_b32_e32 v244, v116
	v_mov_b32_e32 v245, v117
	v_lshl_add_u64 v[252:253], v[126:127], 0, v[242:243]
	s_nop 0
	v_permlane16_swap_b32_e32 v244, v246
	v_permlane16_swap_b32_e32 v245, v247
	global_store_dwordx4 v[252:253], v[244:247], off offset:64
	s_nop 1
	v_mov_b32_e32 v244, v108
	v_mov_b32_e32 v245, v109
	v_mov_b32_e32 v246, v104
	v_mov_b32_e32 v247, v105
	v_lshl_add_u64 v[254:255], v[110:111], 0, v[242:243]
	s_nop 0
	v_permlane16_swap_b32_e32 v244, v246
	v_permlane16_swap_b32_e32 v245, v247
	global_store_dwordx4 v[254:255], v[244:247], off
	v_mov_b32_e32 v248, v100
	v_mov_b32_e32 v249, v101
	v_lshl_add_u64 v[252:253], v[110:111], 0, v[242:243]
	s_nop 0
	v_permlane16_swap_b32_e32 v248, v250
	v_permlane16_swap_b32_e32 v249, v251
	global_store_dwordx4 v[252:253], v[248:251], off offset:64
	s_nop 1
	v_mov_b32_e32 v248, v92
	v_mov_b32_e32 v249, v93
	v_mov_b32_e32 v250, v88
	v_mov_b32_e32 v251, v89
	v_lshl_add_u64 v[254:255], v[94:95], 0, v[242:243]
	s_nop 0
	v_permlane16_swap_b32_e32 v248, v250
	v_permlane16_swap_b32_e32 v249, v251
	global_store_dwordx4 v[254:255], v[248:251], off
	v_mov_b32_e32 v156, v84
	v_mov_b32_e32 v157, v85
	v_lshl_add_u64 v[252:253], v[94:95], 0, v[242:243]
	s_nop 0
	v_permlane16_swap_b32_e32 v156, v158
	v_permlane16_swap_b32_e32 v157, v159
	global_store_dwordx4 v[252:253], v[156:159], off offset:64
	s_nop 1
	v_mov_b32_e32 v244, v76
	v_mov_b32_e32 v245, v77
	v_mov_b32_e32 v246, v72
	v_mov_b32_e32 v247, v73
	v_lshl_add_u64 v[254:255], v[78:79], 0, v[242:243]
	s_nop 0
	v_permlane16_swap_b32_e32 v244, v246
	v_permlane16_swap_b32_e32 v245, v247
	global_store_dwordx4 v[254:255], v[244:247], off
	v_mov_b32_e32 v160, v68
	v_mov_b32_e32 v161, v69
	v_lshl_add_u64 v[252:253], v[78:79], 0, v[242:243]
	s_nop 0
	v_permlane16_swap_b32_e32 v160, v162
	v_permlane16_swap_b32_e32 v161, v163
	global_store_dwordx4 v[252:253], v[160:163], off offset:64
	s_nop 1
	v_mov_b32_e32 v156, v60
	v_mov_b32_e32 v157, v61
	v_mov_b32_e32 v158, v56
	v_mov_b32_e32 v159, v57
	v_lshl_add_u64 v[254:255], v[62:63], 0, v[242:243]
	s_nop 0
	v_permlane16_swap_b32_e32 v156, v158
	v_permlane16_swap_b32_e32 v157, v159
	global_store_dwordx4 v[254:255], v[156:159], off
	v_mov_b32_e32 v164, v52
	v_mov_b32_e32 v165, v53
	v_lshl_add_u64 v[252:253], v[62:63], 0, v[242:243]
	s_nop 0
	v_permlane16_swap_b32_e32 v164, v166
	v_permlane16_swap_b32_e32 v165, v167
	global_store_dwordx4 v[252:253], v[164:167], off offset:64
	v_mov_b32_e32 v248, v44
	v_mov_b32_e32 v249, v45
	v_mov_b32_e32 v250, v40
	v_mov_b32_e32 v251, v41
	v_lshl_add_u64 v[254:255], v[46:47], 0, v[242:243]
	s_nop 0
	v_permlane16_swap_b32_e32 v248, v250
	v_permlane16_swap_b32_e32 v249, v251
	global_store_dwordx4 v[254:255], v[248:251], off
	v_mov_b32_e32 v168, v36
	v_mov_b32_e32 v169, v37
	v_lshl_add_u64 v[252:253], v[46:47], 0, v[242:243]
	s_nop 0
	v_permlane16_swap_b32_e32 v168, v170
	v_permlane16_swap_b32_e32 v169, v171
	global_store_dwordx4 v[252:253], v[168:171], off offset:64
	v_mov_b32_e32 v160, v28
	v_mov_b32_e32 v161, v29
	v_mov_b32_e32 v162, v24
	v_mov_b32_e32 v163, v25
	v_lshl_add_u64 v[254:255], v[30:31], 0, v[242:243]
	s_nop 0
	v_permlane16_swap_b32_e32 v160, v162
	v_permlane16_swap_b32_e32 v161, v163
	global_store_dwordx4 v[254:255], v[160:163], off
	v_mov_b32_e32 v172, v20
	v_mov_b32_e32 v173, v21
	v_lshl_add_u64 v[252:253], v[30:31], 0, v[242:243]
	s_nop 0
	v_permlane16_swap_b32_e32 v172, v174
	v_permlane16_swap_b32_e32 v173, v175
	global_store_dwordx4 v[252:253], v[172:175], off offset:64
	global_store_dwordx2 v[14:15], v[12:13], off
	v_mov_b32_e32 v244, v4
	v_mov_b32_e32 v245, v5
	v_mov_b32_e32 v246, v0
	v_mov_b32_e32 v247, v1
	v_lshl_add_u64 v[254:255], v[14:15], 0, v[242:243]
	s_nop 0
	v_permlane16_swap_b32_e32 v244, v246
	v_permlane16_swap_b32_e32 v245, v247
	global_store_dwordx4 v[254:255], v[244:247], off offset:64
	s_cbranch_vccnz .LBB0_1558

.LBB0_2238:
	s_lshl_b32 s15, s2, 7
	s_lshl_b32 s2, s2, 8
	s_add_u32 s18, s10, s2
	s_addc_u32 s19, s11, 0
	s_and_b32 s17, s30, s28
	s_lshl_b32 s30, s14, 11
	s_lshr_b32 s16, s29, 7
	s_addk_i32 s30, 0x2000
	s_lshl_b32 s14, s14, 8
	s_and_b64 s[12:13], exec, s[12:13]
	s_cselect_b32 s12, s14, s30
	s_lshl_b32 s13, s17, 7
	s_add_i32 s12, s12, s13
	v_add_u32_e32 v0, s12, v190
	v_ashrrev_i32_e32 v1, 31, v0
	v_lshlrev_b64 v[152:153], 11, v[0:1]
	v_lshl_add_u64 v[0:1], s[68:69], 0, v[152:153]
	v_lshl_add_u64 v[0:1], v[0:1], 0, s[2:3]
	v_readfirstlane_b32 s14, v183
	v_lshl_add_u64 v[16:17], v[0:1], 0, v[144:145]
	s_lshl_b32 s17, s14, 4
	global_load_dwordx4 v[0:3], v[16:17], off
	global_load_dwordx4 v[4:7], v[16:17], off offset:64
	global_load_dwordx4 v[8:11], v[16:17], off offset:128
	global_load_dwordx4 v[12:15], v[16:17], off offset:192
	v_or_b32_e32 v17, s17, v188
	v_bitop3_b32 v20, v17, v178, 4 bitop3:0x36
	v_bitop3_b32 v25, v17, v178, 8 bitop3:0x36
	v_lshlrev_b32_e32 v20, 3, v20
	v_lshlrev_b32_e32 v25, 3, v25
	v_mul_lo_u32 v21, v17, s29
	v_or_b32_e32 v19, 4, v17
	v_and_b32_e32 v20, 0x78, v20
	s_lshl_b32 s12, s29, 2
	v_or_b32_e32 v23, 8, v17
	v_and_b32_e32 v26, 0x78, v25
	v_lshl_or_b32 v16, v17, 10, v193
	v_lshl_or_b32 v22, v19, 10, v20
	v_add_u32_e32 v19, s12, v21
	v_lshl_or_b32 v28, v23, 10, v26
	v_or_b32_e32 v23, 12, v17
	v_bitop3_b32 v17, v17, v178, 12 bitop3:0x36
	v_or_b32_e32 v24, v20, v19
	v_add_u32_e32 v19, s12, v19
	v_lshlrev_b32_e32 v17, 3, v17
	v_and_b32_e32 v32, 0x78, v17
	v_add_u32_e32 v17, s12, v19
	s_lshl_b32 s12, s14, 12
	v_or_b32_e32 v36, v32, v17
	s_add_i32 s12, s12, 0
	v_ashrrev_i32_e32 v17, 31, v16
	v_lshl_or_b32 v34, v23, 10, v32
	v_lshl_add_u64 v[16:17], v[16:17], 1, s[18:19]
	s_mov_b32 m0, s12
	v_ashrrev_i32_e32 v23, 31, v22
	global_load_lds_dwordx4 v[16:17], off
	v_lshl_add_u64 v[16:17], v[22:23], 1, s[18:19]
	s_add_i32 m0, s12, 0x400
	v_ashrrev_i32_e32 v29, 31, v28
	v_or_b32_e32 v18, v21, v193
	global_load_lds_dwordx4 v[16:17], off
	v_lshl_add_u64 v[16:17], v[28:29], 1, s[18:19]
	s_add_i32 m0, s12, 0x800
	v_ashrrev_i32_e32 v35, 31, v34
	v_or_b32_e32 v30, v26, v19
	global_load_lds_dwordx4 v[16:17], off
	v_lshl_add_u64 v[16:17], v[34:35], 1, s[18:19]
	s_add_i32 m0, s12, 0xc00
	v_ashrrev_i32_e32 v19, 31, v18
	global_load_lds_dwordx4 v[16:17], off
	s_add_i32 m0, s12, 0x8000
	v_lshl_add_u64 v[16:17], v[18:19], 1, s[0:1]
	v_ashrrev_i32_e32 v25, 31, v24
	global_load_lds_dwordx4 v[16:17], off
	v_lshl_add_u64 v[16:17], v[24:25], 1, s[0:1]
	s_add_i32 m0, s12, 0x8400
	v_ashrrev_i32_e32 v31, 31, v30
	global_load_lds_dwordx4 v[16:17], off
	v_lshl_add_u64 v[16:17], v[30:31], 1, s[0:1]
	s_add_i32 m0, s12, 0x8800
	v_ashrrev_i32_e32 v37, 31, v36
	global_load_lds_dwordx4 v[16:17], off
	v_lshl_add_u64 v[16:17], v[36:37], 1, s[0:1]
	s_add_i32 m0, s12, 0x8c00
	s_add_u32 s0, s0, 0x100
	global_load_lds_dwordx4 v[16:17], off
	v_add_u32_e32 v16, v193, v21
	s_addc_u32 s1, s1, 0
	v_ashrrev_i32_e32 v17, 31, v16
	v_lshl_add_u64 v[154:155], v[16:17], 1, s[0:1]
	v_or_b32_e32 v16, s17, v205
	v_mad_u64_u32 v[16:17], s[18:19], s29, v16, v[20:21]
	v_ashrrev_i32_e32 v17, 31, v16
	v_lshl_add_u64 v[156:157], v[16:17], 1, s[0:1]
	v_or_b32_e32 v16, s17, v206
	v_mad_u64_u32 v[16:17], s[18:19], s29, v16, v[26:27]
	v_ashrrev_i32_e32 v17, 31, v16
	v_lshl_add_u64 v[158:159], v[16:17], 1, s[0:1]
	v_or_b32_e32 v16, s17, v207
	v_mad_u64_u32 v[16:17], s[18:19], s29, v16, v[32:33]
	v_ashrrev_i32_e32 v17, 31, v16
	s_lshl_b32 s14, s14, 14
	v_lshl_add_u64 v[160:161], v[16:17], 1, s[0:1]
	s_add_u32 s0, s10, s2
	s_addc_u32 s1, s11, 0
	v_or_b32_e32 v16, s14, v208
	s_add_u32 s0, s0, 0x40000
	v_ashrrev_i32_e32 v17, 31, v16
	s_addc_u32 s1, s1, 0
	v_lshl_add_u64 v[162:163], v[16:17], 1, s[0:1]
	v_or_b32_e32 v16, s14, v209
	v_add_u32_e32 v16, v16, v20
	v_ashrrev_i32_e32 v17, 31, v16
	v_lshl_add_u64 v[164:165], v[16:17], 1, s[0:1]
	v_or_b32_e32 v16, s14, v210
	v_add_u32_e32 v16, v16, v26
	v_ashrrev_i32_e32 v17, 31, v16
	v_lshl_add_u64 v[166:167], v[16:17], 1, s[0:1]
	v_or_b32_e32 v16, s14, v211
	v_add_u32_e32 v16, v16, v32
	s_waitcnt vmcnt(0)
	v_ashrrev_i32_e32 v17, 31, v16
	v_mov_b32_e32 v72, v145
	v_mov_b32_e32 v73, v145
	v_mov_b32_e32 v74, v145
	v_mov_b32_e32 v75, v145
	v_lshl_add_u64 v[168:169], v[16:17], 1, s[0:1]
	s_lshl_b32 s0, s29, 11
	v_mov_b32_e32 v151, v150
	v_mov_b64_e32 v[16:17], v[72:73]
	v_mov_b64_e32 v[24:25], v[72:73]
	v_mov_b64_e32 v[32:33], v[72:73]
	v_mov_b64_e32 v[40:41], v[72:73]
	v_mov_b64_e32 v[48:49], v[72:73]
	v_mov_b64_e32 v[56:57], v[72:73]
	v_mov_b64_e32 v[64:65], v[72:73]
	v_mov_b64_e32 v[78:79], v[74:75]
	v_mov_b64_e32 v[20:21], v[72:73]
	v_mov_b64_e32 v[28:29], v[72:73]
	v_mov_b64_e32 v[36:37], v[72:73]
	v_mov_b64_e32 v[44:45], v[72:73]
	v_mov_b64_e32 v[52:53], v[72:73]
	v_mov_b64_e32 v[60:61], v[72:73]
	v_mov_b64_e32 v[68:69], v[72:73]
	s_mov_b32 s13, 1
	s_and_b32 s2, s0, 0x7c0000
	v_mov_b32_e32 v174, v145
	v_mov_b32_e32 v175, v145
	s_mov_b32 s14, 0
	s_mov_b64 s[10:11], 0
	v_mov_b64_e32 v[18:19], v[74:75]
	v_mov_b64_e32 v[26:27], v[74:75]
	v_mov_b64_e32 v[34:35], v[74:75]
	v_mov_b64_e32 v[42:43], v[74:75]
	v_mov_b64_e32 v[50:51], v[74:75]
	v_mov_b64_e32 v[58:59], v[74:75]
	v_mov_b64_e32 v[66:67], v[74:75]
	v_mov_b64_e32 v[76:77], v[72:73]
	v_mov_b64_e32 v[22:23], v[74:75]
	v_mov_b64_e32 v[30:31], v[74:75]
	v_mov_b64_e32 v[38:39], v[74:75]
	v_mov_b64_e32 v[46:47], v[74:75]
	v_mov_b64_e32 v[54:55], v[74:75]
	v_mov_b64_e32 v[62:63], v[74:75]
	v_mov_b64_e32 v[70:71], v[74:75]
	v_mov_b64_e32 v[170:171], v[150:151]
	v_mov_b32_e32 v244, 0
	v_mov_b32_e32 v245, 0
	v_mov_b32_e32 v246, 0
	v_mov_b32_e32 v247, 0
	v_mov_b32_e32 v248, 0
	v_mov_b32_e32 v249, 0
	v_mov_b32_e32 v250, 0
	v_mov_b32_e32 v251, 0
	s_waitcnt vmcnt(0) lgkmcnt(0)
	s_barrier
	s_branch .LBB0_2241
.LBB0_2239:
	v_sub_f32_e32 v56, v56, v244
	v_sub_f32_e32 v57, v57, v248
	v_sub_f32_e32 v172, v172, v244
	v_sub_f32_e32 v173, v173, v248
	ds_bpermute_b32 v58, v187, v56
	ds_bpermute_b32 v59, v187, v57
	v_max_f32_e32 v56, v56, v56
	v_max_f32_e32 v57, v57, v57
	s_waitcnt lgkmcnt(1)
	v_max_f32_e32 v58, v58, v58
	s_waitcnt lgkmcnt(0)
	v_max_f32_e32 v59, v59, v59
	v_max_f32_e32 v56, v56, v58
	v_max_f32_e32 v57, v57, v59
	ds_bpermute_b32 v58, v186, v56
	ds_bpermute_b32 v59, v186, v57
	s_waitcnt lgkmcnt(1)
	v_max_f32_e32 v58, v58, v58
	s_waitcnt lgkmcnt(0)
	v_max_f32_e32 v59, v59, v59
	v_max_f32_e32 v56, v56, v58
	v_max_f32_e32 v57, v57, v59
	v_add_f32_e32 v58, 0x41000000, v171
	v_cmp_gt_f32_e32 vcc, v57, v58
	s_nop 1
	v_cndmask_b32_e32 v57, v175, v57, vcc
	v_cmp_gt_f32_e32 vcc, v56, v172
	s_nop 1
	v_cndmask_b32_e32 v56, v174, v56, vcc
	v_pk_add_f32 v[58:59], v[174:175], v[56:57] neg_lo:[0,1] neg_hi:[0,1]
	v_mov_b64_e32 v[170:171], v[56:57]
	v_exp_f32_e32 v58, v58
	v_exp_f32_e32 v60, v59
	v_mov_b32_e32 v61, v58
	v_pk_mul_f32 v[134:135], v[134:135], v[58:59] op_sel_hi:[1,0]
	v_pk_mul_f32 v[132:133], v[132:133], v[58:59] op_sel_hi:[1,0]
	v_pk_mul_f32 v[126:127], v[126:127], v[58:59] op_sel_hi:[1,0]
	v_pk_mul_f32 v[124:125], v[124:125], v[58:59] op_sel_hi:[1,0]
	v_pk_mul_f32 v[118:119], v[118:119], v[58:59] op_sel_hi:[1,0]
	v_pk_mul_f32 v[116:117], v[116:117], v[58:59] op_sel_hi:[1,0]
	v_pk_mul_f32 v[110:111], v[110:111], v[58:59] op_sel_hi:[1,0]
	v_pk_mul_f32 v[108:109], v[108:109], v[58:59] op_sel_hi:[1,0]
	v_pk_mul_f32 v[102:103], v[102:103], v[58:59] op_sel_hi:[1,0]
	v_pk_mul_f32 v[100:101], v[100:101], v[58:59] op_sel_hi:[1,0]
	v_pk_mul_f32 v[94:95], v[94:95], v[58:59] op_sel_hi:[1,0]
	v_pk_mul_f32 v[92:93], v[92:93], v[58:59] op_sel_hi:[1,0]
	v_pk_mul_f32 v[86:87], v[86:87], v[58:59] op_sel_hi:[1,0]
	v_pk_mul_f32 v[84:85], v[84:85], v[58:59] op_sel_hi:[1,0]
	v_pk_mul_f32 v[74:75], v[74:75], v[58:59] op_sel_hi:[1,0]
	v_pk_mul_f32 v[72:73], v[72:73], v[58:59] op_sel_hi:[1,0]
	v_pk_mul_f32 v[176:177], v[176:177], v[60:61]
	v_pk_mul_f32 v[130:131], v[130:131], v[60:61] op_sel_hi:[1,0]
	v_pk_mul_f32 v[128:129], v[128:129], v[60:61] op_sel_hi:[1,0]
	v_pk_mul_f32 v[122:123], v[122:123], v[60:61] op_sel_hi:[1,0]
	v_pk_mul_f32 v[120:121], v[120:121], v[60:61] op_sel_hi:[1,0]
	v_pk_mul_f32 v[114:115], v[114:115], v[60:61] op_sel_hi:[1,0]
	v_pk_mul_f32 v[112:113], v[112:113], v[60:61] op_sel_hi:[1,0]
	v_pk_mul_f32 v[106:107], v[106:107], v[60:61] op_sel_hi:[1,0]
	v_pk_mul_f32 v[104:105], v[104:105], v[60:61] op_sel_hi:[1,0]
	v_pk_mul_f32 v[98:99], v[98:99], v[60:61] op_sel_hi:[1,0]
	v_pk_mul_f32 v[96:97], v[96:97], v[60:61] op_sel_hi:[1,0]
	v_pk_mul_f32 v[90:91], v[90:91], v[60:61] op_sel_hi:[1,0]
	v_pk_mul_f32 v[88:89], v[88:89], v[60:61] op_sel_hi:[1,0]
	v_pk_mul_f32 v[82:83], v[82:83], v[60:61] op_sel_hi:[1,0]
	v_pk_mul_f32 v[80:81], v[80:81], v[60:61] op_sel_hi:[1,0]
	v_pk_mul_f32 v[78:79], v[78:79], v[60:61] op_sel_hi:[1,0]
	v_pk_mul_f32 v[76:77], v[76:77], v[60:61] op_sel_hi:[1,0]
	v_add_f32_e32 v242, v56, v244
	v_add_f32_e32 v243, v57, v248
	v_sub_f32_e32 v40, v40, v243
	v_sub_f32_e32 v41, v41, v243
	v_sub_f32_e32 v42, v42, v243
	v_sub_f32_e32 v43, v43, v243
	v_sub_f32_e32 v44, v44, v243
	v_sub_f32_e32 v45, v45, v243
	v_sub_f32_e32 v46, v46, v243
	v_sub_f32_e32 v47, v47, v243
	v_sub_f32_e32 v48, v48, v242
	v_sub_f32_e32 v49, v49, v242
	v_sub_f32_e32 v50, v50, v242
	v_sub_f32_e32 v51, v51, v242
	v_sub_f32_e32 v52, v52, v242
	v_sub_f32_e32 v53, v53, v242
	v_sub_f32_e32 v54, v54, v242
	v_sub_f32_e32 v55, v55, v242
	v_sub_f32_e32 v244, 0, v56
	v_sub_f32_e32 v245, 0, v56
	v_sub_f32_e32 v246, 0, v56
	v_sub_f32_e32 v247, 0, v56
	v_sub_f32_e32 v248, 0, v57
	v_sub_f32_e32 v249, 0, v57
	v_sub_f32_e32 v250, 0, v57
	v_sub_f32_e32 v251, 0, v57
	v_mov_b32_e32 v172, 0x41000000
	v_mov_b32_e32 v173, 0x41000000

.LBB0_2243:
	s_and_b32 s0, s14, 0x10000
	s_add_i32 s17, s0, 0
	v_add_u32_e32 v88, s17, v191
	v_add_u32_e32 v149, v88, v194
	v_add_u32_e32 v151, v88, v195
	v_add_u32_e32 v213, v88, v196
	v_add_u32_e32 v214, v88, v197
	v_add_u32_e32 v88, s17, v192
	v_add_u32_e32 v89, s17, v198
	ds_read_b128 v[80:83], v149
	ds_read_b128 v[84:87], v149 offset:4096
	ds_read_b128 v[120:123], v151
	ds_read_b128 v[128:131], v151 offset:4096
	ds_read_b128 v[132:135], v213
	ds_read_b128 v[136:139], v213 offset:4096
	ds_read_b128 v[140:143], v214
	ds_read_b128 v[216:219], v214 offset:4096
	ds_read_b64 v[116:117], v88 offset:32768
	ds_read_b64 v[118:119], v89 offset:32768
	ds_read_b64 v[112:113], v88 offset:36864
	ds_read_b64 v[114:115], v89 offset:36864
	ds_read_b64 v[108:109], v88 offset:40960
	ds_read_b64 v[110:111], v89 offset:40960
	ds_read_b64 v[104:105], v88 offset:45056
	ds_read_b64 v[106:107], v89 offset:45056
	ds_read_b64 v[100:101], v88 offset:49152
	ds_read_b64 v[102:103], v89 offset:49152
	ds_read_b64 v[96:97], v88 offset:53248
	ds_read_b64 v[98:99], v89 offset:53248
	ds_read_b64 v[92:93], v88 offset:57344
	ds_read_b64 v[94:95], v89 offset:57344
	ds_read_b64 v[90:91], v89 offset:61440
	ds_read_b64 v[88:89], v88 offset:61440
	s_waitcnt lgkmcnt(0)
	v_mfma_f32_16x16x32_bf16 v[80:83], v[80:83], v[0:3], v[244:247]
	v_mfma_f32_16x16x32_bf16 v[124:127], v[120:123], v[4:7], v[80:83]
	v_mfma_f32_16x16x32_bf16 v[80:83], v[84:87], v[0:3], v[244:247]
	v_mfma_f32_16x16x32_bf16 v[120:123], v[128:131], v[4:7], v[80:83]
	v_mfma_f32_16x16x32_bf16 v[80:83], v[132:135], v[8:11], v[248:251]
	v_mfma_f32_16x16x32_bf16 v[84:87], v[140:143], v[12:15], v[80:83]
	v_mfma_f32_16x16x32_bf16 v[80:83], v[136:139], v[8:11], v[248:251]
	v_mfma_f32_16x16x32_bf16 v[80:83], v[216:219], v[12:15], v[80:83]
	s_nop 1
	v_max3_f32 v128, v124, v125, v126
	s_nop 0
	v_max3_f32 v128, v128, v127, v120
	v_max3_f32 v128, v128, v121, v122
	v_max_f32_e32 v128, v128, v123
	v_max3_f32 v129, v84, v85, v86
	v_max3_f32 v129, v129, v87, v80
	v_max3_f32 v129, v129, v81, v82
	v_max_f32_e32 v129, v129, v83
	v_pk_add_f32 v[172:173], v[170:171], s[8:9] op_sel_hi:[1,0]
	v_add_f32_e32 v172, v172, v244
	v_add_f32_e32 v173, v173, v248
	s_nop 0
	v_cmp_gt_f32_e32 vcc, v128, v172
	v_cmp_gt_f32_e64 s[0:1], v129, v173
	s_or_b64 vcc, vcc, s[0:1]
	s_cbranch_vccz .LBB0_2245
	v_sub_f32_e32 v128, v128, v244
	v_sub_f32_e32 v129, v129, v248
	v_sub_f32_e32 v172, v172, v244
	v_sub_f32_e32 v173, v173, v248
	ds_bpermute_b32 v131, v187, v129
	ds_bpermute_b32 v130, v187, v128
	v_max_f32_e32 v129, v129, v129
	v_max_f32_e32 v128, v128, v128
	s_waitcnt lgkmcnt(1)
	v_max_f32_e32 v131, v131, v131
	s_waitcnt lgkmcnt(0)
	v_max_f32_e32 v130, v130, v130
	v_max_f32_e32 v129, v129, v131
	v_max_f32_e32 v128, v128, v130
	ds_bpermute_b32 v131, v186, v129
	ds_bpermute_b32 v130, v186, v128
	s_waitcnt lgkmcnt(1)
	v_max_f32_e32 v131, v131, v131
	s_waitcnt lgkmcnt(0)
	v_max_f32_e32 v130, v130, v130
	v_max_f32_e32 v129, v129, v131
	v_max_f32_e32 v128, v128, v130
	v_cmp_gt_f32_e32 vcc, v129, v173
	s_nop 1
	v_cndmask_b32_e32 v129, v171, v129, vcc
	v_cmp_gt_f32_e32 vcc, v128, v172
	s_nop 1
	v_cndmask_b32_e32 v128, v170, v128, vcc
	v_pk_add_f32 v[130:131], v[170:171], v[128:129] neg_lo:[0,1] neg_hi:[0,1]
	v_pk_add_f32 v[172:173], v[128:129], s[8:9] op_sel_hi:[1,0]
	v_exp_f32_e32 v130, v130
	v_exp_f32_e32 v132, v131
	v_mov_b64_e32 v[170:171], v[128:129]
	v_mov_b32_e32 v133, v130
	v_pk_mul_f32 v[66:67], v[66:67], v[130:131] op_sel_hi:[1,0]
	v_pk_mul_f32 v[64:65], v[64:65], v[130:131] op_sel_hi:[1,0]
	v_pk_mul_f32 v[58:59], v[58:59], v[130:131] op_sel_hi:[1,0]
	v_pk_mul_f32 v[56:57], v[56:57], v[130:131] op_sel_hi:[1,0]
	v_pk_mul_f32 v[50:51], v[50:51], v[130:131] op_sel_hi:[1,0]
	v_pk_mul_f32 v[48:49], v[48:49], v[130:131] op_sel_hi:[1,0]
	v_pk_mul_f32 v[42:43], v[42:43], v[130:131] op_sel_hi:[1,0]
	v_pk_mul_f32 v[40:41], v[40:41], v[130:131] op_sel_hi:[1,0]
	v_pk_mul_f32 v[34:35], v[34:35], v[130:131] op_sel_hi:[1,0]
	v_pk_mul_f32 v[32:33], v[32:33], v[130:131] op_sel_hi:[1,0]
	v_pk_mul_f32 v[26:27], v[26:27], v[130:131] op_sel_hi:[1,0]
	v_pk_mul_f32 v[24:25], v[24:25], v[130:131] op_sel_hi:[1,0]
	v_pk_mul_f32 v[18:19], v[18:19], v[130:131] op_sel_hi:[1,0]
	v_pk_mul_f32 v[16:17], v[16:17], v[130:131] op_sel_hi:[1,0]
	v_pk_mul_f32 v[74:75], v[74:75], v[130:131] op_sel_hi:[1,0]
	v_pk_mul_f32 v[72:73], v[72:73], v[130:131] op_sel_hi:[1,0]
	v_pk_mul_f32 v[174:175], v[174:175], v[132:133]
	v_pk_mul_f32 v[70:71], v[70:71], v[132:133] op_sel_hi:[1,0]
	v_pk_mul_f32 v[68:69], v[68:69], v[132:133] op_sel_hi:[1,0]
	v_pk_mul_f32 v[62:63], v[62:63], v[132:133] op_sel_hi:[1,0]
	v_pk_mul_f32 v[60:61], v[60:61], v[132:133] op_sel_hi:[1,0]
	v_pk_mul_f32 v[54:55], v[54:55], v[132:133] op_sel_hi:[1,0]
	v_pk_mul_f32 v[52:53], v[52:53], v[132:133] op_sel_hi:[1,0]
	v_pk_mul_f32 v[46:47], v[46:47], v[132:133] op_sel_hi:[1,0]
	v_pk_mul_f32 v[44:45], v[44:45], v[132:133] op_sel_hi:[1,0]
	v_pk_mul_f32 v[38:39], v[38:39], v[132:133] op_sel_hi:[1,0]
	v_pk_mul_f32 v[36:37], v[36:37], v[132:133] op_sel_hi:[1,0]
	v_pk_mul_f32 v[30:31], v[30:31], v[132:133] op_sel_hi:[1,0]
	v_pk_mul_f32 v[28:29], v[28:29], v[132:133] op_sel_hi:[1,0]
	v_pk_mul_f32 v[22:23], v[22:23], v[132:133] op_sel_hi:[1,0]
	v_pk_mul_f32 v[20:21], v[20:21], v[132:133] op_sel_hi:[1,0]
	v_pk_mul_f32 v[78:79], v[78:79], v[132:133] op_sel_hi:[1,0]
	v_pk_mul_f32 v[76:77], v[76:77], v[132:133] op_sel_hi:[1,0]
	v_add_f32_e32 v242, v170, v244
	v_add_f32_e32 v243, v171, v248
	v_sub_f32_e32 v80, v80, v243
	v_sub_f32_e32 v81, v81, v243
	v_sub_f32_e32 v82, v82, v243
	v_sub_f32_e32 v83, v83, v243
	v_sub_f32_e32 v84, v84, v243
	v_sub_f32_e32 v85, v85, v243
	v_sub_f32_e32 v86, v86, v243
	v_sub_f32_e32 v87, v87, v243
	v_sub_f32_e32 v120, v120, v242
	v_sub_f32_e32 v121, v121, v242
	v_sub_f32_e32 v122, v122, v242
	v_sub_f32_e32 v123, v123, v242
	v_sub_f32_e32 v124, v124, v242
	v_sub_f32_e32 v125, v125, v242
	v_sub_f32_e32 v126, v126, v242
	v_sub_f32_e32 v127, v127, v242
	v_sub_f32_e32 v244, 0, v170
	v_sub_f32_e32 v245, 0, v170
	v_sub_f32_e32 v246, 0, v170
	v_sub_f32_e32 v247, 0, v170
	v_sub_f32_e32 v248, 0, v171
	v_sub_f32_e32 v249, 0, v171
	v_sub_f32_e32 v250, 0, v171
	v_sub_f32_e32 v251, 0, v171
	v_mov_b32_e32 v172, 0x41000000
	v_mov_b32_e32 v173, 0x41000000
.LBB0_2245:
	v_exp_f32_e32 v129, v124
	v_exp_f32_e32 v128, v84
	v_exp_f32_e32 v131, v125
	v_exp_f32_e32 v130, v85
	v_exp_f32_e32 v133, v126
	v_exp_f32_e32 v132, v86
	v_exp_f32_e32 v135, v127
	v_exp_f32_e32 v134, v87
	v_exp_f32_e32 v137, v120
	v_exp_f32_e32 v136, v80
	v_pk_add_f32 v[84:85], v[128:129], 0 op_sel_hi:[1,0]
	v_exp_f32_e32 v139, v121
	v_pk_add_f32 v[84:85], v[130:131], v[84:85]
	v_exp_f32_e32 v138, v81
	v_exp_f32_e32 v141, v122
	v_pk_add_f32 v[84:85], v[132:133], v[84:85]
	v_exp_f32_e32 v140, v82
	v_exp_f32_e32 v143, v123
	v_pk_add_f32 v[84:85], v[134:135], v[84:85]
	v_exp_f32_e32 v142, v83
	v_pk_add_f32 v[80:81], v[136:137], v[84:85]
	v_cvt_pk_bf16_f32 v124, v129, v131
	v_pk_add_f32 v[80:81], v[138:139], v[80:81]
	v_cvt_pk_bf16_f32 v125, v133, v135
	v_pk_add_f32 v[80:81], v[140:141], v[80:81]
	v_cvt_pk_bf16_f32 v126, v137, v139
	v_pk_add_f32 v[80:81], v[142:143], v[80:81]
	v_cvt_pk_bf16_f32 v127, v141, v143
	v_cvt_pk_bf16_f32 v120, v128, v130
	v_cvt_pk_bf16_f32 v121, v132, v134
	v_cvt_pk_bf16_f32 v122, v136, v138
	v_cvt_pk_bf16_f32 v123, v140, v142
	v_pk_add_f32 v[128:129], v[174:175], v[80:81]
	s_setprio 1
	s_waitcnt lgkmcnt(0)
	s_nop 1
	v_mfma_f32_16x16x32_bf16 v[80:83], v[116:119], v[124:127], v[64:67]
	v_mfma_f32_16x16x32_bf16 v[84:87], v[116:119], v[120:123], v[68:71]
	v_mfma_f32_16x16x32_bf16 v[68:71], v[112:115], v[120:123], v[60:63]
	v_mfma_f32_16x16x32_bf16 v[64:67], v[112:115], v[124:127], v[56:59]
	v_mfma_f32_16x16x32_bf16 v[56:59], v[108:111], v[124:127], v[48:51]
	v_mfma_f32_16x16x32_bf16 v[60:63], v[108:111], v[120:123], v[52:55]
	v_mfma_f32_16x16x32_bf16 v[52:55], v[104:107], v[120:123], v[44:47]
	v_mfma_f32_16x16x32_bf16 v[48:51], v[104:107], v[124:127], v[40:43]
	v_mfma_f32_16x16x32_bf16 v[40:43], v[100:103], v[124:127], v[32:35]
	v_mfma_f32_16x16x32_bf16 v[44:47], v[100:103], v[120:123], v[36:39]
	v_mfma_f32_16x16x32_bf16 v[36:39], v[96:99], v[120:123], v[28:31]
	v_mfma_f32_16x16x32_bf16 v[32:35], v[96:99], v[124:127], v[24:27]
	v_mfma_f32_16x16x32_bf16 v[24:27], v[92:95], v[124:127], v[16:19]
	v_mfma_f32_16x16x32_bf16 v[28:31], v[92:95], v[120:123], v[20:23]
	v_mfma_f32_16x16x32_bf16 v[16:19], v[88:91], v[124:127], v[72:75]
	v_mfma_f32_16x16x32_bf16 v[20:23], v[88:91], v[120:123], v[76:79]
	s_setprio 0
	s_nop 0
	ds_read_b128 v[72:75], v149 offset:8192
	ds_read_b128 v[76:79], v149 offset:12288
	ds_read_b128 v[120:123], v151 offset:8192
	ds_read_b128 v[130:133], v151 offset:12288
	ds_read_b128 v[134:137], v213 offset:8192
	ds_read_b128 v[138:141], v213 offset:12288
	ds_read_b128 v[174:177], v214 offset:8192
	ds_read_b128 v[216:219], v214 offset:12288
	v_add_u32_e32 v88, s17, v199
	v_add_u32_e32 v89, s17, v200
	ds_read_b64 v[116:117], v88 offset:32768
	ds_read_b64 v[118:119], v89 offset:32768
	ds_read_b64 v[112:113], v88 offset:36864
	ds_read_b64 v[114:115], v89 offset:36864
	ds_read_b64 v[108:109], v88 offset:40960
	ds_read_b64 v[110:111], v89 offset:40960
	ds_read_b64 v[104:105], v88 offset:45056
	ds_read_b64 v[106:107], v89 offset:45056
	ds_read_b64 v[100:101], v88 offset:49152
	ds_read_b64 v[102:103], v89 offset:49152
	ds_read_b64 v[96:97], v88 offset:53248
	ds_read_b64 v[98:99], v89 offset:53248
	ds_read_b64 v[92:93], v88 offset:57344
	ds_read_b64 v[94:95], v89 offset:57344
	ds_read_b64 v[90:91], v89 offset:61440
	ds_read_b64 v[88:89], v88 offset:61440
	s_waitcnt lgkmcnt(14)
	v_mfma_f32_16x16x32_bf16 v[72:75], v[72:75], v[0:3], v[244:247]
	s_waitcnt lgkmcnt(13)
	v_mfma_f32_16x16x32_bf16 v[124:127], v[120:123], v[4:7], v[72:75]
	v_mfma_f32_16x16x32_bf16 v[72:75], v[76:79], v[0:3], v[244:247]
	s_waitcnt lgkmcnt(12)
	v_mfma_f32_16x16x32_bf16 v[120:123], v[130:133], v[4:7], v[72:75]
	s_waitcnt lgkmcnt(11)
	v_mfma_f32_16x16x32_bf16 v[72:75], v[134:137], v[8:11], v[248:251]
	s_waitcnt lgkmcnt(9)
	v_mfma_f32_16x16x32_bf16 v[76:79], v[174:177], v[12:15], v[72:75]
	v_mfma_f32_16x16x32_bf16 v[72:75], v[138:141], v[8:11], v[248:251]
	s_waitcnt lgkmcnt(8)
	v_mfma_f32_16x16x32_bf16 v[72:75], v[216:219], v[12:15], v[72:75]
	v_max3_f32 v130, v124, v125, v126
	v_max3_f32 v130, v130, v127, v120
	v_max3_f32 v130, v130, v121, v122
	v_max_f32_e32 v130, v130, v123
	s_nop 0
	v_max3_f32 v131, v76, v77, v78
	s_nop 1
	v_max3_f32 v131, v131, v79, v72
	v_max3_f32 v131, v131, v73, v74
	v_max_f32_e32 v131, v131, v75
	v_cmp_gt_f32_e32 vcc, v130, v172
	v_cmp_gt_f32_e64 s[0:1], v131, v173
	s_or_b64 vcc, vcc, s[0:1]
	s_cbranch_vccz .LBB0_2247
	v_sub_f32_e32 v130, v130, v244
	v_sub_f32_e32 v131, v131, v248
	v_sub_f32_e32 v172, v172, v244
	v_sub_f32_e32 v173, v173, v248
	ds_bpermute_b32 v132, v187, v130
	ds_bpermute_b32 v133, v187, v131
	v_max_f32_e32 v130, v130, v130
	v_max_f32_e32 v131, v131, v131
	s_waitcnt lgkmcnt(1)
	v_max_f32_e32 v132, v132, v132
	s_waitcnt lgkmcnt(0)
	v_max_f32_e32 v133, v133, v133
	v_max_f32_e32 v130, v130, v132
	v_max_f32_e32 v131, v131, v133
	ds_bpermute_b32 v132, v186, v130
	ds_bpermute_b32 v133, v186, v131
	s_waitcnt lgkmcnt(1)
	v_max_f32_e32 v132, v132, v132
	s_waitcnt lgkmcnt(0)
	v_max_f32_e32 v133, v133, v133
	v_max_f32_e32 v130, v130, v132
	v_max_f32_e32 v131, v131, v133
	v_add_f32_e32 v132, 0x41000000, v171
	v_cmp_gt_f32_e32 vcc, v131, v132
	s_nop 1
	v_cndmask_b32_e32 v175, v171, v131, vcc
	v_cmp_gt_f32_e32 vcc, v130, v172
	s_nop 1
	v_cndmask_b32_e32 v174, v170, v130, vcc
	v_pk_add_f32 v[130:131], v[170:171], v[174:175] neg_lo:[0,1] neg_hi:[0,1]
	v_pk_add_f32 v[172:173], v[174:175], s[8:9] op_sel_hi:[1,0]
	v_exp_f32_e32 v130, v130
	v_exp_f32_e32 v132, v131
	v_mov_b32_e32 v171, v175
	v_mov_b32_e32 v170, v174
	v_mov_b32_e32 v133, v130
	v_pk_mul_f32 v[82:83], v[82:83], v[130:131] op_sel_hi:[1,0]
	v_pk_mul_f32 v[80:81], v[80:81], v[130:131] op_sel_hi:[1,0]
	v_pk_mul_f32 v[66:67], v[66:67], v[130:131] op_sel_hi:[1,0]
	v_pk_mul_f32 v[64:65], v[64:65], v[130:131] op_sel_hi:[1,0]
	v_pk_mul_f32 v[58:59], v[58:59], v[130:131] op_sel_hi:[1,0]
	v_pk_mul_f32 v[56:57], v[56:57], v[130:131] op_sel_hi:[1,0]
	v_pk_mul_f32 v[50:51], v[50:51], v[130:131] op_sel_hi:[1,0]
	v_pk_mul_f32 v[48:49], v[48:49], v[130:131] op_sel_hi:[1,0]
	v_pk_mul_f32 v[42:43], v[42:43], v[130:131] op_sel_hi:[1,0]
	v_pk_mul_f32 v[40:41], v[40:41], v[130:131] op_sel_hi:[1,0]
	v_pk_mul_f32 v[34:35], v[34:35], v[130:131] op_sel_hi:[1,0]
	v_pk_mul_f32 v[32:33], v[32:33], v[130:131] op_sel_hi:[1,0]
	v_pk_mul_f32 v[26:27], v[26:27], v[130:131] op_sel_hi:[1,0]
	v_pk_mul_f32 v[24:25], v[24:25], v[130:131] op_sel_hi:[1,0]
	v_pk_mul_f32 v[18:19], v[18:19], v[130:131] op_sel_hi:[1,0]
	v_pk_mul_f32 v[16:17], v[16:17], v[130:131] op_sel_hi:[1,0]
	v_pk_mul_f32 v[128:129], v[128:129], v[132:133]
	v_pk_mul_f32 v[86:87], v[86:87], v[132:133] op_sel_hi:[1,0]
	v_pk_mul_f32 v[84:85], v[84:85], v[132:133] op_sel_hi:[1,0]
	v_pk_mul_f32 v[70:71], v[70:71], v[132:133] op_sel_hi:[1,0]
	v_pk_mul_f32 v[68:69], v[68:69], v[132:133] op_sel_hi:[1,0]
	v_pk_mul_f32 v[62:63], v[62:63], v[132:133] op_sel_hi:[1,0]
	v_pk_mul_f32 v[60:61], v[60:61], v[132:133] op_sel_hi:[1,0]
	v_pk_mul_f32 v[54:55], v[54:55], v[132:133] op_sel_hi:[1,0]
	v_pk_mul_f32 v[52:53], v[52:53], v[132:133] op_sel_hi:[1,0]
	v_pk_mul_f32 v[46:47], v[46:47], v[132:133] op_sel_hi:[1,0]
	v_pk_mul_f32 v[44:45], v[44:45], v[132:133] op_sel_hi:[1,0]
	v_pk_mul_f32 v[38:39], v[38:39], v[132:133] op_sel_hi:[1,0]
	v_pk_mul_f32 v[36:37], v[36:37], v[132:133] op_sel_hi:[1,0]
	v_pk_mul_f32 v[30:31], v[30:31], v[132:133] op_sel_hi:[1,0]
	v_pk_mul_f32 v[28:29], v[28:29], v[132:133] op_sel_hi:[1,0]
	v_pk_mul_f32 v[22:23], v[22:23], v[132:133] op_sel_hi:[1,0]
	v_pk_mul_f32 v[20:21], v[20:21], v[132:133] op_sel_hi:[1,0]
	v_add_f32_e32 v242, v170, v244
	v_add_f32_e32 v243, v171, v248
	v_sub_f32_e32 v72, v72, v243
	v_sub_f32_e32 v73, v73, v243
	v_sub_f32_e32 v74, v74, v243
	v_sub_f32_e32 v75, v75, v243
	v_sub_f32_e32 v76, v76, v243
	v_sub_f32_e32 v77, v77, v243
	v_sub_f32_e32 v78, v78, v243
	v_sub_f32_e32 v79, v79, v243
	v_sub_f32_e32 v120, v120, v242
	v_sub_f32_e32 v121, v121, v242
	v_sub_f32_e32 v122, v122, v242
	v_sub_f32_e32 v123, v123, v242
	v_sub_f32_e32 v124, v124, v242
	v_sub_f32_e32 v125, v125, v242
	v_sub_f32_e32 v126, v126, v242
	v_sub_f32_e32 v127, v127, v242
	v_sub_f32_e32 v244, 0, v170
	v_sub_f32_e32 v245, 0, v170
	v_sub_f32_e32 v246, 0, v170
	v_sub_f32_e32 v247, 0, v170
	v_sub_f32_e32 v248, 0, v171
	v_sub_f32_e32 v249, 0, v171
	v_sub_f32_e32 v250, 0, v171
	v_sub_f32_e32 v251, 0, v171
	v_mov_b32_e32 v172, 0x41000000
	v_mov_b32_e32 v173, 0x41000000
	s_branch .LBB0_2248

.LBB0_2248:
	v_exp_f32_e32 v131, v124
	v_exp_f32_e32 v130, v76
	v_exp_f32_e32 v133, v125
	v_exp_f32_e32 v137, v120
	v_exp_f32_e32 v132, v77
	v_exp_f32_e32 v135, v126
	v_exp_f32_e32 v121, v121
	v_exp_f32_e32 v134, v78
	v_exp_f32_e32 v127, v127
	v_exp_f32_e32 v139, v122
	v_exp_f32_e32 v126, v79
	v_exp_f32_e32 v136, v72
	v_exp_f32_e32 v141, v123
	v_pk_add_f32 v[76:77], v[130:131], 0 op_sel_hi:[1,0]
	v_exp_f32_e32 v120, v73
	v_pk_add_f32 v[76:77], v[132:133], v[76:77]
	v_exp_f32_e32 v138, v74
	v_exp_f32_e32 v140, v75
	v_pk_add_f32 v[72:73], v[134:135], v[76:77]
	v_cvt_pk_bf16_f32 v122, v131, v133
	v_pk_add_f32 v[72:73], v[126:127], v[72:73]
	v_cvt_pk_bf16_f32 v123, v135, v127
	v_pk_add_f32 v[72:73], v[136:137], v[72:73]
	v_cvt_pk_bf16_f32 v124, v137, v121
	v_pk_add_f32 v[72:73], v[120:121], v[72:73]
	v_cvt_pk_bf16_f32 v130, v130, v132
	v_pk_add_f32 v[72:73], v[138:139], v[72:73]
	v_cvt_pk_bf16_f32 v132, v136, v120
	v_pk_add_f32 v[72:73], v[140:141], v[72:73]
	v_cvt_pk_bf16_f32 v125, v139, v141
	v_pk_add_f32 v[120:121], v[128:129], v[72:73]
	v_cvt_pk_bf16_f32 v131, v134, v126
	v_cvt_pk_bf16_f32 v133, v138, v140
	s_setprio 1
	s_waitcnt lgkmcnt(0)
	s_nop 1
	v_mfma_f32_16x16x32_bf16 v[72:75], v[116:119], v[122:125], v[80:83]
	v_mfma_f32_16x16x32_bf16 v[56:59], v[108:111], v[122:125], v[56:59]
	v_mfma_f32_16x16x32_bf16 v[60:63], v[108:111], v[130:133], v[60:63]
	v_mfma_f32_16x16x32_bf16 v[40:43], v[100:103], v[122:125], v[40:43]
	v_mfma_f32_16x16x32_bf16 v[44:47], v[100:103], v[130:133], v[44:47]
	v_mfma_f32_16x16x32_bf16 v[76:79], v[116:119], v[130:133], v[84:87]
	v_mfma_f32_16x16x32_bf16 v[64:67], v[112:115], v[122:125], v[64:67]
	v_mfma_f32_16x16x32_bf16 v[68:71], v[112:115], v[130:133], v[68:71]
	v_mfma_f32_16x16x32_bf16 v[48:51], v[104:107], v[122:125], v[48:51]
	v_mfma_f32_16x16x32_bf16 v[52:55], v[104:107], v[130:133], v[52:55]
	v_mfma_f32_16x16x32_bf16 v[32:35], v[96:99], v[122:125], v[32:35]
	v_mfma_f32_16x16x32_bf16 v[36:39], v[96:99], v[130:133], v[36:39]
	v_mfma_f32_16x16x32_bf16 v[24:27], v[92:95], v[122:125], v[24:27]
	v_mfma_f32_16x16x32_bf16 v[28:31], v[92:95], v[130:133], v[28:31]
	v_mfma_f32_16x16x32_bf16 v[16:19], v[88:91], v[122:125], v[16:19]
	v_mfma_f32_16x16x32_bf16 v[20:23], v[88:91], v[130:133], v[20:23]
	s_setprio 0
	ds_read_b128 v[104:107], v149 offset:16384
	ds_read_b128 v[108:111], v149 offset:20480
	ds_read_b128 v[112:115], v151 offset:16384
	ds_read_b128 v[122:125], v151 offset:20480
	ds_read_b128 v[126:129], v213 offset:16384
	ds_read_b128 v[130:133], v213 offset:20480
	ds_read_b128 v[216:219], v214 offset:16384
	ds_read_b128 v[220:223], v214 offset:20480
	v_add_u32_e32 v116, s17, v201
	v_add_u32_e32 v117, s17, v202
	ds_read_b64 v[100:101], v116 offset:32768
	ds_read_b64 v[102:103], v117 offset:32768
	ds_read_b64 v[96:97], v116 offset:36864
	ds_read_b64 v[98:99], v117 offset:36864
	ds_read_b64 v[92:93], v116 offset:40960
	ds_read_b64 v[94:95], v117 offset:40960
	ds_read_b64 v[88:89], v116 offset:45056
	ds_read_b64 v[90:91], v117 offset:45056
	ds_read_b64 v[84:85], v116 offset:49152
	ds_read_b64 v[86:87], v117 offset:49152
	ds_read_b64 v[80:81], v116 offset:53248
	ds_read_b64 v[82:83], v117 offset:53248
	ds_read_b64 v[140:141], v116 offset:57344
	ds_read_b64 v[142:143], v117 offset:57344
	ds_read_b64 v[136:137], v116 offset:61440
	ds_read_b64 v[138:139], v117 offset:61440
	s_waitcnt lgkmcnt(14)
	v_mfma_f32_16x16x32_bf16 v[104:107], v[104:107], v[0:3], v[244:247]
	s_waitcnt lgkmcnt(13)
	v_mfma_f32_16x16x32_bf16 v[116:119], v[112:115], v[4:7], v[104:107]
	v_mfma_f32_16x16x32_bf16 v[104:107], v[108:111], v[0:3], v[244:247]
	s_waitcnt lgkmcnt(12)
	v_mfma_f32_16x16x32_bf16 v[112:115], v[122:125], v[4:7], v[104:107]
	s_waitcnt lgkmcnt(11)
	v_mfma_f32_16x16x32_bf16 v[104:107], v[126:129], v[8:11], v[248:251]
	s_waitcnt lgkmcnt(9)
	v_mfma_f32_16x16x32_bf16 v[108:111], v[216:219], v[12:15], v[104:107]
	v_mfma_f32_16x16x32_bf16 v[104:107], v[130:133], v[8:11], v[248:251]
	s_waitcnt lgkmcnt(8)
	v_mfma_f32_16x16x32_bf16 v[104:107], v[220:223], v[12:15], v[104:107]
	v_max3_f32 v122, v116, v117, v118
	v_max3_f32 v122, v122, v119, v112
	v_max3_f32 v122, v122, v113, v114
	v_max_f32_e32 v122, v122, v115
	s_nop 0
	v_max3_f32 v123, v108, v109, v110
	s_nop 1
	v_max3_f32 v123, v123, v111, v104
	v_max3_f32 v123, v123, v105, v106
	v_max_f32_e32 v123, v123, v107
	v_cmp_gt_f32_e32 vcc, v122, v172
	v_cmp_gt_f32_e64 s[0:1], v123, v173
	s_or_b64 vcc, vcc, s[0:1]
	s_cbranch_vccz .LBB0_2250
	v_sub_f32_e32 v122, v122, v244
	v_sub_f32_e32 v123, v123, v248
	v_sub_f32_e32 v172, v172, v244
	v_sub_f32_e32 v173, v173, v248
	ds_bpermute_b32 v124, v187, v122
	ds_bpermute_b32 v125, v187, v123
	v_max_f32_e32 v122, v122, v122
	v_max_f32_e32 v123, v123, v123
	s_waitcnt lgkmcnt(1)
	v_max_f32_e32 v124, v124, v124
	s_waitcnt lgkmcnt(0)
	v_max_f32_e32 v125, v125, v125
	v_max_f32_e32 v122, v122, v124
	v_max_f32_e32 v123, v123, v125
	ds_bpermute_b32 v124, v186, v122
	ds_bpermute_b32 v125, v186, v123
	s_waitcnt lgkmcnt(1)
	v_max_f32_e32 v124, v124, v124
	s_waitcnt lgkmcnt(0)
	v_max_f32_e32 v125, v125, v125
	v_max_f32_e32 v122, v122, v124
	v_max_f32_e32 v123, v123, v125
	v_add_f32_e32 v124, 0x41000000, v171
	v_cmp_gt_f32_e32 vcc, v123, v124
	s_nop 1
	v_cndmask_b32_e32 v171, v175, v123, vcc
	v_cmp_gt_f32_e32 vcc, v122, v172
	s_nop 1
	v_cndmask_b32_e32 v170, v174, v122, vcc
	v_pk_add_f32 v[122:123], v[174:175], v[170:171] neg_lo:[0,1] neg_hi:[0,1]
	v_pk_add_f32 v[172:173], v[170:171], s[8:9] op_sel_hi:[1,0]
	v_exp_f32_e32 v122, v122
	v_exp_f32_e32 v124, v123
	v_mov_b64_e32 v[174:175], v[170:171]
	v_mov_b32_e32 v125, v122
	v_pk_mul_f32 v[74:75], v[74:75], v[122:123] op_sel_hi:[1,0]
	v_pk_mul_f32 v[72:73], v[72:73], v[122:123] op_sel_hi:[1,0]
	v_pk_mul_f32 v[66:67], v[66:67], v[122:123] op_sel_hi:[1,0]
	v_pk_mul_f32 v[64:65], v[64:65], v[122:123] op_sel_hi:[1,0]
	v_pk_mul_f32 v[58:59], v[58:59], v[122:123] op_sel_hi:[1,0]
	v_pk_mul_f32 v[56:57], v[56:57], v[122:123] op_sel_hi:[1,0]
	v_pk_mul_f32 v[50:51], v[50:51], v[122:123] op_sel_hi:[1,0]
	v_pk_mul_f32 v[48:49], v[48:49], v[122:123] op_sel_hi:[1,0]
	v_pk_mul_f32 v[42:43], v[42:43], v[122:123] op_sel_hi:[1,0]
	v_pk_mul_f32 v[40:41], v[40:41], v[122:123] op_sel_hi:[1,0]
	v_pk_mul_f32 v[34:35], v[34:35], v[122:123] op_sel_hi:[1,0]
	v_pk_mul_f32 v[32:33], v[32:33], v[122:123] op_sel_hi:[1,0]
	v_pk_mul_f32 v[26:27], v[26:27], v[122:123] op_sel_hi:[1,0]
	v_pk_mul_f32 v[24:25], v[24:25], v[122:123] op_sel_hi:[1,0]
	v_pk_mul_f32 v[18:19], v[18:19], v[122:123] op_sel_hi:[1,0]
	v_pk_mul_f32 v[16:17], v[16:17], v[122:123] op_sel_hi:[1,0]
	v_pk_mul_f32 v[120:121], v[120:121], v[124:125]
	v_pk_mul_f32 v[78:79], v[78:79], v[124:125] op_sel_hi:[1,0]
	v_pk_mul_f32 v[76:77], v[76:77], v[124:125] op_sel_hi:[1,0]
	v_pk_mul_f32 v[70:71], v[70:71], v[124:125] op_sel_hi:[1,0]
	v_pk_mul_f32 v[68:69], v[68:69], v[124:125] op_sel_hi:[1,0]
	v_pk_mul_f32 v[62:63], v[62:63], v[124:125] op_sel_hi:[1,0]
	v_pk_mul_f32 v[60:61], v[60:61], v[124:125] op_sel_hi:[1,0]
	v_pk_mul_f32 v[54:55], v[54:55], v[124:125] op_sel_hi:[1,0]
	v_pk_mul_f32 v[52:53], v[52:53], v[124:125] op_sel_hi:[1,0]
	v_pk_mul_f32 v[46:47], v[46:47], v[124:125] op_sel_hi:[1,0]
	v_pk_mul_f32 v[44:45], v[44:45], v[124:125] op_sel_hi:[1,0]
	v_pk_mul_f32 v[38:39], v[38:39], v[124:125] op_sel_hi:[1,0]
	v_pk_mul_f32 v[36:37], v[36:37], v[124:125] op_sel_hi:[1,0]
	v_pk_mul_f32 v[30:31], v[30:31], v[124:125] op_sel_hi:[1,0]
	v_pk_mul_f32 v[28:29], v[28:29], v[124:125] op_sel_hi:[1,0]
	v_pk_mul_f32 v[22:23], v[22:23], v[124:125] op_sel_hi:[1,0]
	v_pk_mul_f32 v[20:21], v[20:21], v[124:125] op_sel_hi:[1,0]
	v_add_f32_e32 v242, v170, v244
	v_add_f32_e32 v243, v171, v248
	v_sub_f32_e32 v104, v104, v243
	v_sub_f32_e32 v105, v105, v243
	v_sub_f32_e32 v106, v106, v243
	v_sub_f32_e32 v107, v107, v243
	v_sub_f32_e32 v108, v108, v243
	v_sub_f32_e32 v109, v109, v243
	v_sub_f32_e32 v110, v110, v243
	v_sub_f32_e32 v111, v111, v243
	v_sub_f32_e32 v112, v112, v242
	v_sub_f32_e32 v113, v113, v242
	v_sub_f32_e32 v114, v114, v242
	v_sub_f32_e32 v115, v115, v242
	v_sub_f32_e32 v116, v116, v242
	v_sub_f32_e32 v117, v117, v242
	v_sub_f32_e32 v118, v118, v242
	v_sub_f32_e32 v119, v119, v242
	v_sub_f32_e32 v244, 0, v170
	v_sub_f32_e32 v245, 0, v170
	v_sub_f32_e32 v246, 0, v170
	v_sub_f32_e32 v247, 0, v170
	v_sub_f32_e32 v248, 0, v171
	v_sub_f32_e32 v249, 0, v171
	v_sub_f32_e32 v250, 0, v171
	v_sub_f32_e32 v251, 0, v171
	v_mov_b32_e32 v172, 0x41000000
	v_mov_b32_e32 v173, 0x41000000
.LBB0_2250:
	v_exp_f32_e32 v123, v116
	v_exp_f32_e32 v117, v117
	v_exp_f32_e32 v127, v112
	v_exp_f32_e32 v125, v118
	v_exp_f32_e32 v113, v113
	v_exp_f32_e32 v122, v108
	v_exp_f32_e32 v119, v119
	v_exp_f32_e32 v129, v114
	v_exp_f32_e32 v116, v109
	v_exp_f32_e32 v126, v104
	v_exp_f32_e32 v115, v115
	v_exp_f32_e32 v124, v110
	v_exp_f32_e32 v112, v105
	v_exp_f32_e32 v118, v111
	v_exp_f32_e32 v128, v106
	v_exp_f32_e32 v114, v107
	v_pk_add_f32 v[104:105], v[122:123], 0 op_sel_hi:[1,0]
	v_cvt_pk_bf16_f32 v216, v123, v117
	v_pk_add_f32 v[104:105], v[116:117], v[104:105]
	v_cvt_pk_bf16_f32 v217, v125, v119
	v_pk_add_f32 v[104:105], v[124:125], v[104:105]
	v_cvt_pk_bf16_f32 v218, v127, v113
	v_pk_add_f32 v[104:105], v[118:119], v[104:105]
	v_cvt_pk_bf16_f32 v219, v129, v115
	v_pk_add_f32 v[104:105], v[126:127], v[104:105]
	v_cvt_pk_bf16_f32 v220, v122, v116
	v_pk_add_f32 v[104:105], v[112:113], v[104:105]
	v_cvt_pk_bf16_f32 v221, v124, v118
	v_pk_add_f32 v[104:105], v[128:129], v[104:105]
	v_cvt_pk_bf16_f32 v222, v126, v112
	v_pk_add_f32 v[104:105], v[114:115], v[104:105]
	v_cvt_pk_bf16_f32 v223, v128, v114
	v_pk_add_f32 v[176:177], v[120:121], v[104:105]
	s_setprio 1
	s_waitcnt lgkmcnt(0)
	s_nop 1
	v_mfma_f32_16x16x32_bf16 v[124:127], v[96:99], v[216:219], v[64:67]
	v_mfma_f32_16x16x32_bf16 v[108:111], v[88:91], v[216:219], v[48:51]
	v_mfma_f32_16x16x32_bf16 v[132:135], v[100:103], v[216:219], v[72:75]
	v_mfma_f32_16x16x32_bf16 v[128:131], v[100:103], v[220:223], v[76:79]
	v_mfma_f32_16x16x32_bf16 v[120:123], v[96:99], v[220:223], v[68:71]
	v_mfma_f32_16x16x32_bf16 v[116:119], v[92:95], v[216:219], v[56:59]
	v_mfma_f32_16x16x32_bf16 v[112:115], v[92:95], v[220:223], v[60:63]
	v_mfma_f32_16x16x32_bf16 v[92:95], v[80:83], v[216:219], v[32:35]
	v_mfma_f32_16x16x32_bf16 v[104:107], v[88:91], v[220:223], v[52:55]
	v_mfma_f32_16x16x32_bf16 v[100:103], v[84:87], v[216:219], v[40:43]
	v_mfma_f32_16x16x32_bf16 v[96:99], v[84:87], v[220:223], v[44:47]
	v_mfma_f32_16x16x32_bf16 v[88:91], v[80:83], v[220:223], v[36:39]
	v_mfma_f32_16x16x32_bf16 v[84:87], v[140:143], v[216:219], v[24:27]
	v_mfma_f32_16x16x32_bf16 v[80:83], v[140:143], v[220:223], v[28:31]
	v_mfma_f32_16x16x32_bf16 v[72:75], v[136:139], v[216:219], v[16:19]
	v_mfma_f32_16x16x32_bf16 v[76:79], v[136:139], v[220:223], v[20:23]
	s_setprio 0
	ds_read_b128 v[40:43], v149 offset:24576
	ds_read_b128 v[44:47], v149 offset:28672
	ds_read_b128 v[48:51], v151 offset:24576
	ds_read_b128 v[56:59], v151 offset:28672
	ds_read_b128 v[60:63], v213 offset:24576
	ds_read_b128 v[64:67], v213 offset:28672
	ds_read_b128 v[68:71], v214 offset:24576
	ds_read_b128 v[214:217], v214 offset:28672
	v_add_u32_e32 v52, s17, v203
	v_add_u32_e32 v53, s17, v204
	ds_read_b64 v[36:37], v52 offset:32768
	ds_read_b64 v[38:39], v53 offset:32768
	ds_read_b64 v[32:33], v52 offset:36864
	ds_read_b64 v[34:35], v53 offset:36864
	ds_read_b64 v[28:29], v52 offset:40960
	ds_read_b64 v[30:31], v53 offset:40960
	ds_read_b64 v[24:25], v52 offset:45056
	ds_read_b64 v[26:27], v53 offset:45056
	ds_read_b64 v[20:21], v52 offset:49152
	ds_read_b64 v[22:23], v53 offset:49152
	ds_read_b64 v[16:17], v52 offset:53248
	ds_read_b64 v[18:19], v53 offset:53248
	ds_read_b64 v[140:141], v52 offset:57344
	ds_read_b64 v[142:143], v53 offset:57344
	ds_read_b64 v[136:137], v52 offset:61440
	ds_read_b64 v[138:139], v53 offset:61440
	s_waitcnt lgkmcnt(14)
	v_mfma_f32_16x16x32_bf16 v[40:43], v[40:43], v[0:3], v[244:247]
	s_waitcnt lgkmcnt(13)
	v_mfma_f32_16x16x32_bf16 v[52:55], v[48:51], v[4:7], v[40:43]
	v_mfma_f32_16x16x32_bf16 v[40:43], v[44:47], v[0:3], v[244:247]
	s_waitcnt lgkmcnt(12)
	v_mfma_f32_16x16x32_bf16 v[48:51], v[56:59], v[4:7], v[40:43]
	s_waitcnt lgkmcnt(11)
	v_mfma_f32_16x16x32_bf16 v[40:43], v[60:63], v[8:11], v[248:251]
	s_waitcnt lgkmcnt(9)
	v_mfma_f32_16x16x32_bf16 v[44:47], v[68:71], v[12:15], v[40:43]
	v_mfma_f32_16x16x32_bf16 v[40:43], v[64:67], v[8:11], v[248:251]
	s_waitcnt lgkmcnt(8)
	v_mfma_f32_16x16x32_bf16 v[40:43], v[214:217], v[12:15], v[40:43]
	v_max3_f32 v56, v52, v53, v54
	v_max3_f32 v56, v56, v55, v48
	v_max3_f32 v56, v56, v49, v50
	v_max_f32_e32 v56, v56, v51
	s_nop 0
	v_max3_f32 v57, v44, v45, v46
	s_nop 1
	v_max3_f32 v57, v57, v47, v40
	v_max3_f32 v57, v57, v41, v42
	v_max_f32_e32 v57, v57, v43
	v_cmp_gt_f32_e32 vcc, v56, v172
	v_cmp_gt_f32_e64 s[0:1], v57, v173
	s_or_b64 vcc, vcc, s[0:1]
	s_cbranch_vccnz .LBB0_2239
	v_mov_b32_e32 v57, v171
	v_mov_b32_e32 v56, v170
	v_mov_b64_e32 v[170:171], v[174:175]
	s_branch .LBB0_2240
